# Preloaded the subln gain quads in the attention unit epilogue and the gate/norm-gain quads in the GLA output unit (removes store-ack round trips)
# speedup vs baseline: 1.0189x; 1.0101x over previous
; #define LAS __attribute__((address_space(3)))
; #define LAS __attribute__((address_space(3)))
; template <int MODE>
; DI void gla4_unit(const bf16_t* z, float* ST, float* DEC, bf16_t* Y, const float* aw_g, const float* ab_g, const float* ng, ldsp lds, int tid, int u) {
;     ...
;     __syncthreads();
;     {
;         constexpr int NM = MODE ? 3 : 2;
; #pragma unroll
;         for (int i = 0; i < NM * 4; ++i) {
;             const int pi = tid + 512 * i, mh = pi >> 9, mat = mh >> 2, head = mh & 3, row = (pi >> 3) & 63, pc = pi & 7;
;             const int col = (MODE ? (mat == 0 ? C_GQ : (mat == 1 ? C_GK : C_GV)) : (mat == 0 ? C_GK : C_GV)) + head * 64 + pc * 8;
;             const int reg = MODE ? mat * 9216 : (mat == 0 ? 0 : G4_R2);
;             *(LAS u32x4*)(lds + head * G4_HEAD + reg + row * 144 + pc * 16) = *(const u32x4*)(z + (size_t)(tok0 + row) * ZLD + col);
; __global__ void __launch_bounds__(512, 2) hybrid_fwd(Args a) {
;     ...
;                 if (!((live >> qi) & 1u)) continue;
;                 for (;; ++it) {
;                     const ldsp slot = lds + LDS_PHASE + 16 + (it & 1) * 4;
;                     if (tid == 0) *(LAS unsigned*)slot = __hip_atomic_fetch_add(ctr + xq * 64, 1u, __ATOMIC_RELAXED, __HIP_MEMORY_SCOPE_AGENT);
;                     __syncthreads();
;                     const int idx = (int)*(LAS unsigned*)slot;
;                     if (idx >= 128 + 64) break;
;                     int tu = tid; asm volatile("" : "+v"(tu));
;                     if (idx < 128) {
;                         const int r = 63 - (xq & 1) - 2 * (idx >> 2), h = idx & 3, b = xq >> 1;
;                         const float slope = exp2f(-2.0f * (float)(h + 1));
;                         const float wf = (104.0f + 2.0f * smax) / slope;
;                         const int win = wf < 16384.0f ? (int)wf + 1 : 16384;
;                         attn_unit(Z, VT, Y, a.diff_subln_g + l * 128, lds, tu, b, h, r, lam, -slope * LOG2E, 1.0f - lam_init, win);
;                     } else {
;                         gla4_unit<1>(Z, ST, DEC, Y, a.gla_alpha_w + (size_t)l * 16 * 256, a.gla_alpha_b + l * 256, a.gla_norm_g + l * 64, lds, tu, xq * 64 + idx - 128);
.LBB0_407:
	s_or_b64 exec, exec, s[0:1]
	s_add_i32 s0, s6, 0
	s_add_i32 s0, s0, 0x20010
	v_mov_b32_e32 v0, s0
	s_waitcnt lgkmcnt(0)
	s_barrier
	ds_read_b32 v0, v0
	s_movk_i32 s0, 0xbf
	s_waitcnt lgkmcnt(0)
	v_cmp_lt_i32_e32 vcc, s0, v0
	v_readfirstlane_b32 s28, v0
	s_mov_b64 s[0:1], -1
	s_cbranch_vccnz .LBB0_402
	v_mov_b32_e32 v80, v136
	s_cmpk_gt_i32 s28, 0x7f
	v_and_b32_e32 v81, 15, v80
	v_and_b32_e32 v178, 63, v80
	v_bfe_u32 v177, v80, 4, 2
	s_cbranch_scc0 .LBB0_410
	s_add_i32 s30, s28, s83
	v_ashrrev_i32_e32 v14, 11, v80
	s_add_i32 s0, s30, 0xffffff80
	v_cmp_eq_u32_e32 vcc, 1, v14
	s_lshl_b32 s29, s0, 6
	v_bfe_u32 v4, v80, 3, 6
	v_and_b32_e32 v5, 7, v80
	v_bfe_u32 v15, v80, 9, 2
	v_cndmask_b32_e32 v7, v200, v201, vcc
	v_cmp_lt_u32_e32 vcc, s94, v80
	v_lshlrev_b32_e32 v6, 3, v5
	v_or_b32_e32 v0, s29, v4
	v_cndmask_b32_e32 v8, v202, v7, vcc
	v_lshlrev_b32_e32 v7, 6, v15
	v_mul_lo_u32 v156, v0, s52
	v_or3_b32 v8, v6, v8, v7
	v_lshl_add_u64 v[0:1], v[156:157], 1, s[70:71]
	v_lshlrev_b32_e32 v156, 1, v8
	v_lshl_add_u64 v[8:9], v[0:1], 0, v[156:157]
	s_barrier
	global_load_dwordx4 v[86:89], v[8:9], off
	v_mad_u32_u24 v8, v15, s5, 0
	v_mul_u32_u24_e32 v4, 0x90, v4
	v_lshlrev_b32_e32 v5, 4, v5
	v_mad_i32_i24 v9, v14, s95, v8
	v_add3_u32 v9, v9, v4, v5
	s_movk_i32 s1, 0xf800
	s_lshr_b32 s0, s0, 5
	v_ashrrev_i32_e32 v2, 7, v80
	s_and_b32 s0, s0, 12
	v_mov_b64_e32 v[32:33], s[70:71]
	v_add_u32_e32 v28, s0, v2
	v_lshlrev_b32_e32 v34, 6, v2
	v_bfe_u32 v29, v80, 6, 1
	v_mul_lo_u32 v3, v2, s5
	v_lshlrev_b32_e32 v2, 8, v2
	v_mov_b32_e32 v142, v9
	v_add_u32_e32 v9, 0x200, v80
	v_ashrrev_i32_e32 v10, 11, v9
	v_cmp_eq_u32_e32 vcc, 1, v10
	v_bfe_u32 v14, v9, 9, 2
	v_mul_i32_i24_e32 v15, 0x2400, v10
	v_cndmask_b32_e32 v11, v200, v201, vcc
	v_cmp_lt_u32_e32 vcc, s94, v9
	s_nop 1
	v_cndmask_b32_e32 v9, v202, v11, vcc
	v_lshlrev_b32_e32 v11, 6, v14
	v_or3_b32 v9, v9, v11, v6
	v_lshlrev_b32_e32 v156, 1, v9
	v_lshl_add_u64 v[10:11], v[0:1], 0, v[156:157]
	global_load_dwordx4 v[90:93], v[10:11], off
	v_mul_u32_u24_e32 v9, 0x6c00, v14
	v_add3_u32 v9, 0, v9, v15
	v_add3_u32 v9, v9, v4, v5
	v_mov_b32_e32 v143, v9
	v_add_u32_e32 v9, 0x400, v80
	v_ashrrev_i32_e32 v10, 11, v9
	v_cmp_eq_u32_e32 vcc, 1, v10
	v_bfe_u32 v14, v9, 9, 2
	v_mul_i32_i24_e32 v15, 0x2400, v10
	v_cndmask_b32_e32 v11, v200, v201, vcc
	v_cmp_lt_u32_e32 vcc, s94, v9
	s_nop 1
	v_cndmask_b32_e32 v9, v202, v11, vcc
	v_lshlrev_b32_e32 v11, 6, v14
	v_or3_b32 v9, v9, v11, v6
	v_lshlrev_b32_e32 v156, 1, v9
	v_lshl_add_u64 v[10:11], v[0:1], 0, v[156:157]
	global_load_dwordx4 v[94:97], v[10:11], off
	v_mul_u32_u24_e32 v9, 0x6c00, v14
	v_add3_u32 v9, 0, v9, v15
	v_add3_u32 v9, v9, v4, v5
	v_mov_b32_e32 v144, v9
	v_add_u32_e32 v9, 0x600, v80
	v_ashrrev_i32_e32 v10, 11, v9
	v_cmp_eq_u32_e32 vcc, 1, v10
	v_bfe_u32 v14, v9, 9, 2
	v_mul_i32_i24_e32 v15, 0x2400, v10
	v_cndmask_b32_e32 v11, v200, v201, vcc
	v_cmp_lt_u32_e32 vcc, s94, v9
	s_nop 1
	v_cndmask_b32_e32 v9, v202, v11, vcc
	v_lshlrev_b32_e32 v11, 6, v14
	v_or3_b32 v9, v9, v11, v6
	v_lshlrev_b32_e32 v156, 1, v9
	v_lshl_add_u64 v[10:11], v[0:1], 0, v[156:157]
	global_load_dwordx4 v[98:101], v[10:11], off
	v_mul_u32_u24_e32 v9, 0x6c00, v14
	v_add3_u32 v9, 0, v9, v15
	v_add3_u32 v9, v9, v4, v5
	v_mov_b32_e32 v145, v9
	v_add_u32_e32 v9, 0x800, v80
	v_ashrrev_i32_e32 v9, 11, v9
	v_cmp_eq_u32_e32 vcc, 1, v9
	v_mad_i32_i24 v9, v9, s95, v8
	v_add3_u32 v9, v9, v4, v5
	v_cndmask_b32_e32 v10, v200, v201, vcc
	v_cmp_gt_u32_e32 vcc, s1, v80
	s_nop 1
	v_cndmask_b32_e32 v10, v202, v10, vcc
	v_or3_b32 v10, v6, v10, v7
	v_lshlrev_b32_e32 v156, 1, v10
	v_lshl_add_u64 v[10:11], v[0:1], 0, v[156:157]
	global_load_dwordx4 v[102:105], v[10:11], off
	v_mov_b32_e32 v146, v9
	v_add_u32_e32 v9, 0xa00, v80
	v_ashrrev_i32_e32 v10, 11, v9
	v_cmp_eq_u32_e32 vcc, 1, v10
	v_bfe_u32 v14, v9, 9, 2
	v_mul_i32_i24_e32 v15, 0x2400, v10
	v_cndmask_b32_e32 v11, v200, v201, vcc
	v_cmp_lt_u32_e32 vcc, s94, v9
	s_nop 1
	v_cndmask_b32_e32 v9, v202, v11, vcc
	v_lshlrev_b32_e32 v11, 6, v14
	v_or3_b32 v9, v9, v11, v6
	v_lshlrev_b32_e32 v156, 1, v9
	v_lshl_add_u64 v[10:11], v[0:1], 0, v[156:157]
	global_load_dwordx4 v[106:109], v[10:11], off
	v_mul_u32_u24_e32 v9, 0x6c00, v14
	v_add3_u32 v9, 0, v9, v15
	v_add3_u32 v9, v9, v4, v5
	v_mov_b32_e32 v147, v9
	v_add_u32_e32 v9, 0xc00, v80
	v_ashrrev_i32_e32 v10, 11, v9
	v_cmp_eq_u32_e32 vcc, 1, v10
	v_bfe_u32 v14, v9, 9, 2
	v_mul_i32_i24_e32 v15, 0x2400, v10
	v_cndmask_b32_e32 v11, v200, v201, vcc
	v_cmp_lt_u32_e32 vcc, s94, v9
	s_nop 1
	v_cndmask_b32_e32 v9, v202, v11, vcc
	v_lshlrev_b32_e32 v11, 6, v14
	v_or3_b32 v9, v9, v11, v6
	v_lshlrev_b32_e32 v156, 1, v9
	v_lshl_add_u64 v[10:11], v[0:1], 0, v[156:157]
	global_load_dwordx4 v[110:113], v[10:11], off
	v_mul_u32_u24_e32 v9, 0x6c00, v14
	v_add3_u32 v9, 0, v9, v15
	v_add3_u32 v9, v9, v4, v5
	v_mov_b32_e32 v148, v9
	v_add_u32_e32 v9, 0xe00, v80
	v_ashrrev_i32_e32 v10, 11, v9
	v_cmp_eq_u32_e32 vcc, 1, v10
	v_bfe_u32 v14, v9, 9, 2
	v_mul_i32_i24_e32 v15, 0x2400, v10
	v_cndmask_b32_e32 v11, v200, v201, vcc
	v_cmp_lt_u32_e32 vcc, s94, v9
	s_nop 1
	v_cndmask_b32_e32 v9, v202, v11, vcc
	v_lshlrev_b32_e32 v11, 6, v14
	v_or3_b32 v9, v9, v11, v6
	v_lshlrev_b32_e32 v156, 1, v9
	v_lshl_add_u64 v[10:11], v[0:1], 0, v[156:157]
	global_load_dwordx4 v[120:123], v[10:11], off
	v_mul_u32_u24_e32 v9, 0x6c00, v14
	v_add3_u32 v9, 0, v9, v15
	v_add3_u32 v9, v9, v4, v5
	v_mov_b32_e32 v149, v9
	v_add_u32_e32 v9, 0x1000, v80
	v_ashrrev_i32_e32 v14, 11, v9
	v_cmp_eq_u32_e32 vcc, 1, v14
	s_nop 1
	v_cndmask_b32_e32 v10, v200, v201, vcc
	v_cmp_lt_u32_e32 vcc, s94, v9
	s_nop 1
	v_cndmask_b32_e32 v9, v202, v10, vcc
	v_or3_b32 v7, v6, v9, v7
; #define LAS __attribute__((address_space(3)))
; #define LAS __attribute__((address_space(3)))
; DI float bflo(unsigned v) { return __uint_as_float(v << 16); }
; DI float bfhi(unsigned v) { return __uint_as_float(v & 0xffff0000u); }
; DI float log_sigmoid_fast(float x) { return fminf(x, 0.f) - __logf(1.0f + __expf(-fabsf(x))); }
; template <int MODE>
; DI void gla4_unit(const bf16_t* z, float* ST, float* DEC, bf16_t* Y, const float* aw_g, const float* ab_g, const float* ng, ldsp lds, int tid, int u) {
;     ...
;         for (int i = 0; i < NM * 4; ++i) {
;             const int pi = tid + 512 * i, mh = pi >> 9, mat = mh >> 2, head = mh & 3, row = (pi >> 3) & 63, pc = pi & 7;
;             const int col = (MODE ? (mat == 0 ? C_GQ : (mat == 1 ? C_GK : C_GV)) : (mat == 0 ? C_GK : C_GV)) + head * 64 + pc * 8;
;             const int reg = MODE ? mat * 9216 : (mat == 0 ? 0 : G4_R2);
;             *(LAS u32x4*)(lds + head * G4_HEAD + reg + row * 144 + pc * 16) = *(const u32x4*)(z + (size_t)(tok0 + row) * ZLD + col);
;         }
;         const int idx = tid * 2, t = idx >> 4, r = idx & 15;
;         const unsigned v = *(const unsigned*)(z + (size_t)(tok0 + t) * ZLD + C_GA + r);
;         alr[t * 16 + r] = bflo(v); alr[t * 16 + r + 1] = bfhi(v);
;     }
;     float aw[16];
; #pragma unroll
;     for (int r = 0; r < 16; ++r) aw[r] = aw_g[r * 256 + hd * 64 + d];
;     const float ab = ab_g[hd * 64 + d];
;     __syncthreads();
;     float bc[32];
;     {
;         float run = 0.f;
; #pragma unroll
;         for (int i = 0; i < 32; ++i) {
;             const int t = 32 * half + i;
;             float al = ab;
; #pragma unroll
;             for (int r = 0; r < 16; ++r) al += alr[t * 16 + r] * aw[r];
;             run += log_sigmoid_fast(al) * (1.0f / 16.0f);
;             bc[i] = run;
;         }
	v_lshlrev_b32_e32 v156, 1, v7
	v_lshl_add_u64 v[10:11], v[0:1], 0, v[156:157]
	global_load_dwordx4 v[124:127], v[10:11], off
	v_mad_i32_i24 v7, v14, s95, v8
	v_add3_u32 v7, v7, v4, v5
	v_mov_b32_e32 v150, v7
	v_add_u32_e32 v7, 0x1200, v80
	v_ashrrev_i32_e32 v8, 11, v7
	v_cmp_eq_u32_e32 vcc, 1, v8
	v_bfe_u32 v12, v7, 9, 2
	v_mul_i32_i24_e32 v13, 0x2400, v8
	v_cndmask_b32_e32 v9, v200, v201, vcc
	v_cmp_lt_u32_e32 vcc, s94, v7
	s_nop 1
	v_cndmask_b32_e32 v7, v202, v9, vcc
	v_lshlrev_b32_e32 v9, 6, v12
	v_or3_b32 v7, v7, v9, v6
	v_lshlrev_b32_e32 v156, 1, v7
	v_lshl_add_u64 v[8:9], v[0:1], 0, v[156:157]
	global_load_dwordx4 v[128:131], v[8:9], off
	v_mul_u32_u24_e32 v7, 0x6c00, v12
	v_add3_u32 v7, 0, v7, v13
	v_add3_u32 v7, v7, v4, v5
	v_mov_b32_e32 v151, v7
	v_add_u32_e32 v7, 0x1400, v80
	v_ashrrev_i32_e32 v8, 11, v7
	v_cmp_eq_u32_e32 vcc, 1, v8
	v_bfe_u32 v12, v7, 9, 2
	v_mul_i32_i24_e32 v13, 0x2400, v8
	v_cndmask_b32_e32 v9, v200, v201, vcc
	v_cmp_lt_u32_e32 vcc, s94, v7
	s_nop 1
	v_cndmask_b32_e32 v7, v202, v9, vcc
	v_lshlrev_b32_e32 v9, 6, v12
	v_or3_b32 v7, v7, v9, v6
	v_lshlrev_b32_e32 v156, 1, v7
	v_lshl_add_u64 v[8:9], v[0:1], 0, v[156:157]
	global_load_dwordx4 v[132:135], v[8:9], off
	v_mul_u32_u24_e32 v7, 0x6c00, v12
	v_add3_u32 v7, 0, v7, v13
	v_add3_u32 v7, v7, v4, v5
	v_mov_b32_e32 v152, v7
	v_add_u32_e32 v7, 0x1600, v80
	v_ashrrev_i32_e32 v8, 11, v7
	v_cmp_eq_u32_e32 vcc, 1, v8
	v_bfe_u32 v10, v7, 9, 2
	v_mul_i32_i24_e32 v11, 0x2400, v8
	v_cndmask_b32_e32 v9, v200, v201, vcc
	v_cmp_lt_u32_e32 vcc, s94, v7
	s_nop 1
	v_cndmask_b32_e32 v7, v202, v9, vcc
	v_lshlrev_b32_e32 v9, 6, v10
	v_or3_b32 v6, v7, v9, v6
	v_lshlrev_b32_e32 v156, 1, v6
	v_lshl_add_u64 v[0:1], v[0:1], 0, v[156:157]
	global_load_dwordx4 v[138:141], v[0:1], off
	v_mul_u32_u24_e32 v0, 0x6c00, v10
	v_add3_u32 v0, 0, v0, v11
	v_add3_u32 v0, v0, v4, v5
	v_ashrrev_i32_e32 v4, 3, v80
	v_mov_b32_e32 v153, v0
	v_lshlrev_b32_e32 v0, 1, v80
	v_and_b32_e32 v5, 14, v0
	v_add_u32_e32 v0, s29, v4
	v_mad_i64_i32 v[0:1], s[0:1], v0, s97, v[32:33]
	v_lshlrev_b32_e32 v156, 1, v5
	v_lshl_add_u64 v[0:1], v[0:1], 0, v[156:157]
	v_add_co_u32_e32 v0, vcc, s33, v0
	v_lshlrev_b32_e32 v4, 6, v4
	s_nop 0
	v_addc_co_u32_e32 v1, vcc, 0, v1, vcc
	global_load_dword v1, v[0:1], off offset:2560
	v_lshlrev_b32_e32 v5, 2, v5
	v_add3_u32 v4, s98, v4, v5
	v_lshlrev_b32_e32 v156, 5, v177
	s_waitcnt vmcnt(0)
	ds_write_b128 v142, v[86:89]
	ds_write_b128 v143, v[90:93]
	ds_write_b128 v144, v[94:97]
	ds_write_b128 v145, v[98:101]
	ds_write_b128 v146, v[102:105]
	ds_write_b128 v147, v[106:109]
	ds_write_b128 v148, v[110:113]
	ds_write_b128 v149, v[120:123]
	ds_write_b128 v150, v[124:127]
	ds_write_b128 v151, v[128:131]
	ds_write_b128 v152, v[132:135]
	ds_write_b128 v153, v[138:141]
	v_lshlrev_b32_e32 v0, 16, v1
	v_and_b32_e32 v1, 0xffff0000, v1
	ds_write_b64 v4, v[0:1]
	v_or_b32_e32 v0, v34, v178
	v_ashrrev_i32_e32 v1, 31, v0
	v_lshlrev_b64 v[20:21], 2, v[0:1]
	v_lshl_add_u64 v[4:5], s[24:25], 0, v[20:21]
	v_add_co_u32_e32 v6, vcc, s33, v4
	v_lshl_add_u64 v[20:21], s[2:3], 0, v[20:21]
	s_nop 0
	v_addc_co_u32_e32 v7, vcc, 0, v5, vcc
	v_add_co_u32_e32 v10, vcc, s88, v4
	global_load_dword v16, v[4:5], off
	global_load_dword v17, v[4:5], off offset:1024
	global_load_dword v18, v[4:5], off offset:2048
	global_load_dword v19, v[4:5], off offset:3072
	v_addc_co_u32_e32 v11, vcc, 0, v5, vcc
	v_add_co_u32_e32 v22, vcc, s99, v4
	global_load_dword v12, v[10:11], off offset:-4096
	global_load_dword v13, v[6:7], off offset:1024
	global_load_dword v14, v[6:7], off offset:2048
	global_load_dword v15, v[6:7], off offset:3072
	s_nop 0
	global_load_dword v7, v[10:11], off
	global_load_dword v8, v[10:11], off offset:1024
	global_load_dword v9, v[10:11], off offset:2048
	s_nop 0
	global_load_dword v10, v[10:11], off offset:3072
	v_addc_co_u32_e32 v23, vcc, 0, v5, vcc
	global_load_dword v6, v[22:23], off
	global_load_dword v5, v[22:23], off offset:1024
	global_load_dword v4, v[22:23], off offset:2048
	global_load_dword v1, v[22:23], off offset:3072
	global_load_dword v11, v[20:21], off
	v_lshl_add_u32 v21, v29, 11, s98
	s_waitcnt lgkmcnt(0)
	s_barrier
	ds_read_b128 v[22:25], v21
	ds_read_b128 v[36:39], v21 offset:16
	ds_read_b128 v[40:43], v21 offset:32
	ds_read_b128 v[44:47], v21 offset:48
	s_waitcnt vmcnt(0) lgkmcnt(3)
	v_fma_f32 v20, v16, v22, v11
	v_fmac_f32_e32 v20, v17, v23
	v_fmac_f32_e32 v20, v18, v24
	v_fmac_f32_e32 v20, v19, v25
	s_waitcnt lgkmcnt(2)
	v_fmac_f32_e32 v20, v12, v36
	v_fmac_f32_e32 v20, v13, v37
	v_fmac_f32_e32 v20, v14, v38
	v_fmac_f32_e32 v20, v15, v39
	s_waitcnt lgkmcnt(1)
	v_fmac_f32_e32 v20, v7, v40
	v_fmac_f32_e32 v20, v8, v41
	v_fmac_f32_e32 v20, v9, v42
	v_fmac_f32_e32 v20, v10, v43
	s_waitcnt lgkmcnt(0)
	v_fmac_f32_e32 v20, v6, v44
	v_fmac_f32_e32 v20, v5, v45
	v_fmac_f32_e32 v20, v4, v46
	v_fmac_f32_e32 v20, v1, v47
	v_min_f32_e32 v22, 0, v20
	v_mul_f32_e64 v20, |v20|, s46
	v_exp_f32_e32 v20, v20
	ds_read_b128 v[36:39], v21 offset:256
	v_add_f32_e32 v20, 1.0, v20
	v_cmp_gt_f32_e32 vcc, s47, v20
	s_nop 1
	v_cndmask_b32_e64 v23, 0, 32, vcc
	v_ldexp_f32 v20, v20, v23
	v_log_f32_e32 v20, v20
	s_nop 0
	v_mul_f32_e32 v23, 0x3f317217, v20
	v_fma_f32 v23, v20, s4, -v23
	v_fmac_f32_e32 v23, 0x3377d1cf, v20
	v_fmac_f32_e32 v23, 0x3f317217, v20
	v_cmp_lt_f32_e64 s[0:1], |v20|, s90
	s_nop 1
	v_cndmask_b32_e64 v20, v20, v23, s[0:1]
	v_cndmask_b32_e32 v23, 0, v203, vcc
	v_sub_f32_e32 v20, v20, v23
	v_sub_f32_e32 v20, v22, v20
	ds_read_b128 v[22:25], v21 offset:64
	v_fma_f32 v20, v20, s79, 0
	s_waitcnt lgkmcnt(0)
	v_fma_f32 v26, v16, v22, v11
	v_fmac_f32_e32 v26, v17, v23
	v_fmac_f32_e32 v26, v18, v24
	v_fmac_f32_e32 v26, v19, v25
	ds_read_b128 v[22:25], v21 offset:80
	s_waitcnt lgkmcnt(0)
; DI float log_sigmoid_fast(float x) { return fminf(x, 0.f) - __logf(1.0f + __expf(-fabsf(x))); }
; template <int MODE>
; DI void gla4_unit(const bf16_t* z, float* ST, float* DEC, bf16_t* Y, const float* aw_g, const float* ab_g, const float* ng, ldsp lds, int tid, int u) {
;     ...
;     {
;         float run = 0.f;
; #pragma unroll
;         for (int i = 0; i < 32; ++i) {
;             const int t = 32 * half + i;
;             float al = ab;
; #pragma unroll
;             for (int r = 0; r < 16; ++r) al += alr[t * 16 + r] * aw[r];
;             run += log_sigmoid_fast(al) * (1.0f / 16.0f);
;             bc[i] = run;
;         }
	v_fmac_f32_e32 v26, v12, v22
	v_fmac_f32_e32 v26, v13, v23
	v_fmac_f32_e32 v26, v14, v24
	v_fmac_f32_e32 v26, v15, v25
	ds_read_b128 v[22:25], v21 offset:96
	s_waitcnt lgkmcnt(0)
	v_fmac_f32_e32 v26, v7, v22
	v_fmac_f32_e32 v26, v8, v23
	v_fmac_f32_e32 v26, v9, v24
	v_fmac_f32_e32 v26, v10, v25
	ds_read_b128 v[22:25], v21 offset:112
	s_waitcnt lgkmcnt(0)
	v_fmac_f32_e32 v26, v6, v22
	v_fmac_f32_e32 v26, v5, v23
	v_fmac_f32_e32 v26, v4, v24
	v_fmac_f32_e32 v26, v1, v25
	v_mul_f32_e64 v23, |v26|, s46
	v_exp_f32_e32 v23, v23
	v_min_f32_e32 v22, 0, v26
	v_add_f32_e32 v23, 1.0, v23
	v_cmp_gt_f32_e32 vcc, s47, v23
	s_nop 1
	v_cndmask_b32_e64 v24, 0, 32, vcc
	v_ldexp_f32 v23, v23, v24
	v_log_f32_e32 v23, v23
	s_nop 0
	v_mul_f32_e32 v24, 0x3f317217, v23
	v_fma_f32 v24, v23, s4, -v24
	v_fmac_f32_e32 v24, 0x3377d1cf, v23
	v_fmac_f32_e32 v24, 0x3f317217, v23
	v_cmp_lt_f32_e64 s[0:1], |v23|, s90
	s_nop 1
	v_cndmask_b32_e64 v23, v23, v24, s[0:1]
	v_cndmask_b32_e32 v24, 0, v203, vcc
	v_sub_f32_e32 v23, v23, v24
	ds_read_b128 v[24:27], v21 offset:128
	v_sub_f32_e32 v22, v22, v23
	v_fmamk_f32 v22, v22, 0x3d800000, v20
	s_waitcnt lgkmcnt(0)
	v_fma_f32 v23, v16, v24, v11
	v_fmac_f32_e32 v23, v17, v25
	v_fmac_f32_e32 v23, v18, v26
	v_fmac_f32_e32 v23, v19, v27
	ds_read_b128 v[24:27], v21 offset:144
	s_waitcnt lgkmcnt(0)
	v_fmac_f32_e32 v23, v12, v24
	v_fmac_f32_e32 v23, v13, v25
	v_fmac_f32_e32 v23, v14, v26
	v_fmac_f32_e32 v23, v15, v27
	ds_read_b128 v[24:27], v21 offset:160
	s_waitcnt lgkmcnt(0)
	v_fmac_f32_e32 v23, v7, v24
	v_fmac_f32_e32 v23, v8, v25
	v_fmac_f32_e32 v23, v9, v26
	v_fmac_f32_e32 v23, v10, v27
	ds_read_b128 v[24:27], v21 offset:176
	s_waitcnt lgkmcnt(0)
	v_fmac_f32_e32 v23, v6, v24
	v_fmac_f32_e32 v23, v5, v25
	v_fmac_f32_e32 v23, v4, v26
	v_fmac_f32_e32 v23, v1, v27
	v_min_f32_e32 v24, 0, v23
	v_mul_f32_e64 v23, |v23|, s46
	v_exp_f32_e32 v23, v23
	s_nop 0
	v_add_f32_e32 v23, 1.0, v23
	v_cmp_gt_f32_e32 vcc, s47, v23
	s_nop 1
	v_cndmask_b32_e64 v25, 0, 32, vcc
	v_ldexp_f32 v23, v23, v25
	v_log_f32_e32 v23, v23
	s_nop 0
	v_mul_f32_e32 v25, 0x3f317217, v23
	v_fma_f32 v25, v23, s4, -v25
	v_fmac_f32_e32 v25, 0x3377d1cf, v23
	v_fmac_f32_e32 v25, 0x3f317217, v23
	v_cmp_lt_f32_e64 s[0:1], |v23|, s90
	s_nop 1
	v_cndmask_b32_e64 v23, v23, v25, s[0:1]
	v_cndmask_b32_e32 v25, 0, v203, vcc
	v_sub_f32_e32 v23, v23, v25
	v_sub_f32_e32 v23, v24, v23
	ds_read_b128 v[24:27], v21 offset:192
	v_fmamk_f32 v23, v23, 0x3d800000, v22
	s_waitcnt lgkmcnt(0)
	v_fma_f32 v30, v16, v24, v11
	v_fmac_f32_e32 v30, v17, v25
	v_fmac_f32_e32 v30, v18, v26
	v_fmac_f32_e32 v30, v19, v27
	ds_read_b128 v[24:27], v21 offset:208
	s_waitcnt lgkmcnt(0)
	v_fmac_f32_e32 v30, v12, v24
	v_fmac_f32_e32 v30, v13, v25
	v_fmac_f32_e32 v30, v14, v26
	v_fmac_f32_e32 v30, v15, v27
	ds_read_b128 v[24:27], v21 offset:224
	s_waitcnt lgkmcnt(0)
	v_fmac_f32_e32 v30, v7, v24
	v_fmac_f32_e32 v30, v8, v25
	v_fmac_f32_e32 v30, v9, v26
	v_fmac_f32_e32 v30, v10, v27
	ds_read_b128 v[24:27], v21 offset:240
	s_waitcnt lgkmcnt(0)
	v_fmac_f32_e32 v30, v6, v24
	v_fmac_f32_e32 v30, v5, v25
	v_fmac_f32_e32 v30, v4, v26
	v_fmac_f32_e32 v30, v1, v27
	v_mul_f32_e64 v25, |v30|, s46
	v_exp_f32_e32 v25, v25
	v_min_f32_e32 v24, 0, v30
	v_add_f32_e32 v25, 1.0, v25
	v_cmp_gt_f32_e32 vcc, s47, v25
	s_nop 1
	v_cndmask_b32_e64 v26, 0, 32, vcc
	v_ldexp_f32 v25, v25, v26
	v_log_f32_e32 v25, v25
	s_nop 0
	v_mul_f32_e32 v26, 0x3f317217, v25
	v_fma_f32 v26, v25, s4, -v26
	v_fmac_f32_e32 v26, 0x3377d1cf, v25
	v_fmac_f32_e32 v26, 0x3f317217, v25
	v_cmp_lt_f32_e64 s[0:1], |v25|, s90
	s_nop 1
	v_cndmask_b32_e64 v25, v25, v26, s[0:1]
	v_cndmask_b32_e32 v26, 0, v203, vcc
	v_sub_f32_e32 v25, v25, v26
	v_sub_f32_e32 v24, v24, v25
	v_fma_f32 v25, v16, v36, v11
	v_fmac_f32_e32 v25, v17, v37
	v_fmac_f32_e32 v25, v18, v38
	v_fmac_f32_e32 v25, v19, v39
	ds_read_b128 v[36:39], v21 offset:272
	v_fmamk_f32 v24, v24, 0x3d800000, v23
	s_waitcnt lgkmcnt(0)
	v_fmac_f32_e32 v25, v12, v36
	v_fmac_f32_e32 v25, v13, v37
	v_fmac_f32_e32 v25, v14, v38
	v_fmac_f32_e32 v25, v15, v39
	ds_read_b128 v[36:39], v21 offset:288
	s_waitcnt lgkmcnt(0)
	v_fmac_f32_e32 v25, v7, v36
	v_fmac_f32_e32 v25, v8, v37
	v_fmac_f32_e32 v25, v9, v38
	v_fmac_f32_e32 v25, v10, v39
	ds_read_b128 v[36:39], v21 offset:304
	s_waitcnt lgkmcnt(0)
	v_fmac_f32_e32 v25, v6, v36
	v_fmac_f32_e32 v25, v5, v37
	v_fmac_f32_e32 v25, v4, v38
	v_fmac_f32_e32 v25, v1, v39
	v_min_f32_e32 v26, 0, v25
	v_mul_f32_e64 v25, |v25|, s46
	v_exp_f32_e32 v25, v25
	ds_read_b128 v[36:39], v21 offset:320
	v_add_f32_e32 v25, 1.0, v25
	v_cmp_gt_f32_e32 vcc, s47, v25
	s_nop 1
	v_cndmask_b32_e64 v27, 0, 32, vcc
	v_ldexp_f32 v25, v25, v27
	v_log_f32_e32 v25, v25
	s_nop 0
	v_mul_f32_e32 v27, 0x3f317217, v25
	v_fma_f32 v27, v25, s4, -v27
	v_fmac_f32_e32 v27, 0x3377d1cf, v25
	v_fmac_f32_e32 v27, 0x3f317217, v25
	v_cmp_lt_f32_e64 s[0:1], |v25|, s90
	s_nop 1
	v_cndmask_b32_e64 v25, v25, v27, s[0:1]
	v_cndmask_b32_e32 v27, 0, v203, vcc
	v_sub_f32_e32 v25, v25, v27
	v_sub_f32_e32 v25, v26, v25
	s_waitcnt lgkmcnt(0)
	v_fma_f32 v26, v16, v36, v11
	v_fmac_f32_e32 v26, v17, v37
	v_fmac_f32_e32 v26, v18, v38
	v_fmac_f32_e32 v26, v19, v39
	ds_read_b128 v[36:39], v21 offset:336
	v_fmamk_f32 v25, v25, 0x3d800000, v24
	s_waitcnt lgkmcnt(0)
	v_fmac_f32_e32 v26, v12, v36
	v_fmac_f32_e32 v26, v13, v37
	v_fmac_f32_e32 v26, v14, v38
	v_fmac_f32_e32 v26, v15, v39
	ds_read_b128 v[36:39], v21 offset:352
	s_waitcnt lgkmcnt(0)
	v_fmac_f32_e32 v26, v7, v36
	v_fmac_f32_e32 v26, v8, v37
	v_fmac_f32_e32 v26, v9, v38
	v_fmac_f32_e32 v26, v10, v39
	ds_read_b128 v[36:39], v21 offset:368
	s_waitcnt lgkmcnt(0)
; DI float log_sigmoid_fast(float x) { return fminf(x, 0.f) - __logf(1.0f + __expf(-fabsf(x))); }
; template <int MODE>
; DI void gla4_unit(const bf16_t* z, float* ST, float* DEC, bf16_t* Y, const float* aw_g, const float* ab_g, const float* ng, ldsp lds, int tid, int u) {
;     ...
;     {
;         float run = 0.f;
; #pragma unroll
;         for (int i = 0; i < 32; ++i) {
;             const int t = 32 * half + i;
;             float al = ab;
; #pragma unroll
;             for (int r = 0; r < 16; ++r) al += alr[t * 16 + r] * aw[r];
;             run += log_sigmoid_fast(al) * (1.0f / 16.0f);
;             bc[i] = run;
;         }
	v_fmac_f32_e32 v26, v6, v36
	v_fmac_f32_e32 v26, v5, v37
	v_fmac_f32_e32 v26, v4, v38
	v_fmac_f32_e32 v26, v1, v39
	v_min_f32_e32 v27, 0, v26
	v_mul_f32_e64 v26, |v26|, s46
	v_exp_f32_e32 v26, v26
	ds_read_b128 v[36:39], v21 offset:384
	v_add_f32_e32 v26, 1.0, v26
	v_cmp_gt_f32_e32 vcc, s47, v26
	s_nop 1
	v_cndmask_b32_e64 v30, 0, 32, vcc
	v_ldexp_f32 v26, v26, v30
	v_log_f32_e32 v26, v26
	s_nop 0
	v_mul_f32_e32 v30, 0x3f317217, v26
	v_fma_f32 v30, v26, s4, -v30
	v_fmac_f32_e32 v30, 0x3377d1cf, v26
	v_fmac_f32_e32 v30, 0x3f317217, v26
	v_cmp_lt_f32_e64 s[0:1], |v26|, s90
	s_nop 1
	v_cndmask_b32_e64 v26, v26, v30, s[0:1]
	v_cndmask_b32_e32 v30, 0, v203, vcc
	v_sub_f32_e32 v26, v26, v30
	v_sub_f32_e32 v26, v27, v26
	s_waitcnt lgkmcnt(0)
	v_fma_f32 v27, v16, v36, v11
	v_fmac_f32_e32 v27, v17, v37
	v_fmac_f32_e32 v27, v18, v38
	v_fmac_f32_e32 v27, v19, v39
	ds_read_b128 v[36:39], v21 offset:400
	v_fmamk_f32 v26, v26, 0x3d800000, v25
	s_waitcnt lgkmcnt(0)
	v_fmac_f32_e32 v27, v12, v36
	v_fmac_f32_e32 v27, v13, v37
	v_fmac_f32_e32 v27, v14, v38
	v_fmac_f32_e32 v27, v15, v39
	ds_read_b128 v[36:39], v21 offset:416
	s_waitcnt lgkmcnt(0)
	v_fmac_f32_e32 v27, v7, v36
	v_fmac_f32_e32 v27, v8, v37
	v_fmac_f32_e32 v27, v9, v38
	v_fmac_f32_e32 v27, v10, v39
	ds_read_b128 v[36:39], v21 offset:432
	s_waitcnt lgkmcnt(0)
	v_fmac_f32_e32 v27, v6, v36
	v_fmac_f32_e32 v27, v5, v37
	v_fmac_f32_e32 v27, v4, v38
	v_fmac_f32_e32 v27, v1, v39
	v_min_f32_e32 v30, 0, v27
	v_mul_f32_e64 v27, |v27|, s46
	v_exp_f32_e32 v27, v27
	ds_read_b128 v[36:39], v21 offset:448
	v_add_f32_e32 v27, 1.0, v27
	v_cmp_gt_f32_e32 vcc, s47, v27
	s_nop 1
	v_cndmask_b32_e64 v31, 0, 32, vcc
	v_ldexp_f32 v27, v27, v31
	v_log_f32_e32 v27, v27
	s_nop 0
	v_mul_f32_e32 v31, 0x3f317217, v27
	v_fma_f32 v31, v27, s4, -v31
	v_fmac_f32_e32 v31, 0x3377d1cf, v27
	v_fmac_f32_e32 v31, 0x3f317217, v27
	v_cmp_lt_f32_e64 s[0:1], |v27|, s90
	s_nop 1
	v_cndmask_b32_e64 v27, v27, v31, s[0:1]
	v_cndmask_b32_e32 v31, 0, v203, vcc
	v_sub_f32_e32 v27, v27, v31
	v_sub_f32_e32 v27, v30, v27
	s_waitcnt lgkmcnt(0)
	v_fma_f32 v30, v16, v36, v11
	v_fmac_f32_e32 v30, v17, v37
	v_fmac_f32_e32 v30, v18, v38
	v_fmac_f32_e32 v30, v19, v39
	ds_read_b128 v[36:39], v21 offset:464
	v_fmamk_f32 v27, v27, 0x3d800000, v26
	s_waitcnt lgkmcnt(0)
	v_fmac_f32_e32 v30, v12, v36
	v_fmac_f32_e32 v30, v13, v37
	v_fmac_f32_e32 v30, v14, v38
	v_fmac_f32_e32 v30, v15, v39
	ds_read_b128 v[36:39], v21 offset:480
	s_waitcnt lgkmcnt(0)
	v_fmac_f32_e32 v30, v7, v36
	v_fmac_f32_e32 v30, v8, v37
	v_fmac_f32_e32 v30, v9, v38
	v_fmac_f32_e32 v30, v10, v39
	ds_read_b128 v[36:39], v21 offset:496
	s_waitcnt lgkmcnt(0)
	v_fmac_f32_e32 v30, v6, v36
	v_fmac_f32_e32 v30, v5, v37
	v_fmac_f32_e32 v30, v4, v38
	v_fmac_f32_e32 v30, v1, v39
	v_min_f32_e32 v31, 0, v30
	v_mul_f32_e64 v30, |v30|, s46
	v_exp_f32_e32 v30, v30
	ds_read_b128 v[36:39], v21 offset:512
	v_add_f32_e32 v30, 1.0, v30
	v_cmp_gt_f32_e32 vcc, s47, v30
	s_nop 1
	v_cndmask_b32_e64 v35, 0, 32, vcc
	v_ldexp_f32 v30, v30, v35
	v_log_f32_e32 v30, v30
	s_nop 0
	v_mul_f32_e32 v35, 0x3f317217, v30
	v_fma_f32 v35, v30, s4, -v35
	v_fmac_f32_e32 v35, 0x3377d1cf, v30
	v_fmac_f32_e32 v35, 0x3f317217, v30
	v_cmp_lt_f32_e64 s[0:1], |v30|, s90
	s_nop 1
	v_cndmask_b32_e64 v30, v30, v35, s[0:1]
	v_cndmask_b32_e32 v35, 0, v203, vcc
	v_sub_f32_e32 v30, v30, v35
	v_sub_f32_e32 v30, v31, v30
	s_waitcnt lgkmcnt(0)
	v_fma_f32 v31, v16, v36, v11
	v_fmac_f32_e32 v31, v17, v37
	v_fmac_f32_e32 v31, v18, v38
	v_fmac_f32_e32 v31, v19, v39
	ds_read_b128 v[36:39], v21 offset:528
	v_fmamk_f32 v30, v30, 0x3d800000, v27
	s_waitcnt lgkmcnt(0)
	v_fmac_f32_e32 v31, v12, v36
	v_fmac_f32_e32 v31, v13, v37
	v_fmac_f32_e32 v31, v14, v38
	v_fmac_f32_e32 v31, v15, v39
	ds_read_b128 v[36:39], v21 offset:544
	s_waitcnt lgkmcnt(0)
	v_fmac_f32_e32 v31, v7, v36
	v_fmac_f32_e32 v31, v8, v37
	v_fmac_f32_e32 v31, v9, v38
	v_fmac_f32_e32 v31, v10, v39
	ds_read_b128 v[36:39], v21 offset:560
	s_waitcnt lgkmcnt(0)
	v_fmac_f32_e32 v31, v6, v36
	v_fmac_f32_e32 v31, v5, v37
	v_fmac_f32_e32 v31, v4, v38
	v_fmac_f32_e32 v31, v1, v39
	v_min_f32_e32 v35, 0, v31
	v_mul_f32_e64 v31, |v31|, s46
	v_exp_f32_e32 v31, v31
	s_nop 0
	v_add_f32_e32 v31, 1.0, v31
	v_cmp_gt_f32_e32 vcc, s47, v31
	s_nop 1
	v_cndmask_b32_e64 v36, 0, 32, vcc
	v_ldexp_f32 v31, v31, v36
	v_log_f32_e32 v31, v31
	s_nop 0
	v_mul_f32_e32 v36, 0x3f317217, v31
	v_fma_f32 v36, v31, s4, -v36
	v_fmac_f32_e32 v36, 0x3377d1cf, v31
	v_fmac_f32_e32 v36, 0x3f317217, v31
	v_cmp_lt_f32_e64 s[0:1], |v31|, s90
	s_nop 1
	v_cndmask_b32_e64 v31, v31, v36, s[0:1]
	v_cndmask_b32_e32 v36, 0, v203, vcc
	v_sub_f32_e32 v31, v31, v36
	ds_read_b128 v[36:39], v21 offset:576
	v_sub_f32_e32 v31, v35, v31
	v_fmamk_f32 v31, v31, 0x3d800000, v30
	s_waitcnt lgkmcnt(0)
	v_fma_f32 v35, v16, v36, v11
	v_fmac_f32_e32 v35, v17, v37
	v_fmac_f32_e32 v35, v18, v38
	v_fmac_f32_e32 v35, v19, v39
	ds_read_b128 v[36:39], v21 offset:592
	s_waitcnt lgkmcnt(0)
	v_fmac_f32_e32 v35, v12, v36
	v_fmac_f32_e32 v35, v13, v37
	v_fmac_f32_e32 v35, v14, v38
	v_fmac_f32_e32 v35, v15, v39
	ds_read_b128 v[36:39], v21 offset:608
	s_waitcnt lgkmcnt(0)
	v_fmac_f32_e32 v35, v7, v36
	v_fmac_f32_e32 v35, v8, v37
	v_fmac_f32_e32 v35, v9, v38
	v_fmac_f32_e32 v35, v10, v39
	ds_read_b128 v[36:39], v21 offset:624
	s_waitcnt lgkmcnt(0)
; DI float log_sigmoid_fast(float x) { return fminf(x, 0.f) - __logf(1.0f + __expf(-fabsf(x))); }
; template <int MODE>
; DI void gla4_unit(const bf16_t* z, float* ST, float* DEC, bf16_t* Y, const float* aw_g, const float* ab_g, const float* ng, ldsp lds, int tid, int u) {
;     ...
;     {
;         float run = 0.f;
; #pragma unroll
;         for (int i = 0; i < 32; ++i) {
;             const int t = 32 * half + i;
;             float al = ab;
; #pragma unroll
;             for (int r = 0; r < 16; ++r) al += alr[t * 16 + r] * aw[r];
;             run += log_sigmoid_fast(al) * (1.0f / 16.0f);
;             bc[i] = run;
;         }
	v_fmac_f32_e32 v35, v6, v36
	v_fmac_f32_e32 v35, v5, v37
	v_fmac_f32_e32 v35, v4, v38
	v_fmac_f32_e32 v35, v1, v39
	v_min_f32_e32 v36, 0, v35
	v_mul_f32_e64 v35, |v35|, s46
	v_exp_f32_e32 v35, v35
	s_nop 0
	v_add_f32_e32 v35, 1.0, v35
	v_cmp_gt_f32_e32 vcc, s47, v35
	s_nop 1
	v_cndmask_b32_e64 v37, 0, 32, vcc
	v_ldexp_f32 v35, v35, v37
	v_log_f32_e32 v35, v35
	s_nop 0
	v_mul_f32_e32 v37, 0x3f317217, v35
	v_fma_f32 v37, v35, s4, -v37
	v_fmac_f32_e32 v37, 0x3377d1cf, v35
	v_fmac_f32_e32 v37, 0x3f317217, v35
	v_cmp_lt_f32_e64 s[0:1], |v35|, s90
	s_nop 1
	v_cndmask_b32_e64 v35, v35, v37, s[0:1]
	v_cndmask_b32_e32 v37, 0, v203, vcc
	v_sub_f32_e32 v35, v35, v37
	v_sub_f32_e32 v35, v36, v35
	ds_read_b128 v[36:39], v21 offset:640
	v_fmamk_f32 v35, v35, 0x3d800000, v31
	s_waitcnt lgkmcnt(0)
	v_fma_f32 v40, v16, v36, v11
	v_fmac_f32_e32 v40, v17, v37
	v_fmac_f32_e32 v40, v18, v38
	v_fmac_f32_e32 v40, v19, v39
	ds_read_b128 v[36:39], v21 offset:656
	s_waitcnt lgkmcnt(0)
	v_fmac_f32_e32 v40, v12, v36
	v_fmac_f32_e32 v40, v13, v37
	v_fmac_f32_e32 v40, v14, v38
	v_fmac_f32_e32 v40, v15, v39
	ds_read_b128 v[36:39], v21 offset:672
	s_waitcnt lgkmcnt(0)
	v_fmac_f32_e32 v40, v7, v36
	v_fmac_f32_e32 v40, v8, v37
	v_fmac_f32_e32 v40, v9, v38
	v_fmac_f32_e32 v40, v10, v39
	ds_read_b128 v[36:39], v21 offset:688
	s_waitcnt lgkmcnt(0)
	v_fmac_f32_e32 v40, v6, v36
	v_fmac_f32_e32 v40, v5, v37
	v_fmac_f32_e32 v40, v4, v38
	v_fmac_f32_e32 v40, v1, v39
	v_mul_f32_e64 v37, |v40|, s46
	v_exp_f32_e32 v37, v37
	v_min_f32_e32 v36, 0, v40
	v_add_f32_e32 v37, 1.0, v37
	v_cmp_gt_f32_e32 vcc, s47, v37
	s_nop 1
	v_cndmask_b32_e64 v38, 0, 32, vcc
	v_ldexp_f32 v37, v37, v38
	v_log_f32_e32 v37, v37
	s_nop 0
	v_mul_f32_e32 v38, 0x3f317217, v37
	v_fma_f32 v38, v37, s4, -v38
	v_fmac_f32_e32 v38, 0x3377d1cf, v37
	v_fmac_f32_e32 v38, 0x3f317217, v37
	v_cmp_lt_f32_e64 s[0:1], |v37|, s90
	s_nop 1
	v_cndmask_b32_e64 v37, v37, v38, s[0:1]
	v_cndmask_b32_e32 v38, 0, v203, vcc
	v_sub_f32_e32 v37, v37, v38
	ds_read_b128 v[38:41], v21 offset:704
	v_sub_f32_e32 v36, v36, v37
	v_fmamk_f32 v36, v36, 0x3d800000, v35
	s_waitcnt lgkmcnt(0)
	v_fma_f32 v37, v16, v38, v11
	v_fmac_f32_e32 v37, v17, v39
	v_fmac_f32_e32 v37, v18, v40
	v_fmac_f32_e32 v37, v19, v41
	ds_read_b128 v[38:41], v21 offset:720
	s_waitcnt lgkmcnt(0)
	v_fmac_f32_e32 v37, v12, v38
	v_fmac_f32_e32 v37, v13, v39
	v_fmac_f32_e32 v37, v14, v40
	v_fmac_f32_e32 v37, v15, v41
	ds_read_b128 v[38:41], v21 offset:736
	s_waitcnt lgkmcnt(0)
	v_fmac_f32_e32 v37, v7, v38
	v_fmac_f32_e32 v37, v8, v39
	v_fmac_f32_e32 v37, v9, v40
	v_fmac_f32_e32 v37, v10, v41
	ds_read_b128 v[38:41], v21 offset:752
	s_waitcnt lgkmcnt(0)
	v_fmac_f32_e32 v37, v6, v38
	v_fmac_f32_e32 v37, v5, v39
	v_fmac_f32_e32 v37, v4, v40
	v_fmac_f32_e32 v37, v1, v41
	v_min_f32_e32 v38, 0, v37
	v_mul_f32_e64 v37, |v37|, s46
	v_exp_f32_e32 v37, v37
	s_nop 0
	v_add_f32_e32 v37, 1.0, v37
	v_cmp_gt_f32_e32 vcc, s47, v37
	s_nop 1
	v_cndmask_b32_e64 v39, 0, 32, vcc
	v_ldexp_f32 v37, v37, v39
	v_log_f32_e32 v37, v37
	s_nop 0
	v_mul_f32_e32 v39, 0x3f317217, v37
	v_fma_f32 v39, v37, s4, -v39
	v_fmac_f32_e32 v39, 0x3377d1cf, v37
	v_fmac_f32_e32 v39, 0x3f317217, v37
	v_cmp_lt_f32_e64 s[0:1], |v37|, s90
	s_nop 1
	v_cndmask_b32_e64 v37, v37, v39, s[0:1]
	v_cndmask_b32_e32 v39, 0, v203, vcc
	v_sub_f32_e32 v37, v37, v39
	v_sub_f32_e32 v37, v38, v37
	ds_read_b128 v[38:41], v21 offset:768
	v_fmamk_f32 v37, v37, 0x3d800000, v36
	s_waitcnt lgkmcnt(0)
	v_fma_f32 v42, v16, v38, v11
	v_fmac_f32_e32 v42, v17, v39
	v_fmac_f32_e32 v42, v18, v40
	v_fmac_f32_e32 v42, v19, v41
	ds_read_b128 v[38:41], v21 offset:784
	s_waitcnt lgkmcnt(0)
	v_fmac_f32_e32 v42, v12, v38
	v_fmac_f32_e32 v42, v13, v39
	v_fmac_f32_e32 v42, v14, v40
	v_fmac_f32_e32 v42, v15, v41
	ds_read_b128 v[38:41], v21 offset:800
	s_waitcnt lgkmcnt(0)
	v_fmac_f32_e32 v42, v7, v38
	v_fmac_f32_e32 v42, v8, v39
	v_fmac_f32_e32 v42, v9, v40
	v_fmac_f32_e32 v42, v10, v41
	ds_read_b128 v[38:41], v21 offset:816
	s_waitcnt lgkmcnt(0)
	v_fmac_f32_e32 v42, v6, v38
	v_fmac_f32_e32 v42, v5, v39
	v_fmac_f32_e32 v42, v4, v40
	v_fmac_f32_e32 v42, v1, v41
	v_mul_f32_e64 v39, |v42|, s46
	v_exp_f32_e32 v39, v39
	v_min_f32_e32 v38, 0, v42
	v_add_f32_e32 v39, 1.0, v39
	v_cmp_gt_f32_e32 vcc, s47, v39
	s_nop 1
	v_cndmask_b32_e64 v40, 0, 32, vcc
	v_ldexp_f32 v39, v39, v40
	v_log_f32_e32 v39, v39
	s_nop 0
	v_mul_f32_e32 v40, 0x3f317217, v39
	v_fma_f32 v40, v39, s4, -v40
	v_fmac_f32_e32 v40, 0x3377d1cf, v39
	v_fmac_f32_e32 v40, 0x3f317217, v39
	v_cmp_lt_f32_e64 s[0:1], |v39|, s90
	s_nop 1
	v_cndmask_b32_e64 v39, v39, v40, s[0:1]
	v_cndmask_b32_e32 v40, 0, v203, vcc
	v_sub_f32_e32 v39, v39, v40
	ds_read_b128 v[40:43], v21 offset:832
	v_sub_f32_e32 v38, v38, v39
	v_fmamk_f32 v38, v38, 0x3d800000, v37
	s_waitcnt lgkmcnt(0)
	v_fma_f32 v39, v16, v40, v11
	v_fmac_f32_e32 v39, v17, v41
	v_fmac_f32_e32 v39, v18, v42
	v_fmac_f32_e32 v39, v19, v43
	ds_read_b128 v[40:43], v21 offset:848
	s_waitcnt lgkmcnt(0)
	v_fmac_f32_e32 v39, v12, v40
	v_fmac_f32_e32 v39, v13, v41
	v_fmac_f32_e32 v39, v14, v42
	v_fmac_f32_e32 v39, v15, v43
	ds_read_b128 v[40:43], v21 offset:864
	s_waitcnt lgkmcnt(0)
	v_fmac_f32_e32 v39, v7, v40
	v_fmac_f32_e32 v39, v8, v41
	v_fmac_f32_e32 v39, v9, v42
	v_fmac_f32_e32 v39, v10, v43
	ds_read_b128 v[40:43], v21 offset:880
	s_waitcnt lgkmcnt(0)
; DI float log_sigmoid_fast(float x) { return fminf(x, 0.f) - __logf(1.0f + __expf(-fabsf(x))); }
; template <int MODE>
; DI void gla4_unit(const bf16_t* z, float* ST, float* DEC, bf16_t* Y, const float* aw_g, const float* ab_g, const float* ng, ldsp lds, int tid, int u) {
;     ...
;     {
;         float run = 0.f;
; #pragma unroll
;         for (int i = 0; i < 32; ++i) {
;             const int t = 32 * half + i;
;             float al = ab;
; #pragma unroll
;             for (int r = 0; r < 16; ++r) al += alr[t * 16 + r] * aw[r];
;             run += log_sigmoid_fast(al) * (1.0f / 16.0f);
;             bc[i] = run;
;         }
	v_fmac_f32_e32 v39, v6, v40
	v_fmac_f32_e32 v39, v5, v41
	v_fmac_f32_e32 v39, v4, v42
	v_fmac_f32_e32 v39, v1, v43
	v_min_f32_e32 v40, 0, v39
	v_mul_f32_e64 v39, |v39|, s46
	v_exp_f32_e32 v39, v39
	s_nop 0
	v_add_f32_e32 v39, 1.0, v39
	v_cmp_gt_f32_e32 vcc, s47, v39
	s_nop 1
	v_cndmask_b32_e64 v41, 0, 32, vcc
	v_ldexp_f32 v39, v39, v41
	v_log_f32_e32 v39, v39
	s_nop 0
	v_mul_f32_e32 v41, 0x3f317217, v39
	v_fma_f32 v41, v39, s4, -v41
	v_fmac_f32_e32 v41, 0x3377d1cf, v39
	v_fmac_f32_e32 v41, 0x3f317217, v39
	v_cmp_lt_f32_e64 s[0:1], |v39|, s90
	s_nop 1
	v_cndmask_b32_e64 v39, v39, v41, s[0:1]
	v_cndmask_b32_e32 v41, 0, v203, vcc
	v_sub_f32_e32 v39, v39, v41
	v_sub_f32_e32 v39, v40, v39
	ds_read_b128 v[40:43], v21 offset:896
	v_fmamk_f32 v39, v39, 0x3d800000, v38
	s_waitcnt lgkmcnt(0)
	v_fma_f32 v44, v16, v40, v11
	v_fmac_f32_e32 v44, v17, v41
	v_fmac_f32_e32 v44, v18, v42
	v_fmac_f32_e32 v44, v19, v43
	ds_read_b128 v[40:43], v21 offset:912
	s_waitcnt lgkmcnt(0)
	v_fmac_f32_e32 v44, v12, v40
	v_fmac_f32_e32 v44, v13, v41
	v_fmac_f32_e32 v44, v14, v42
	v_fmac_f32_e32 v44, v15, v43
	ds_read_b128 v[40:43], v21 offset:928
	s_waitcnt lgkmcnt(0)
	v_fmac_f32_e32 v44, v7, v40
	v_fmac_f32_e32 v44, v8, v41
	v_fmac_f32_e32 v44, v9, v42
	v_fmac_f32_e32 v44, v10, v43
	ds_read_b128 v[40:43], v21 offset:944
	s_waitcnt lgkmcnt(0)
	v_fmac_f32_e32 v44, v6, v40
	v_fmac_f32_e32 v44, v5, v41
	v_fmac_f32_e32 v44, v4, v42
	v_fmac_f32_e32 v44, v1, v43
	v_mul_f32_e64 v41, |v44|, s46
	v_exp_f32_e32 v41, v41
	v_min_f32_e32 v40, 0, v44
	v_add_f32_e32 v41, 1.0, v41
	v_cmp_gt_f32_e32 vcc, s47, v41
	s_nop 1
	v_cndmask_b32_e64 v42, 0, 32, vcc
	v_ldexp_f32 v41, v41, v42
	v_log_f32_e32 v41, v41
	s_nop 0
	v_mul_f32_e32 v42, 0x3f317217, v41
	v_fma_f32 v42, v41, s4, -v42
	v_fmac_f32_e32 v42, 0x3377d1cf, v41
	v_fmac_f32_e32 v42, 0x3f317217, v41
	v_cmp_lt_f32_e64 s[0:1], |v41|, s90
	s_nop 1
	v_cndmask_b32_e64 v41, v41, v42, s[0:1]
	v_cndmask_b32_e32 v42, 0, v203, vcc
	v_sub_f32_e32 v41, v41, v42
	ds_read_b128 v[42:45], v21 offset:960
	v_sub_f32_e32 v40, v40, v41
	v_fmamk_f32 v40, v40, 0x3d800000, v39
	s_waitcnt lgkmcnt(0)
	v_fma_f32 v41, v16, v42, v11
	v_fmac_f32_e32 v41, v17, v43
	v_fmac_f32_e32 v41, v18, v44
	v_fmac_f32_e32 v41, v19, v45
	ds_read_b128 v[42:45], v21 offset:976
	s_waitcnt lgkmcnt(0)
	v_fmac_f32_e32 v41, v12, v42
	v_fmac_f32_e32 v41, v13, v43
	v_fmac_f32_e32 v41, v14, v44
	v_fmac_f32_e32 v41, v15, v45
	ds_read_b128 v[42:45], v21 offset:992
	s_waitcnt lgkmcnt(0)
	v_fmac_f32_e32 v41, v7, v42
	v_fmac_f32_e32 v41, v8, v43
	v_fmac_f32_e32 v41, v9, v44
	v_fmac_f32_e32 v41, v10, v45
	ds_read_b128 v[42:45], v21 offset:1008
	s_waitcnt lgkmcnt(0)
	v_fmac_f32_e32 v41, v6, v42
	v_fmac_f32_e32 v41, v5, v43
	v_fmac_f32_e32 v41, v4, v44
	v_fmac_f32_e32 v41, v1, v45
	v_min_f32_e32 v42, 0, v41
	v_mul_f32_e64 v41, |v41|, s46
	v_exp_f32_e32 v41, v41
	s_nop 0
	v_add_f32_e32 v41, 1.0, v41
	v_cmp_gt_f32_e32 vcc, s47, v41
	s_nop 1
	v_cndmask_b32_e64 v43, 0, 32, vcc
	v_ldexp_f32 v41, v41, v43
	v_log_f32_e32 v41, v41
	s_nop 0
	v_mul_f32_e32 v43, 0x3f317217, v41
	v_fma_f32 v43, v41, s4, -v43
	v_fmac_f32_e32 v43, 0x3377d1cf, v41
	v_fmac_f32_e32 v43, 0x3f317217, v41
	v_cmp_lt_f32_e64 s[0:1], |v41|, s90
	s_nop 1
	v_cndmask_b32_e64 v41, v41, v43, s[0:1]
	v_cndmask_b32_e32 v43, 0, v203, vcc
	v_sub_f32_e32 v41, v41, v43
	v_sub_f32_e32 v41, v42, v41
	ds_read_b128 v[42:45], v21 offset:1024
	v_fmamk_f32 v41, v41, 0x3d800000, v40
	s_waitcnt lgkmcnt(0)
	v_fma_f32 v46, v16, v42, v11
	v_fmac_f32_e32 v46, v17, v43
	v_fmac_f32_e32 v46, v18, v44
	v_fmac_f32_e32 v46, v19, v45
	ds_read_b128 v[42:45], v21 offset:1040
	s_waitcnt lgkmcnt(0)
	v_fmac_f32_e32 v46, v12, v42
	v_fmac_f32_e32 v46, v13, v43
	v_fmac_f32_e32 v46, v14, v44
	v_fmac_f32_e32 v46, v15, v45
	ds_read_b128 v[42:45], v21 offset:1056
	s_waitcnt lgkmcnt(0)
	v_fmac_f32_e32 v46, v7, v42
	v_fmac_f32_e32 v46, v8, v43
	v_fmac_f32_e32 v46, v9, v44
	v_fmac_f32_e32 v46, v10, v45
	ds_read_b128 v[42:45], v21 offset:1072
	s_waitcnt lgkmcnt(0)
	v_fmac_f32_e32 v46, v6, v42
	v_fmac_f32_e32 v46, v5, v43
	v_fmac_f32_e32 v46, v4, v44
	v_fmac_f32_e32 v46, v1, v45
	v_mul_f32_e64 v43, |v46|, s46
	v_exp_f32_e32 v43, v43
	v_min_f32_e32 v42, 0, v46
	v_add_f32_e32 v43, 1.0, v43
	v_cmp_gt_f32_e32 vcc, s47, v43
	s_nop 1
	v_cndmask_b32_e64 v44, 0, 32, vcc
	v_ldexp_f32 v43, v43, v44
	v_log_f32_e32 v43, v43
	s_nop 0
	v_mul_f32_e32 v44, 0x3f317217, v43
	v_fma_f32 v44, v43, s4, -v44
	v_fmac_f32_e32 v44, 0x3377d1cf, v43
	v_fmac_f32_e32 v44, 0x3f317217, v43
	v_cmp_lt_f32_e64 s[0:1], |v43|, s90
	s_nop 1
	v_cndmask_b32_e64 v43, v43, v44, s[0:1]
	v_cndmask_b32_e32 v44, 0, v203, vcc
	v_sub_f32_e32 v43, v43, v44
	ds_read_b128 v[44:47], v21 offset:1088
	v_sub_f32_e32 v42, v42, v43
	v_fmamk_f32 v42, v42, 0x3d800000, v41
	s_waitcnt lgkmcnt(0)
	v_fma_f32 v43, v16, v44, v11
	v_fmac_f32_e32 v43, v17, v45
	v_fmac_f32_e32 v43, v18, v46
	v_fmac_f32_e32 v43, v19, v47
	ds_read_b128 v[44:47], v21 offset:1104
	s_waitcnt lgkmcnt(0)
	v_fmac_f32_e32 v43, v12, v44
	v_fmac_f32_e32 v43, v13, v45
	v_fmac_f32_e32 v43, v14, v46
	v_fmac_f32_e32 v43, v15, v47
	ds_read_b128 v[44:47], v21 offset:1120
	s_waitcnt lgkmcnt(0)
	v_fmac_f32_e32 v43, v7, v44
	v_fmac_f32_e32 v43, v8, v45
	v_fmac_f32_e32 v43, v9, v46
	v_fmac_f32_e32 v43, v10, v47
	ds_read_b128 v[44:47], v21 offset:1136
	s_waitcnt lgkmcnt(0)
; DI float log_sigmoid_fast(float x) { return fminf(x, 0.f) - __logf(1.0f + __expf(-fabsf(x))); }
; template <int MODE>
; DI void gla4_unit(const bf16_t* z, float* ST, float* DEC, bf16_t* Y, const float* aw_g, const float* ab_g, const float* ng, ldsp lds, int tid, int u) {
;     ...
;     {
;         float run = 0.f;
; #pragma unroll
;         for (int i = 0; i < 32; ++i) {
;             const int t = 32 * half + i;
;             float al = ab;
; #pragma unroll
;             for (int r = 0; r < 16; ++r) al += alr[t * 16 + r] * aw[r];
;             run += log_sigmoid_fast(al) * (1.0f / 16.0f);
;             bc[i] = run;
;         }
	v_fmac_f32_e32 v43, v6, v44
	v_fmac_f32_e32 v43, v5, v45
	v_fmac_f32_e32 v43, v4, v46
	v_fmac_f32_e32 v43, v1, v47
	v_min_f32_e32 v44, 0, v43
	v_mul_f32_e64 v43, |v43|, s46
	v_exp_f32_e32 v43, v43
	s_nop 0
	v_add_f32_e32 v43, 1.0, v43
	v_cmp_gt_f32_e32 vcc, s47, v43
	s_nop 1
	v_cndmask_b32_e64 v45, 0, 32, vcc
	v_ldexp_f32 v43, v43, v45
	v_log_f32_e32 v43, v43
	s_nop 0
	v_mul_f32_e32 v45, 0x3f317217, v43
	v_fma_f32 v45, v43, s4, -v45
	v_fmac_f32_e32 v45, 0x3377d1cf, v43
	v_fmac_f32_e32 v45, 0x3f317217, v43
	v_cmp_lt_f32_e64 s[0:1], |v43|, s90
	s_nop 1
	v_cndmask_b32_e64 v43, v43, v45, s[0:1]
	v_cndmask_b32_e32 v45, 0, v203, vcc
	v_sub_f32_e32 v43, v43, v45
	v_sub_f32_e32 v43, v44, v43
	ds_read_b128 v[44:47], v21 offset:1152
	v_fmamk_f32 v43, v43, 0x3d800000, v42
	s_waitcnt lgkmcnt(0)
	v_fma_f32 v48, v16, v44, v11
	v_fmac_f32_e32 v48, v17, v45
	v_fmac_f32_e32 v48, v18, v46
	v_fmac_f32_e32 v48, v19, v47
	ds_read_b128 v[44:47], v21 offset:1168
	s_waitcnt lgkmcnt(0)
	v_fmac_f32_e32 v48, v12, v44
	v_fmac_f32_e32 v48, v13, v45
	v_fmac_f32_e32 v48, v14, v46
	v_fmac_f32_e32 v48, v15, v47
	ds_read_b128 v[44:47], v21 offset:1184
	s_waitcnt lgkmcnt(0)
	v_fmac_f32_e32 v48, v7, v44
	v_fmac_f32_e32 v48, v8, v45
	v_fmac_f32_e32 v48, v9, v46
	v_fmac_f32_e32 v48, v10, v47
	ds_read_b128 v[44:47], v21 offset:1200
	s_waitcnt lgkmcnt(0)
	v_fmac_f32_e32 v48, v6, v44
	v_fmac_f32_e32 v48, v5, v45
	v_fmac_f32_e32 v48, v4, v46
	v_fmac_f32_e32 v48, v1, v47
	v_mul_f32_e64 v45, |v48|, s46
	v_exp_f32_e32 v45, v45
	v_min_f32_e32 v44, 0, v48
	v_add_f32_e32 v45, 1.0, v45
	v_cmp_gt_f32_e32 vcc, s47, v45
	s_nop 1
	v_cndmask_b32_e64 v46, 0, 32, vcc
	v_ldexp_f32 v45, v45, v46
	v_log_f32_e32 v45, v45
	s_nop 0
	v_mul_f32_e32 v46, 0x3f317217, v45
	v_fma_f32 v46, v45, s4, -v46
	v_fmac_f32_e32 v46, 0x3377d1cf, v45
	v_fmac_f32_e32 v46, 0x3f317217, v45
	v_cmp_lt_f32_e64 s[0:1], |v45|, s90
	s_nop 1
	v_cndmask_b32_e64 v45, v45, v46, s[0:1]
	v_cndmask_b32_e32 v46, 0, v203, vcc
	v_sub_f32_e32 v45, v45, v46
	ds_read_b128 v[46:49], v21 offset:1216
	v_sub_f32_e32 v44, v44, v45
	v_fmamk_f32 v44, v44, 0x3d800000, v43
	s_waitcnt lgkmcnt(0)
	v_fma_f32 v45, v16, v46, v11
	v_fmac_f32_e32 v45, v17, v47
	v_fmac_f32_e32 v45, v18, v48
	v_fmac_f32_e32 v45, v19, v49
	ds_read_b128 v[46:49], v21 offset:1232
	s_waitcnt lgkmcnt(0)
	v_fmac_f32_e32 v45, v12, v46
	v_fmac_f32_e32 v45, v13, v47
	v_fmac_f32_e32 v45, v14, v48
	v_fmac_f32_e32 v45, v15, v49
	ds_read_b128 v[46:49], v21 offset:1248
	s_waitcnt lgkmcnt(0)
	v_fmac_f32_e32 v45, v7, v46
	v_fmac_f32_e32 v45, v8, v47
	v_fmac_f32_e32 v45, v9, v48
	v_fmac_f32_e32 v45, v10, v49
	ds_read_b128 v[46:49], v21 offset:1264
	s_waitcnt lgkmcnt(0)
	v_fmac_f32_e32 v45, v6, v46
	v_fmac_f32_e32 v45, v5, v47
	v_fmac_f32_e32 v45, v4, v48
	v_fmac_f32_e32 v45, v1, v49
	v_min_f32_e32 v46, 0, v45
	v_mul_f32_e64 v45, |v45|, s46
	v_exp_f32_e32 v45, v45
	s_nop 0
	v_add_f32_e32 v45, 1.0, v45
	v_cmp_gt_f32_e32 vcc, s47, v45
	s_nop 1
	v_cndmask_b32_e64 v47, 0, 32, vcc
	v_ldexp_f32 v45, v45, v47
	v_log_f32_e32 v45, v45
	s_nop 0
	v_mul_f32_e32 v47, 0x3f317217, v45
	v_fma_f32 v47, v45, s4, -v47
	v_fmac_f32_e32 v47, 0x3377d1cf, v45
	v_fmac_f32_e32 v47, 0x3f317217, v45
	v_cmp_lt_f32_e64 s[0:1], |v45|, s90
	s_nop 1
	v_cndmask_b32_e64 v45, v45, v47, s[0:1]
	v_cndmask_b32_e32 v47, 0, v203, vcc
	v_sub_f32_e32 v45, v45, v47
	v_sub_f32_e32 v45, v46, v45
	ds_read_b128 v[46:49], v21 offset:1280
	v_fmamk_f32 v45, v45, 0x3d800000, v44
	s_waitcnt lgkmcnt(0)
	v_fma_f32 v50, v16, v46, v11
	v_fmac_f32_e32 v50, v17, v47
	v_fmac_f32_e32 v50, v18, v48
	v_fmac_f32_e32 v50, v19, v49
	ds_read_b128 v[46:49], v21 offset:1296
	s_waitcnt lgkmcnt(0)
	v_fmac_f32_e32 v50, v12, v46
	v_fmac_f32_e32 v50, v13, v47
	v_fmac_f32_e32 v50, v14, v48
	v_fmac_f32_e32 v50, v15, v49
	ds_read_b128 v[46:49], v21 offset:1312
	s_waitcnt lgkmcnt(0)
	v_fmac_f32_e32 v50, v7, v46
	v_fmac_f32_e32 v50, v8, v47
	v_fmac_f32_e32 v50, v9, v48
	v_fmac_f32_e32 v50, v10, v49
	ds_read_b128 v[46:49], v21 offset:1328
	s_waitcnt lgkmcnt(0)
	v_fmac_f32_e32 v50, v6, v46
	v_fmac_f32_e32 v50, v5, v47
	v_fmac_f32_e32 v50, v4, v48
	v_fmac_f32_e32 v50, v1, v49
	v_mul_f32_e64 v47, |v50|, s46
	v_exp_f32_e32 v47, v47
	v_min_f32_e32 v46, 0, v50
	v_add_f32_e32 v47, 1.0, v47
	v_cmp_gt_f32_e32 vcc, s47, v47
	s_nop 1
	v_cndmask_b32_e64 v48, 0, 32, vcc
	v_ldexp_f32 v47, v47, v48
	v_log_f32_e32 v47, v47
	s_nop 0
	v_mul_f32_e32 v48, 0x3f317217, v47
	v_fma_f32 v48, v47, s4, -v48
	v_fmac_f32_e32 v48, 0x3377d1cf, v47
	v_fmac_f32_e32 v48, 0x3f317217, v47
	v_cmp_lt_f32_e64 s[0:1], |v47|, s90
	s_nop 1
	v_cndmask_b32_e64 v47, v47, v48, s[0:1]
	v_cndmask_b32_e32 v48, 0, v203, vcc
	v_sub_f32_e32 v47, v47, v48
	ds_read_b128 v[48:51], v21 offset:1344
	v_sub_f32_e32 v46, v46, v47
	v_fmamk_f32 v46, v46, 0x3d800000, v45
	s_waitcnt lgkmcnt(0)
	v_fma_f32 v47, v16, v48, v11
	v_fmac_f32_e32 v47, v17, v49
	v_fmac_f32_e32 v47, v18, v50
	v_fmac_f32_e32 v47, v19, v51
	ds_read_b128 v[48:51], v21 offset:1360
	s_waitcnt lgkmcnt(0)
	v_fmac_f32_e32 v47, v12, v48
	v_fmac_f32_e32 v47, v13, v49
	v_fmac_f32_e32 v47, v14, v50
	v_fmac_f32_e32 v47, v15, v51
	ds_read_b128 v[48:51], v21 offset:1376
	s_waitcnt lgkmcnt(0)
	v_fmac_f32_e32 v47, v7, v48
	v_fmac_f32_e32 v47, v8, v49
	v_fmac_f32_e32 v47, v9, v50
	v_fmac_f32_e32 v47, v10, v51
	ds_read_b128 v[48:51], v21 offset:1392
	s_waitcnt lgkmcnt(0)
; DI float log_sigmoid_fast(float x) { return fminf(x, 0.f) - __logf(1.0f + __expf(-fabsf(x))); }
; template <int MODE>
; DI void gla4_unit(const bf16_t* z, float* ST, float* DEC, bf16_t* Y, const float* aw_g, const float* ab_g, const float* ng, ldsp lds, int tid, int u) {
;     ...
;     {
;         float run = 0.f;
; #pragma unroll
;         for (int i = 0; i < 32; ++i) {
;             const int t = 32 * half + i;
;             float al = ab;
; #pragma unroll
;             for (int r = 0; r < 16; ++r) al += alr[t * 16 + r] * aw[r];
;             run += log_sigmoid_fast(al) * (1.0f / 16.0f);
;             bc[i] = run;
;         }
	v_fmac_f32_e32 v47, v6, v48
	v_fmac_f32_e32 v47, v5, v49
	v_fmac_f32_e32 v47, v4, v50
	v_fmac_f32_e32 v47, v1, v51
	v_min_f32_e32 v48, 0, v47
	v_mul_f32_e64 v47, |v47|, s46
	v_exp_f32_e32 v47, v47
	s_nop 0
	v_add_f32_e32 v47, 1.0, v47
	v_cmp_gt_f32_e32 vcc, s47, v47
	s_nop 1
	v_cndmask_b32_e64 v49, 0, 32, vcc
	v_ldexp_f32 v47, v47, v49
	v_log_f32_e32 v47, v47
	s_nop 0
	v_mul_f32_e32 v49, 0x3f317217, v47
	v_fma_f32 v49, v47, s4, -v49
	v_fmac_f32_e32 v49, 0x3377d1cf, v47
	v_fmac_f32_e32 v49, 0x3f317217, v47
	v_cmp_lt_f32_e64 s[0:1], |v47|, s90
	s_nop 1
	v_cndmask_b32_e64 v47, v47, v49, s[0:1]
	v_cndmask_b32_e32 v49, 0, v203, vcc
	v_sub_f32_e32 v47, v47, v49
	v_sub_f32_e32 v47, v48, v47
	ds_read_b128 v[48:51], v21 offset:1408
	v_fmamk_f32 v47, v47, 0x3d800000, v46
	s_waitcnt lgkmcnt(0)
	v_fma_f32 v52, v16, v48, v11
	v_fmac_f32_e32 v52, v17, v49
	v_fmac_f32_e32 v52, v18, v50
	v_fmac_f32_e32 v52, v19, v51
	ds_read_b128 v[48:51], v21 offset:1424
	s_waitcnt lgkmcnt(0)
	v_fmac_f32_e32 v52, v12, v48
	v_fmac_f32_e32 v52, v13, v49
	v_fmac_f32_e32 v52, v14, v50
	v_fmac_f32_e32 v52, v15, v51
	ds_read_b128 v[48:51], v21 offset:1440
	s_waitcnt lgkmcnt(0)
	v_fmac_f32_e32 v52, v7, v48
	v_fmac_f32_e32 v52, v8, v49
	v_fmac_f32_e32 v52, v9, v50
	v_fmac_f32_e32 v52, v10, v51
	ds_read_b128 v[48:51], v21 offset:1456
	s_waitcnt lgkmcnt(0)
	v_fmac_f32_e32 v52, v6, v48
	v_fmac_f32_e32 v52, v5, v49
	v_fmac_f32_e32 v52, v4, v50
	v_fmac_f32_e32 v52, v1, v51
	v_mul_f32_e64 v49, |v52|, s46
	v_exp_f32_e32 v49, v49
	v_min_f32_e32 v48, 0, v52
	v_add_f32_e32 v49, 1.0, v49
	v_cmp_gt_f32_e32 vcc, s47, v49
	s_nop 1
	v_cndmask_b32_e64 v50, 0, 32, vcc
	v_ldexp_f32 v49, v49, v50
	v_log_f32_e32 v49, v49
	s_nop 0
	v_mul_f32_e32 v50, 0x3f317217, v49
	v_fma_f32 v50, v49, s4, -v50
	v_fmac_f32_e32 v50, 0x3377d1cf, v49
	v_fmac_f32_e32 v50, 0x3f317217, v49
	v_cmp_lt_f32_e64 s[0:1], |v49|, s90
	s_nop 1
	v_cndmask_b32_e64 v49, v49, v50, s[0:1]
	v_cndmask_b32_e32 v50, 0, v203, vcc
	v_sub_f32_e32 v49, v49, v50
	ds_read_b128 v[50:53], v21 offset:1472
	v_sub_f32_e32 v48, v48, v49
	v_fmamk_f32 v48, v48, 0x3d800000, v47
	s_waitcnt lgkmcnt(0)
	v_fma_f32 v49, v16, v50, v11
	v_fmac_f32_e32 v49, v17, v51
	v_fmac_f32_e32 v49, v18, v52
	v_fmac_f32_e32 v49, v19, v53
	ds_read_b128 v[50:53], v21 offset:1488
	s_waitcnt lgkmcnt(0)
	v_fmac_f32_e32 v49, v12, v50
	v_fmac_f32_e32 v49, v13, v51
	v_fmac_f32_e32 v49, v14, v52
	v_fmac_f32_e32 v49, v15, v53
	ds_read_b128 v[50:53], v21 offset:1504
	s_waitcnt lgkmcnt(0)
	v_fmac_f32_e32 v49, v7, v50
	v_fmac_f32_e32 v49, v8, v51
	v_fmac_f32_e32 v49, v9, v52
	v_fmac_f32_e32 v49, v10, v53
	ds_read_b128 v[50:53], v21 offset:1520
	s_waitcnt lgkmcnt(0)
	v_fmac_f32_e32 v49, v6, v50
	v_fmac_f32_e32 v49, v5, v51
	v_fmac_f32_e32 v49, v4, v52
	v_fmac_f32_e32 v49, v1, v53
	v_min_f32_e32 v50, 0, v49
	v_mul_f32_e64 v49, |v49|, s46
	v_exp_f32_e32 v49, v49
	ds_read_b128 v[52:55], v21 offset:1536
	v_add_f32_e32 v49, 1.0, v49
	v_cmp_gt_f32_e32 vcc, s47, v49
	s_nop 1
	v_cndmask_b32_e64 v51, 0, 32, vcc
	v_ldexp_f32 v49, v49, v51
	v_log_f32_e32 v49, v49
	s_nop 0
	v_mul_f32_e32 v51, 0x3f317217, v49
	v_fma_f32 v51, v49, s4, -v51
	v_fmac_f32_e32 v51, 0x3377d1cf, v49
	v_fmac_f32_e32 v51, 0x3f317217, v49
	v_cmp_lt_f32_e64 s[0:1], |v49|, s90
	s_nop 1
	v_cndmask_b32_e64 v49, v49, v51, s[0:1]
	v_cndmask_b32_e32 v51, 0, v203, vcc
	v_sub_f32_e32 v49, v49, v51
	v_sub_f32_e32 v49, v50, v49
	v_fmamk_f32 v50, v49, 0x3d800000, v48
	s_waitcnt lgkmcnt(0)
	v_fma_f32 v49, v16, v52, v11
	v_fmac_f32_e32 v49, v17, v53
	v_fmac_f32_e32 v49, v18, v54
	v_fmac_f32_e32 v49, v19, v55
	ds_read_b128 v[52:55], v21 offset:1552
	s_waitcnt lgkmcnt(0)
	v_fmac_f32_e32 v49, v12, v52
	v_fmac_f32_e32 v49, v13, v53
	v_fmac_f32_e32 v49, v14, v54
	v_fmac_f32_e32 v49, v15, v55
	ds_read_b128 v[52:55], v21 offset:1568
	s_waitcnt lgkmcnt(0)
	v_fmac_f32_e32 v49, v7, v52
	v_fmac_f32_e32 v49, v8, v53
	v_fmac_f32_e32 v49, v9, v54
	v_fmac_f32_e32 v49, v10, v55
	ds_read_b128 v[52:55], v21 offset:1584
	s_waitcnt lgkmcnt(0)
	v_fmac_f32_e32 v49, v6, v52
	v_fmac_f32_e32 v49, v5, v53
	v_fmac_f32_e32 v49, v4, v54
	v_fmac_f32_e32 v49, v1, v55
	v_min_f32_e32 v51, 0, v49
	v_mul_f32_e64 v49, |v49|, s46
	v_exp_f32_e32 v49, v49
	s_nop 0
	v_add_f32_e32 v49, 1.0, v49
	v_cmp_gt_f32_e32 vcc, s47, v49
	s_nop 1
	v_cndmask_b32_e64 v52, 0, 32, vcc
	v_ldexp_f32 v49, v49, v52
	v_log_f32_e32 v49, v49
	s_nop 0
	v_mul_f32_e32 v52, 0x3f317217, v49
	v_fma_f32 v52, v49, s4, -v52
	v_fmac_f32_e32 v52, 0x3377d1cf, v49
	v_fmac_f32_e32 v52, 0x3f317217, v49
	v_cmp_lt_f32_e64 s[0:1], |v49|, s90
	s_nop 1
	v_cndmask_b32_e64 v49, v49, v52, s[0:1]
	v_cndmask_b32_e32 v52, 0, v203, vcc
	v_sub_f32_e32 v49, v49, v52
	ds_read_b128 v[52:55], v21 offset:1600
	v_sub_f32_e32 v49, v51, v49
	v_fmamk_f32 v51, v49, 0x3d800000, v50
	s_waitcnt lgkmcnt(0)
	v_fma_f32 v49, v16, v52, v11
	v_fmac_f32_e32 v49, v17, v53
	v_fmac_f32_e32 v49, v18, v54
	v_fmac_f32_e32 v49, v19, v55
	ds_read_b128 v[52:55], v21 offset:1616
	s_waitcnt lgkmcnt(0)
	v_fmac_f32_e32 v49, v12, v52
	v_fmac_f32_e32 v49, v13, v53
	v_fmac_f32_e32 v49, v14, v54
	v_fmac_f32_e32 v49, v15, v55
	ds_read_b128 v[52:55], v21 offset:1632
	s_waitcnt lgkmcnt(0)
	v_fmac_f32_e32 v49, v7, v52
	v_fmac_f32_e32 v49, v8, v53
	v_fmac_f32_e32 v49, v9, v54
	v_fmac_f32_e32 v49, v10, v55
	ds_read_b128 v[52:55], v21 offset:1648
	s_waitcnt lgkmcnt(0)
; DI float log_sigmoid_fast(float x) { return fminf(x, 0.f) - __logf(1.0f + __expf(-fabsf(x))); }
; template <int MODE>
; DI void gla4_unit(const bf16_t* z, float* ST, float* DEC, bf16_t* Y, const float* aw_g, const float* ab_g, const float* ng, ldsp lds, int tid, int u) {
;     ...
;     {
;         float run = 0.f;
; #pragma unroll
;         for (int i = 0; i < 32; ++i) {
;             const int t = 32 * half + i;
;             float al = ab;
; #pragma unroll
;             for (int r = 0; r < 16; ++r) al += alr[t * 16 + r] * aw[r];
;             run += log_sigmoid_fast(al) * (1.0f / 16.0f);
;             bc[i] = run;
;         }
	v_fmac_f32_e32 v49, v6, v52
	v_fmac_f32_e32 v49, v5, v53
	v_fmac_f32_e32 v49, v4, v54
	v_fmac_f32_e32 v49, v1, v55
	v_min_f32_e32 v52, 0, v49
	v_mul_f32_e64 v49, |v49|, s46
	v_exp_f32_e32 v49, v49
	ds_read_b128 v[54:57], v21 offset:1664
	v_add_f32_e32 v49, 1.0, v49
	v_cmp_gt_f32_e32 vcc, s47, v49
	s_nop 1
	v_cndmask_b32_e64 v53, 0, 32, vcc
	v_ldexp_f32 v49, v49, v53
	v_log_f32_e32 v49, v49
	s_nop 0
	v_mul_f32_e32 v53, 0x3f317217, v49
	v_fma_f32 v53, v49, s4, -v53
	v_fmac_f32_e32 v53, 0x3377d1cf, v49
	v_fmac_f32_e32 v53, 0x3f317217, v49
	v_cmp_lt_f32_e64 s[0:1], |v49|, s90
	s_nop 1
	v_cndmask_b32_e64 v49, v49, v53, s[0:1]
	v_cndmask_b32_e32 v53, 0, v203, vcc
	v_sub_f32_e32 v49, v49, v53
	v_sub_f32_e32 v49, v52, v49
	v_fmamk_f32 v52, v49, 0x3d800000, v51
	s_waitcnt lgkmcnt(0)
	v_fma_f32 v49, v16, v54, v11
	v_fmac_f32_e32 v49, v17, v55
	v_fmac_f32_e32 v49, v18, v56
	v_fmac_f32_e32 v49, v19, v57
	ds_read_b128 v[54:57], v21 offset:1680
	s_waitcnt lgkmcnt(0)
	v_fmac_f32_e32 v49, v12, v54
	v_fmac_f32_e32 v49, v13, v55
	v_fmac_f32_e32 v49, v14, v56
	v_fmac_f32_e32 v49, v15, v57
	ds_read_b128 v[54:57], v21 offset:1696
	s_waitcnt lgkmcnt(0)
	v_fmac_f32_e32 v49, v7, v54
	v_fmac_f32_e32 v49, v8, v55
	v_fmac_f32_e32 v49, v9, v56
	v_fmac_f32_e32 v49, v10, v57
	ds_read_b128 v[54:57], v21 offset:1712
	s_waitcnt lgkmcnt(0)
	v_fmac_f32_e32 v49, v6, v54
	v_fmac_f32_e32 v49, v5, v55
	v_fmac_f32_e32 v49, v4, v56
	v_fmac_f32_e32 v49, v1, v57
	v_min_f32_e32 v53, 0, v49
	v_mul_f32_e64 v49, |v49|, s46
	v_exp_f32_e32 v49, v49
	s_nop 0
	v_add_f32_e32 v49, 1.0, v49
	v_cmp_gt_f32_e32 vcc, s47, v49
	s_nop 1
	v_cndmask_b32_e64 v54, 0, 32, vcc
	v_ldexp_f32 v49, v49, v54
	v_log_f32_e32 v49, v49
	s_nop 0
	v_mul_f32_e32 v54, 0x3f317217, v49
	v_fma_f32 v54, v49, s4, -v54
	v_fmac_f32_e32 v54, 0x3377d1cf, v49
	v_fmac_f32_e32 v54, 0x3f317217, v49
	v_cmp_lt_f32_e64 s[0:1], |v49|, s90
	s_nop 1
	v_cndmask_b32_e64 v49, v49, v54, s[0:1]
	v_cndmask_b32_e32 v54, 0, v203, vcc
	v_sub_f32_e32 v49, v49, v54
	ds_read_b128 v[54:57], v21 offset:1728
	v_sub_f32_e32 v49, v53, v49
	v_fmamk_f32 v53, v49, 0x3d800000, v52
	s_waitcnt lgkmcnt(0)
	v_fma_f32 v49, v16, v54, v11
	v_fmac_f32_e32 v49, v17, v55
	v_fmac_f32_e32 v49, v18, v56
	v_fmac_f32_e32 v49, v19, v57
	ds_read_b128 v[54:57], v21 offset:1744
	s_waitcnt lgkmcnt(0)
	v_fmac_f32_e32 v49, v12, v54
	v_fmac_f32_e32 v49, v13, v55
	v_fmac_f32_e32 v49, v14, v56
	v_fmac_f32_e32 v49, v15, v57
	ds_read_b128 v[54:57], v21 offset:1760
	s_waitcnt lgkmcnt(0)
	v_fmac_f32_e32 v49, v7, v54
	v_fmac_f32_e32 v49, v8, v55
	v_fmac_f32_e32 v49, v9, v56
	v_fmac_f32_e32 v49, v10, v57
	ds_read_b128 v[54:57], v21 offset:1776
	s_waitcnt lgkmcnt(0)
	v_fmac_f32_e32 v49, v6, v54
	v_fmac_f32_e32 v49, v5, v55
	v_fmac_f32_e32 v49, v4, v56
	v_fmac_f32_e32 v49, v1, v57
	v_min_f32_e32 v54, 0, v49
	v_mul_f32_e64 v49, |v49|, s46
	v_exp_f32_e32 v49, v49
	ds_read_b128 v[56:59], v21 offset:1792
	v_add_f32_e32 v49, 1.0, v49
	v_cmp_gt_f32_e32 vcc, s47, v49
	s_nop 1
	v_cndmask_b32_e64 v55, 0, 32, vcc
	v_ldexp_f32 v49, v49, v55
	v_log_f32_e32 v49, v49
	s_nop 0
	v_mul_f32_e32 v55, 0x3f317217, v49
	v_fma_f32 v55, v49, s4, -v55
	v_fmac_f32_e32 v55, 0x3377d1cf, v49
	v_fmac_f32_e32 v55, 0x3f317217, v49
	v_cmp_lt_f32_e64 s[0:1], |v49|, s90
	s_nop 1
	v_cndmask_b32_e64 v49, v49, v55, s[0:1]
	v_cndmask_b32_e32 v55, 0, v203, vcc
	v_sub_f32_e32 v49, v49, v55
	v_sub_f32_e32 v49, v54, v49
	v_fmamk_f32 v54, v49, 0x3d800000, v53
	s_waitcnt lgkmcnt(0)
	v_fma_f32 v49, v16, v56, v11
	v_fmac_f32_e32 v49, v17, v57
	v_fmac_f32_e32 v49, v18, v58
	v_fmac_f32_e32 v49, v19, v59
	ds_read_b128 v[56:59], v21 offset:1808
	s_waitcnt lgkmcnt(0)
	v_fmac_f32_e32 v49, v12, v56
	v_fmac_f32_e32 v49, v13, v57
	v_fmac_f32_e32 v49, v14, v58
	v_fmac_f32_e32 v49, v15, v59
	ds_read_b128 v[56:59], v21 offset:1824
	s_waitcnt lgkmcnt(0)
	v_fmac_f32_e32 v49, v7, v56
	v_fmac_f32_e32 v49, v8, v57
	v_fmac_f32_e32 v49, v9, v58
	v_fmac_f32_e32 v49, v10, v59
	ds_read_b128 v[56:59], v21 offset:1840
	s_waitcnt lgkmcnt(0)
	v_fmac_f32_e32 v49, v6, v56
	v_fmac_f32_e32 v49, v5, v57
	v_fmac_f32_e32 v49, v4, v58
	v_fmac_f32_e32 v49, v1, v59
	v_min_f32_e32 v55, 0, v49
	v_mul_f32_e64 v49, |v49|, s46
	v_exp_f32_e32 v49, v49
	s_nop 0
	v_add_f32_e32 v49, 1.0, v49
	v_cmp_gt_f32_e32 vcc, s47, v49
	s_nop 1
	v_cndmask_b32_e64 v56, 0, 32, vcc
	v_ldexp_f32 v49, v49, v56
	v_log_f32_e32 v49, v49
	s_nop 0
	v_mul_f32_e32 v56, 0x3f317217, v49
	v_fma_f32 v56, v49, s4, -v56
	v_fmac_f32_e32 v56, 0x3377d1cf, v49
	v_fmac_f32_e32 v56, 0x3f317217, v49
	v_cmp_lt_f32_e64 s[0:1], |v49|, s90
	s_nop 1
	v_cndmask_b32_e64 v49, v49, v56, s[0:1]
	v_cndmask_b32_e32 v56, 0, v203, vcc
	v_sub_f32_e32 v49, v49, v56
	ds_read_b128 v[56:59], v21 offset:1856
	v_sub_f32_e32 v49, v55, v49
	v_fmamk_f32 v55, v49, 0x3d800000, v54
	s_waitcnt lgkmcnt(0)
	v_fma_f32 v49, v16, v56, v11
	v_fmac_f32_e32 v49, v17, v57
	v_fmac_f32_e32 v49, v18, v58
	v_fmac_f32_e32 v49, v19, v59
	ds_read_b128 v[56:59], v21 offset:1872
	s_waitcnt lgkmcnt(0)
	v_fmac_f32_e32 v49, v12, v56
	v_fmac_f32_e32 v49, v13, v57
	v_fmac_f32_e32 v49, v14, v58
	v_fmac_f32_e32 v49, v15, v59
	ds_read_b128 v[56:59], v21 offset:1888
	s_waitcnt lgkmcnt(0)
	v_fmac_f32_e32 v49, v7, v56
	v_fmac_f32_e32 v49, v8, v57
	v_fmac_f32_e32 v49, v9, v58
	v_fmac_f32_e32 v49, v10, v59
	ds_read_b128 v[56:59], v21 offset:1904
	s_waitcnt lgkmcnt(0)
; #define LAS __attribute__((address_space(3)))
; #define LAS __attribute__((address_space(3)))
; DI float bf1(bf16_t v) { return __uint_as_float((unsigned)v << 16); }
; DI bf16_t f2bf(float f) { return (bf16_t)(pk(f, 0.f) & 0xffffu); }
; DI float log_sigmoid_fast(float x) { return fminf(x, 0.f) - __logf(1.0f + __expf(-fabsf(x))); }
; template <int MODE>
; DI void gla4_unit(const bf16_t* z, float* ST, float* DEC, bf16_t* Y, const float* aw_g, const float* ab_g, const float* ng, ldsp lds, int tid, int u) {
;     ...
;     {
;         float run = 0.f;
; #pragma unroll
;         for (int i = 0; i < 32; ++i) {
;             const int t = 32 * half + i;
;             float al = ab;
; #pragma unroll
;             for (int r = 0; r < 16; ++r) al += alr[t * 16 + r] * aw[r];
;             run += log_sigmoid_fast(al) * (1.0f / 16.0f);
;             bc[i] = run;
;         }
;         tot[half * 256 + hd * 64 + d] = run;
;     }
;     __syncthreads();
;     const float t0 = tot[hd * 64 + d], t1 = tot[256 + hd * 64 + d];
;     const float pre = half ? t0 : 0.f, blast = t0 + t1;
;     ...
;         for (int i = 0; i < 32; ++i) {
;             const float bb = bc[i] + pre;
;             LAS bf16_t* qp = (LAS bf16_t*)(hr + (32 * half + i) * 144 + d * 2); LAS bf16_t* kp = (LAS bf16_t*)(hr + G4_R1 + (32 * half + i) * 144 + d * 2);
;             *qp = f2bf(bf1(*qp) * 0.125f * __expf(bb)); *kp = f2bf(bf1(*kp) * __expf(-bb));
;         }
	v_fmac_f32_e32 v49, v6, v56
	v_fmac_f32_e32 v49, v5, v57
	v_fmac_f32_e32 v49, v4, v58
	v_fmac_f32_e32 v49, v1, v59
	v_min_f32_e32 v56, 0, v49
	v_mul_f32_e64 v49, |v49|, s46
	v_exp_f32_e32 v49, v49
	ds_read_b128 v[58:61], v21 offset:1920
	v_add_f32_e32 v49, 1.0, v49
	v_cmp_gt_f32_e32 vcc, s47, v49
	s_nop 1
	v_cndmask_b32_e64 v57, 0, 32, vcc
	v_ldexp_f32 v49, v49, v57
	v_log_f32_e32 v49, v49
	s_nop 0
	v_mul_f32_e32 v57, 0x3f317217, v49
	v_fma_f32 v57, v49, s4, -v57
	v_fmac_f32_e32 v57, 0x3377d1cf, v49
	v_fmac_f32_e32 v57, 0x3f317217, v49
	v_cmp_lt_f32_e64 s[0:1], |v49|, s90
	s_nop 1
	v_cndmask_b32_e64 v49, v49, v57, s[0:1]
	v_cndmask_b32_e32 v57, 0, v203, vcc
	v_sub_f32_e32 v49, v49, v57
	v_sub_f32_e32 v49, v56, v49
	v_fmamk_f32 v57, v49, 0x3d800000, v55
	s_waitcnt lgkmcnt(0)
	v_fma_f32 v49, v16, v58, v11
	v_fmac_f32_e32 v49, v17, v59
	v_fmac_f32_e32 v49, v18, v60
	v_fmac_f32_e32 v49, v19, v61
	ds_read_b128 v[58:61], v21 offset:1936
	s_waitcnt lgkmcnt(0)
	v_fmac_f32_e32 v49, v12, v58
	v_fmac_f32_e32 v49, v13, v59
	v_fmac_f32_e32 v49, v14, v60
	v_fmac_f32_e32 v49, v15, v61
	ds_read_b128 v[58:61], v21 offset:1952
	s_waitcnt lgkmcnt(0)
	v_fmac_f32_e32 v49, v7, v58
	v_fmac_f32_e32 v49, v8, v59
	v_fmac_f32_e32 v49, v9, v60
	v_fmac_f32_e32 v49, v10, v61
	ds_read_b128 v[58:61], v21 offset:1968
	s_waitcnt lgkmcnt(0)
	v_fmac_f32_e32 v49, v6, v58
	v_fmac_f32_e32 v49, v5, v59
	v_fmac_f32_e32 v49, v4, v60
	v_fmac_f32_e32 v49, v1, v61
	ds_read_b128 v[60:63], v21 offset:1984
	v_min_f32_e32 v56, 0, v49
	v_mul_f32_e64 v49, |v49|, s46
	v_exp_f32_e32 v49, v49
	s_waitcnt lgkmcnt(0)
	v_fmac_f32_e32 v11, v16, v60
	v_fmac_f32_e32 v11, v17, v61
	v_fmac_f32_e32 v11, v18, v62
	v_fmac_f32_e32 v11, v19, v63
	ds_read_b128 v[16:19], v21 offset:2000
	v_add_f32_e32 v49, 1.0, v49
	v_cmp_gt_f32_e32 vcc, s47, v49
	s_waitcnt lgkmcnt(0)
	v_fmac_f32_e32 v11, v12, v16
	v_fmac_f32_e32 v11, v13, v17
	v_fmac_f32_e32 v11, v14, v18
	v_fmac_f32_e32 v11, v15, v19
	ds_read_b128 v[12:15], v21 offset:2016
	v_cndmask_b32_e64 v58, 0, 32, vcc
	v_ldexp_f32 v49, v49, v58
	v_log_f32_e32 v49, v49
	s_waitcnt lgkmcnt(0)
	v_fmac_f32_e32 v11, v7, v12
	v_fmac_f32_e32 v11, v8, v13
	v_fmac_f32_e32 v11, v9, v14
	v_fmac_f32_e32 v11, v10, v15
	ds_read_b128 v[12:15], v21 offset:2032
	v_mul_f32_e32 v58, 0x3f317217, v49
	v_fma_f32 v58, v49, s4, -v58
	v_fmac_f32_e32 v58, 0x3377d1cf, v49
	v_fmac_f32_e32 v58, 0x3f317217, v49
	s_waitcnt lgkmcnt(0)
	v_fmac_f32_e32 v11, v6, v12
	v_fmac_f32_e32 v11, v5, v13
	v_fmac_f32_e32 v11, v4, v14
	v_fmac_f32_e32 v11, v1, v15
	v_mul_f32_e64 v4, |v11|, s46
	v_exp_f32_e32 v4, v4
	v_cmp_lt_f32_e64 s[0:1], |v49|, s90
	v_min_f32_e32 v1, 0, v11
	v_add_f32_e32 v4, 1.0, v4
	v_cndmask_b32_e64 v49, v49, v58, s[0:1]
	v_cndmask_b32_e32 v58, 0, v203, vcc
	v_cmp_gt_f32_e32 vcc, s47, v4
	v_sub_f32_e32 v49, v49, v58
	v_sub_f32_e32 v49, v56, v49
	v_cndmask_b32_e64 v5, 0, 32, vcc
	v_ldexp_f32 v4, v4, v5
	v_log_f32_e32 v4, v4
	v_fmamk_f32 v58, v49, 0x3d800000, v57
	v_add_u32_e32 v49, 0, v3
	v_lshlrev_b32_e32 v3, 2, v178
	v_mul_f32_e32 v5, 0x3f317217, v4
	v_fma_f32 v5, v4, s4, -v5
	v_fmac_f32_e32 v5, 0x3377d1cf, v4
	v_fmac_f32_e32 v5, 0x3f317217, v4
	v_cmp_lt_f32_e64 s[0:1], |v4|, s90
	v_lshlrev_b32_e32 v56, 5, v29
	s_nop 0
	v_cndmask_b32_e64 v4, v4, v5, s[0:1]
	v_cndmask_b32_e32 v5, 0, v203, vcc
	v_sub_f32_e32 v4, v4, v5
	v_sub_f32_e32 v1, v1, v4
	s_add_i32 s0, 0, 0x1c000
	v_fmamk_f32 v4, v1, 0x3d800000, v58
	v_lshl_add_u32 v1, v29, 10, s0
	v_add3_u32 v1, v1, v2, v3
	v_lshl_add_u32 v0, v0, 2, s0
	ds_write_b32 v1, v4
	s_waitcnt lgkmcnt(0)
	s_barrier
	ds_read_b32 v0, v0
	v_and_b32_e32 v1, 64, v80
	v_cmp_ne_u32_e32 vcc, 0, v1
	v_mul_u32_u24_e32 v1, 0x1200, v29
	s_waitcnt lgkmcnt(0)
	v_cndmask_b32_e32 v3, 0, v0, vcc
	v_lshlrev_b32_e32 v0, 1, v178
	v_add3_u32 v2, v49, v0, v1
	ds_read_u16 v6, v2
	v_add_f32_e32 v5, v20, v3
	v_mul_f32_e32 v7, 0x3fb8aa3b, v5
	v_exp_f32_e32 v7, v7
	v_mul_f32_e32 v5, 0xbfb8aa3b, v5
	s_waitcnt lgkmcnt(0)
	v_lshlrev_b32_e32 v6, 16, v6
	v_mul_f32_e32 v6, 0x3e000000, v6
	v_mul_f32_e32 v6, v7, v6
	v_cvt_pk_bf16_f32 v6, v6, v157
	ds_write_b16 v2, v6
	ds_read_u16 v6, v2 offset:9216
	v_exp_f32_e32 v5, v5
	s_waitcnt lgkmcnt(0)
	v_lshlrev_b32_e32 v6, 16, v6
	v_mul_f32_e32 v5, v5, v6
	v_cvt_pk_bf16_f32 v5, v5, v157
	ds_read_u16 v6, v2 offset:144
	ds_write_b16 v2, v5 offset:9216
	v_add_f32_e32 v5, v22, v3
	v_mul_f32_e32 v7, 0x3fb8aa3b, v5
	v_exp_f32_e32 v7, v7
	s_waitcnt lgkmcnt(1)
	v_lshlrev_b32_e32 v6, 16, v6
	v_mul_f32_e32 v6, 0x3e000000, v6
	v_mul_f32_e32 v5, 0xbfb8aa3b, v5
	v_mul_f32_e32 v6, v7, v6
	v_cvt_pk_bf16_f32 v6, v6, v157
	ds_write_b16 v2, v6 offset:144
	ds_read_u16 v6, v2 offset:9360
	v_exp_f32_e32 v5, v5
	s_waitcnt lgkmcnt(0)
	v_lshlrev_b32_e32 v6, 16, v6
	v_mul_f32_e32 v5, v5, v6
	v_cvt_pk_bf16_f32 v5, v5, v157
	ds_read_u16 v6, v2 offset:288
	ds_write_b16 v2, v5 offset:9360
	v_add_f32_e32 v5, v23, v3
	v_mul_f32_e32 v7, 0x3fb8aa3b, v5
	v_exp_f32_e32 v7, v7
	s_waitcnt lgkmcnt(1)
	v_lshlrev_b32_e32 v6, 16, v6
	v_mul_f32_e32 v6, 0x3e000000, v6
	v_mul_f32_e32 v5, 0xbfb8aa3b, v5
	v_mul_f32_e32 v6, v7, v6
	v_cvt_pk_bf16_f32 v6, v6, v157
	ds_write_b16 v2, v6 offset:288
	ds_read_u16 v6, v2 offset:9504
	v_exp_f32_e32 v5, v5
	s_waitcnt lgkmcnt(0)
	v_lshlrev_b32_e32 v6, 16, v6
	v_mul_f32_e32 v5, v5, v6
	v_cvt_pk_bf16_f32 v5, v5, v157
	ds_read_u16 v6, v2 offset:432
	ds_write_b16 v2, v5 offset:9504
	v_add_f32_e32 v5, v24, v3
	v_mul_f32_e32 v7, 0x3fb8aa3b, v5
	v_exp_f32_e32 v7, v7
	s_waitcnt lgkmcnt(1)
	v_lshlrev_b32_e32 v6, 16, v6
	v_mul_f32_e32 v6, 0x3e000000, v6
	v_mul_f32_e32 v5, 0xbfb8aa3b, v5
	v_mul_f32_e32 v6, v7, v6
	v_cvt_pk_bf16_f32 v6, v6, v157
	ds_write_b16 v2, v6 offset:432
	ds_read_u16 v6, v2 offset:9648
	v_exp_f32_e32 v5, v5
	s_waitcnt lgkmcnt(0)
; #define LAS __attribute__((address_space(3)))
; #define LAS __attribute__((address_space(3)))
; DI float bf1(bf16_t v) { return __uint_as_float((unsigned)v << 16); }
; DI bf16_t f2bf(float f) { return (bf16_t)(pk(f, 0.f) & 0xffffu); }
; template <int MODE>
; DI void gla4_unit(const bf16_t* z, float* ST, float* DEC, bf16_t* Y, const float* aw_g, const float* ab_g, const float* ng, ldsp lds, int tid, int u) {
;     ...
;         for (int i = 0; i < 32; ++i) {
;             const float bb = bc[i] + pre;
;             LAS bf16_t* qp = (LAS bf16_t*)(hr + (32 * half + i) * 144 + d * 2); LAS bf16_t* kp = (LAS bf16_t*)(hr + G4_R1 + (32 * half + i) * 144 + d * 2);
;             *qp = f2bf(bf1(*qp) * 0.125f * __expf(bb)); *kp = f2bf(bf1(*kp) * __expf(-bb));
;         }
	v_lshlrev_b32_e32 v6, 16, v6
	v_mul_f32_e32 v5, v5, v6
	v_cvt_pk_bf16_f32 v5, v5, v157
	ds_read_u16 v6, v2 offset:576
	ds_write_b16 v2, v5 offset:9648
	v_add_f32_e32 v5, v25, v3
	v_mul_f32_e32 v7, 0x3fb8aa3b, v5
	v_exp_f32_e32 v7, v7
	s_waitcnt lgkmcnt(1)
	v_lshlrev_b32_e32 v6, 16, v6
	v_mul_f32_e32 v6, 0x3e000000, v6
	v_mul_f32_e32 v5, 0xbfb8aa3b, v5
	v_mul_f32_e32 v6, v7, v6
	v_cvt_pk_bf16_f32 v6, v6, v157
	ds_write_b16 v2, v6 offset:576
	ds_read_u16 v6, v2 offset:9792
	v_exp_f32_e32 v5, v5
	s_waitcnt lgkmcnt(0)
	v_lshlrev_b32_e32 v6, 16, v6
	v_mul_f32_e32 v5, v5, v6
	v_cvt_pk_bf16_f32 v5, v5, v157
	ds_read_u16 v6, v2 offset:720
	ds_write_b16 v2, v5 offset:9792
	v_add_f32_e32 v5, v26, v3
	v_mul_f32_e32 v7, 0x3fb8aa3b, v5
	v_exp_f32_e32 v7, v7
	s_waitcnt lgkmcnt(1)
	v_lshlrev_b32_e32 v6, 16, v6
	v_mul_f32_e32 v6, 0x3e000000, v6
	v_mul_f32_e32 v5, 0xbfb8aa3b, v5
	v_mul_f32_e32 v6, v7, v6
	v_cvt_pk_bf16_f32 v6, v6, v157
	ds_write_b16 v2, v6 offset:720
	ds_read_u16 v6, v2 offset:9936
	v_exp_f32_e32 v5, v5
	s_waitcnt lgkmcnt(0)
	v_lshlrev_b32_e32 v6, 16, v6
	v_mul_f32_e32 v5, v5, v6
	v_cvt_pk_bf16_f32 v5, v5, v157
	ds_read_u16 v6, v2 offset:864
	ds_write_b16 v2, v5 offset:9936
	v_add_f32_e32 v5, v27, v3
	v_mul_f32_e32 v7, 0x3fb8aa3b, v5
	v_exp_f32_e32 v7, v7
	s_waitcnt lgkmcnt(1)
	v_lshlrev_b32_e32 v6, 16, v6
	v_mul_f32_e32 v6, 0x3e000000, v6
	v_mul_f32_e32 v5, 0xbfb8aa3b, v5
	v_mul_f32_e32 v6, v7, v6
	v_cvt_pk_bf16_f32 v6, v6, v157
	ds_write_b16 v2, v6 offset:864
	ds_read_u16 v6, v2 offset:10080
	v_exp_f32_e32 v5, v5
	s_waitcnt lgkmcnt(0)
	v_lshlrev_b32_e32 v6, 16, v6
	v_mul_f32_e32 v5, v5, v6
	v_cvt_pk_bf16_f32 v5, v5, v157
	ds_read_u16 v6, v2 offset:1008
	ds_write_b16 v2, v5 offset:10080
	v_add_f32_e32 v5, v30, v3
	v_mul_f32_e32 v7, 0x3fb8aa3b, v5
	v_exp_f32_e32 v7, v7
	s_waitcnt lgkmcnt(1)
	v_lshlrev_b32_e32 v6, 16, v6
	v_mul_f32_e32 v6, 0x3e000000, v6
	v_mul_f32_e32 v5, 0xbfb8aa3b, v5
	v_mul_f32_e32 v6, v7, v6
	v_cvt_pk_bf16_f32 v6, v6, v157
	ds_write_b16 v2, v6 offset:1008
	ds_read_u16 v6, v2 offset:10224
	v_exp_f32_e32 v5, v5
	v_add3_u32 v30, v49, v1, v0
	s_waitcnt lgkmcnt(0)
	v_lshlrev_b32_e32 v6, 16, v6
	v_mul_f32_e32 v5, v5, v6
	v_cvt_pk_bf16_f32 v5, v5, v157
	ds_read_u16 v6, v2 offset:1152
	ds_write_b16 v2, v5 offset:10224
	v_add_f32_e32 v5, v31, v3
	v_mul_f32_e32 v7, 0x3fb8aa3b, v5
	v_exp_f32_e32 v7, v7
	s_waitcnt lgkmcnt(1)
	v_lshlrev_b32_e32 v6, 16, v6
	v_mul_f32_e32 v6, 0x3e000000, v6
	v_mul_f32_e32 v5, 0xbfb8aa3b, v5
	v_mul_f32_e32 v6, v7, v6
	v_cvt_pk_bf16_f32 v6, v6, v157
	ds_write_b16 v2, v6 offset:1152
	ds_read_u16 v6, v2 offset:10368
	v_exp_f32_e32 v5, v5
	s_waitcnt lgkmcnt(0)
	v_lshlrev_b32_e32 v6, 16, v6
	v_mul_f32_e32 v5, v5, v6
	v_cvt_pk_bf16_f32 v5, v5, v157
	ds_read_u16 v6, v2 offset:1296
	ds_write_b16 v2, v5 offset:10368
	v_add_f32_e32 v5, v35, v3
	v_mul_f32_e32 v7, 0x3fb8aa3b, v5
	v_exp_f32_e32 v7, v7
	s_waitcnt lgkmcnt(1)
	v_lshlrev_b32_e32 v6, 16, v6
	v_mul_f32_e32 v6, 0x3e000000, v6
	v_mul_f32_e32 v5, 0xbfb8aa3b, v5
	v_mul_f32_e32 v6, v7, v6
	v_cvt_pk_bf16_f32 v6, v6, v157
	ds_write_b16 v2, v6 offset:1296
	ds_read_u16 v6, v2 offset:10512
	v_exp_f32_e32 v5, v5
	v_mad_u32_u24 v35, v81, s89, v202
	s_waitcnt lgkmcnt(0)
	v_lshlrev_b32_e32 v6, 16, v6
	v_mul_f32_e32 v5, v5, v6
	v_cvt_pk_bf16_f32 v5, v5, v157
	ds_read_u16 v6, v2 offset:1440
	ds_write_b16 v2, v5 offset:10512
	v_add_f32_e32 v5, v36, v3
	v_mul_f32_e32 v7, 0x3fb8aa3b, v5
	v_exp_f32_e32 v7, v7
	s_waitcnt lgkmcnt(1)
	v_lshlrev_b32_e32 v6, 16, v6
	v_mul_f32_e32 v6, 0x3e000000, v6
	v_mul_f32_e32 v5, 0xbfb8aa3b, v5
	v_mul_f32_e32 v6, v7, v6
	v_cvt_pk_bf16_f32 v6, v6, v157
	ds_write_b16 v2, v6 offset:1440
	ds_read_u16 v6, v2 offset:10656
	v_exp_f32_e32 v5, v5
	v_mad_u32_u24 v36, v81, s89, v204
	s_waitcnt lgkmcnt(0)
	v_lshlrev_b32_e32 v6, 16, v6
	v_mul_f32_e32 v5, v5, v6
	v_cvt_pk_bf16_f32 v5, v5, v157
	ds_read_u16 v6, v2 offset:1584
	ds_write_b16 v2, v5 offset:10656
	v_add_f32_e32 v5, v37, v3
	v_mul_f32_e32 v7, 0x3fb8aa3b, v5
	v_exp_f32_e32 v7, v7
	s_waitcnt lgkmcnt(1)
	v_lshlrev_b32_e32 v6, 16, v6
	v_mul_f32_e32 v6, 0x3e000000, v6
	v_mul_f32_e32 v5, 0xbfb8aa3b, v5
	v_mul_f32_e32 v6, v7, v6
	v_cvt_pk_bf16_f32 v6, v6, v157
	ds_write_b16 v2, v6 offset:1584
	ds_read_u16 v6, v2 offset:10800
	v_exp_f32_e32 v5, v5
	v_mad_u32_u24 v37, v81, s89, v205
	s_waitcnt lgkmcnt(0)
	v_lshlrev_b32_e32 v6, 16, v6
	v_mul_f32_e32 v5, v5, v6
	v_cvt_pk_bf16_f32 v5, v5, v157
	ds_read_u16 v6, v2 offset:1728
	ds_write_b16 v2, v5 offset:10800
	v_add_f32_e32 v5, v38, v3
	v_mul_f32_e32 v7, 0x3fb8aa3b, v5
	v_exp_f32_e32 v7, v7
	s_waitcnt lgkmcnt(1)
	v_lshlrev_b32_e32 v6, 16, v6
	v_mul_f32_e32 v6, 0x3e000000, v6
	v_mul_f32_e32 v5, 0xbfb8aa3b, v5
	v_mul_f32_e32 v6, v7, v6
	v_cvt_pk_bf16_f32 v6, v6, v157
	ds_write_b16 v2, v6 offset:1728
	ds_read_u16 v6, v2 offset:10944
	v_exp_f32_e32 v5, v5
	v_or_b32_e32 v38, v56, v81
	s_waitcnt lgkmcnt(0)
	v_lshlrev_b32_e32 v6, 16, v6
	v_mul_f32_e32 v5, v5, v6
	v_cvt_pk_bf16_f32 v5, v5, v157
	ds_read_u16 v6, v2 offset:1872
	ds_write_b16 v2, v5 offset:10944
	v_add_f32_e32 v5, v39, v3
	v_mul_f32_e32 v7, 0x3fb8aa3b, v5
	v_exp_f32_e32 v7, v7
	s_waitcnt lgkmcnt(1)
	v_lshlrev_b32_e32 v6, 16, v6
	v_mul_f32_e32 v6, 0x3e000000, v6
	v_mul_f32_e32 v5, 0xbfb8aa3b, v5
	v_mul_f32_e32 v6, v7, v6
	v_cvt_pk_bf16_f32 v6, v6, v157
	ds_write_b16 v2, v6 offset:1872
	ds_read_u16 v6, v2 offset:11088
	v_exp_f32_e32 v5, v5
	s_waitcnt lgkmcnt(0)
	v_lshlrev_b32_e32 v6, 16, v6
	v_mul_f32_e32 v5, v5, v6
	v_cvt_pk_bf16_f32 v5, v5, v157
	ds_read_u16 v6, v2 offset:2016
	ds_write_b16 v2, v5 offset:11088
	v_add_f32_e32 v5, v40, v3
	v_mul_f32_e32 v7, 0x3fb8aa3b, v5
	v_exp_f32_e32 v7, v7
	s_waitcnt lgkmcnt(1)
; #define LAS __attribute__((address_space(3)))
; #define LAS __attribute__((address_space(3)))
; DI float bf1(bf16_t v) { return __uint_as_float((unsigned)v << 16); }
; DI bf16_t f2bf(float f) { return (bf16_t)(pk(f, 0.f) & 0xffffu); }
; template <int MODE>
; DI void gla4_unit(const bf16_t* z, float* ST, float* DEC, bf16_t* Y, const float* aw_g, const float* ab_g, const float* ng, ldsp lds, int tid, int u) {
;     ...
;         for (int i = 0; i < 32; ++i) {
;             const float bb = bc[i] + pre;
;             LAS bf16_t* qp = (LAS bf16_t*)(hr + (32 * half + i) * 144 + d * 2); LAS bf16_t* kp = (LAS bf16_t*)(hr + G4_R1 + (32 * half + i) * 144 + d * 2);
;             *qp = f2bf(bf1(*qp) * 0.125f * __expf(bb)); *kp = f2bf(bf1(*kp) * __expf(-bb));
;         }
	v_lshlrev_b32_e32 v6, 16, v6
	v_mul_f32_e32 v6, 0x3e000000, v6
	v_mul_f32_e32 v5, 0xbfb8aa3b, v5
	v_mul_f32_e32 v6, v7, v6
	v_cvt_pk_bf16_f32 v6, v6, v157
	ds_write_b16 v2, v6 offset:2016
	ds_read_u16 v6, v2 offset:11232
	v_exp_f32_e32 v5, v5
	s_waitcnt lgkmcnt(0)
	v_lshlrev_b32_e32 v6, 16, v6
	v_mul_f32_e32 v5, v5, v6
	v_cvt_pk_bf16_f32 v5, v5, v157
	ds_read_u16 v6, v2 offset:2160
	ds_write_b16 v2, v5 offset:11232
	v_add_f32_e32 v5, v41, v3
	v_mul_f32_e32 v7, 0x3fb8aa3b, v5
	v_exp_f32_e32 v7, v7
	s_waitcnt lgkmcnt(1)
	v_lshlrev_b32_e32 v6, 16, v6
	v_mul_f32_e32 v6, 0x3e000000, v6
	v_mul_f32_e32 v5, 0xbfb8aa3b, v5
	v_mul_f32_e32 v6, v7, v6
	v_cvt_pk_bf16_f32 v6, v6, v157
	ds_write_b16 v2, v6 offset:2160
	ds_read_u16 v6, v2 offset:11376
	v_exp_f32_e32 v5, v5
	s_waitcnt lgkmcnt(0)
	v_lshlrev_b32_e32 v6, 16, v6
	v_mul_f32_e32 v5, v5, v6
	v_cvt_pk_bf16_f32 v5, v5, v157
	ds_read_u16 v6, v2 offset:2304
	ds_write_b16 v2, v5 offset:11376
	v_add_f32_e32 v5, v42, v3
	v_mul_f32_e32 v7, 0x3fb8aa3b, v5
	v_exp_f32_e32 v7, v7
	s_waitcnt lgkmcnt(1)
	v_lshlrev_b32_e32 v6, 16, v6
	v_mul_f32_e32 v6, 0x3e000000, v6
	v_mul_f32_e32 v5, 0xbfb8aa3b, v5
	v_mul_f32_e32 v6, v7, v6
	v_cvt_pk_bf16_f32 v6, v6, v157
	ds_write_b16 v2, v6 offset:2304
	ds_read_u16 v6, v2 offset:11520
	v_exp_f32_e32 v5, v5
	s_waitcnt lgkmcnt(0)
	v_lshlrev_b32_e32 v6, 16, v6
	v_mul_f32_e32 v5, v5, v6
	v_cvt_pk_bf16_f32 v5, v5, v157
	ds_read_u16 v6, v2 offset:2448
	ds_write_b16 v2, v5 offset:11520
	v_add_f32_e32 v5, v43, v3
	v_mul_f32_e32 v7, 0x3fb8aa3b, v5
	v_exp_f32_e32 v7, v7
	s_waitcnt lgkmcnt(1)
	v_lshlrev_b32_e32 v6, 16, v6
	v_mul_f32_e32 v6, 0x3e000000, v6
	v_mul_f32_e32 v5, 0xbfb8aa3b, v5
	v_mul_f32_e32 v6, v7, v6
	v_cvt_pk_bf16_f32 v6, v6, v157
	ds_write_b16 v2, v6 offset:2448
	ds_read_u16 v6, v2 offset:11664
	v_exp_f32_e32 v5, v5
	s_waitcnt lgkmcnt(0)
	v_lshlrev_b32_e32 v6, 16, v6
	v_mul_f32_e32 v5, v5, v6
	v_cvt_pk_bf16_f32 v5, v5, v157
	ds_read_u16 v6, v2 offset:2592
	ds_write_b16 v2, v5 offset:11664
	v_add_f32_e32 v5, v44, v3
	v_mul_f32_e32 v7, 0x3fb8aa3b, v5
	v_exp_f32_e32 v7, v7
	s_waitcnt lgkmcnt(1)
	v_lshlrev_b32_e32 v6, 16, v6
	v_mul_f32_e32 v6, 0x3e000000, v6
	v_mul_f32_e32 v5, 0xbfb8aa3b, v5
	v_mul_f32_e32 v6, v7, v6
	v_cvt_pk_bf16_f32 v6, v6, v157
	ds_write_b16 v2, v6 offset:2592
	ds_read_u16 v6, v2 offset:11808
	v_exp_f32_e32 v5, v5
	s_waitcnt lgkmcnt(0)
	v_lshlrev_b32_e32 v6, 16, v6
	v_mul_f32_e32 v5, v5, v6
	v_cvt_pk_bf16_f32 v5, v5, v157
	ds_read_u16 v6, v2 offset:2736
	ds_write_b16 v2, v5 offset:11808
	v_add_f32_e32 v5, v45, v3
	v_mul_f32_e32 v7, 0x3fb8aa3b, v5
	v_exp_f32_e32 v7, v7
	s_waitcnt lgkmcnt(1)
	v_lshlrev_b32_e32 v6, 16, v6
	v_mul_f32_e32 v6, 0x3e000000, v6
	v_mul_f32_e32 v5, 0xbfb8aa3b, v5
	v_mul_f32_e32 v6, v7, v6
	v_cvt_pk_bf16_f32 v6, v6, v157
	ds_write_b16 v2, v6 offset:2736
	ds_read_u16 v6, v2 offset:11952
	v_exp_f32_e32 v5, v5
	s_waitcnt lgkmcnt(0)
	v_lshlrev_b32_e32 v6, 16, v6
	v_mul_f32_e32 v5, v5, v6
	v_cvt_pk_bf16_f32 v5, v5, v157
	ds_read_u16 v6, v2 offset:2880
	ds_write_b16 v2, v5 offset:11952
	v_add_f32_e32 v5, v46, v3
	v_mul_f32_e32 v7, 0x3fb8aa3b, v5
	v_exp_f32_e32 v7, v7
	s_waitcnt lgkmcnt(1)
	v_lshlrev_b32_e32 v6, 16, v6
	v_mul_f32_e32 v6, 0x3e000000, v6
	v_mul_f32_e32 v5, 0xbfb8aa3b, v5
	v_mul_f32_e32 v6, v7, v6
	v_cvt_pk_bf16_f32 v6, v6, v157
	ds_write_b16 v2, v6 offset:2880
	ds_read_u16 v6, v2 offset:12096
	v_exp_f32_e32 v5, v5
	s_waitcnt lgkmcnt(0)
	v_lshlrev_b32_e32 v6, 16, v6
	v_mul_f32_e32 v5, v5, v6
	v_cvt_pk_bf16_f32 v5, v5, v157
	ds_read_u16 v6, v2 offset:3024
	ds_write_b16 v2, v5 offset:12096
	v_add_f32_e32 v5, v47, v3
	v_mul_f32_e32 v7, 0x3fb8aa3b, v5
	v_exp_f32_e32 v7, v7
	s_waitcnt lgkmcnt(1)
	v_lshlrev_b32_e32 v6, 16, v6
	v_mul_f32_e32 v6, 0x3e000000, v6
	v_mul_f32_e32 v5, 0xbfb8aa3b, v5
	v_mul_f32_e32 v6, v7, v6
	v_cvt_pk_bf16_f32 v6, v6, v157
	ds_write_b16 v2, v6 offset:3024
	ds_read_u16 v6, v2 offset:12240
	v_exp_f32_e32 v5, v5
	s_waitcnt lgkmcnt(0)
	v_lshlrev_b32_e32 v6, 16, v6
	v_mul_f32_e32 v5, v5, v6
	v_cvt_pk_bf16_f32 v5, v5, v157
	ds_read_u16 v6, v2 offset:3168
	ds_write_b16 v2, v5 offset:12240
	v_add_f32_e32 v5, v48, v3
	v_mul_f32_e32 v7, 0x3fb8aa3b, v5
	v_exp_f32_e32 v7, v7
	s_waitcnt lgkmcnt(1)
	v_lshlrev_b32_e32 v6, 16, v6
	v_mul_f32_e32 v6, 0x3e000000, v6
	v_mul_f32_e32 v5, 0xbfb8aa3b, v5
	v_mul_f32_e32 v6, v7, v6
	v_cvt_pk_bf16_f32 v6, v6, v157
	ds_write_b16 v2, v6 offset:3168
	ds_read_u16 v6, v2 offset:12384
	v_exp_f32_e32 v5, v5
	v_or_b32_e32 v48, 16, v81
	s_waitcnt lgkmcnt(0)
	v_lshlrev_b32_e32 v6, 16, v6
	v_mul_f32_e32 v5, v5, v6
	v_cvt_pk_bf16_f32 v5, v5, v157
	ds_read_u16 v6, v2 offset:3312
	ds_write_b16 v2, v5 offset:12384
	v_add_f32_e32 v5, v50, v3
	v_mul_f32_e32 v7, 0x3fb8aa3b, v5
	v_exp_f32_e32 v7, v7
	s_waitcnt lgkmcnt(1)
	v_lshlrev_b32_e32 v6, 16, v6
	v_mul_f32_e32 v6, 0x3e000000, v6
	v_mul_f32_e32 v5, 0xbfb8aa3b, v5
	v_mul_f32_e32 v6, v7, v6
	v_cvt_pk_bf16_f32 v6, v6, v157
	ds_write_b16 v2, v6 offset:3312
	ds_read_u16 v6, v2 offset:12528
	v_exp_f32_e32 v5, v5
	s_waitcnt lgkmcnt(0)
	v_lshlrev_b32_e32 v6, 16, v6
	v_mul_f32_e32 v5, v5, v6
	v_cvt_pk_bf16_f32 v5, v5, v157
	ds_read_u16 v6, v2 offset:3456
	ds_write_b16 v2, v5 offset:12528
	v_add_f32_e32 v5, v51, v3
	v_mul_f32_e32 v7, 0x3fb8aa3b, v5
	v_exp_f32_e32 v7, v7
	s_waitcnt lgkmcnt(1)
	v_lshlrev_b32_e32 v6, 16, v6
	v_mul_f32_e32 v6, 0x3e000000, v6
	v_mul_f32_e32 v5, 0xbfb8aa3b, v5
	v_mul_f32_e32 v6, v7, v6
	v_cvt_pk_bf16_f32 v6, v6, v157
	ds_write_b16 v2, v6 offset:3456
	ds_read_u16 v6, v2 offset:12672
	v_exp_f32_e32 v5, v5
	s_waitcnt lgkmcnt(0)
; #define LAS __attribute__((address_space(3)))
; #define LAS __attribute__((address_space(3)))
; DI float bf1(bf16_t v) { return __uint_as_float((unsigned)v << 16); }
; DI bf16_t f2bf(float f) { return (bf16_t)(pk(f, 0.f) & 0xffffu); }
; #define MFMA16(a, b, c) __builtin_amdgcn_mfma_f32_16x16x32_bf16((a), (b), (c), 0, 0, 0)
; template <int MODE>
; DI void gla4_unit(const bf16_t* z, float* ST, float* DEC, bf16_t* Y, const float* aw_g, const float* ab_g, const float* ng, ldsp lds, int tid, int u) {
;     ...
;         for (int i = 0; i < 32; ++i) {
;             const float bb = bc[i] + pre;
;             LAS bf16_t* qp = (LAS bf16_t*)(hr + (32 * half + i) * 144 + d * 2); LAS bf16_t* kp = (LAS bf16_t*)(hr + G4_R1 + (32 * half + i) * 144 + d * 2);
;             *qp = f2bf(bf1(*qp) * 0.125f * __expf(bb)); *kp = f2bf(bf1(*kp) * __expf(-bb));
;         }
;         __syncthreads();
;         f32x4 acc[2][4];
; #pragma unroll
;         for (int rt = 0; rt < 2; ++rt)
; #pragma unroll
;             for (int nt = 0; nt < 4; ++nt) acc[rt][nt] = (f32x4){0.f, 0.f, 0.f, 0.f};
; #pragma unroll
;         for (int ks = 0; ks < 2; ++ks) {
;             bf16x8 af[2], bfm[4];
; #pragma unroll
;             for (int rt = 0; rt < 2; ++rt) af[rt] = *(LAS bf16x8*)(hr + (32 * half + 16 * rt + fr) * 144 + (32 * ks + 8 * fq) * 2);
; #pragma unroll
;             for (int nt = 0; nt < 4; ++nt) bfm[nt] = *(LAS bf16x8*)(hr + G4_R1 + (16 * nt + fr) * 144 + (32 * ks + 8 * fq) * 2);
; #pragma unroll
;             for (int rt = 0; rt < 2; ++rt)
; #pragma unroll
;                 for (int nt = 0; nt < 4; ++nt) acc[rt][nt] = MFMA16(af[rt], bfm[nt], acc[rt][nt]);
;         }
;         unsigned vw[16];
; #pragma unroll
;         for (int k = 0; k < 16; ++k) {
;             const unsigned lo = *(LAS bf16_t*)(hr + G4_R2 + (32 * half + 2 * k) * 144 + d * 2), hi = *(LAS bf16_t*)(hr + G4_R2 + (32 * half + 2 * k + 1) * 144 + d * 2);
;             vw[k] = lo | (hi << 16);
;         }
	v_lshlrev_b32_e32 v6, 16, v6
	v_mul_f32_e32 v5, v5, v6
	v_cvt_pk_bf16_f32 v5, v5, v157
	ds_read_u16 v6, v2 offset:3600
	ds_write_b16 v2, v5 offset:12672
	v_add_f32_e32 v5, v52, v3
	v_mul_f32_e32 v7, 0x3fb8aa3b, v5
	v_exp_f32_e32 v7, v7
	s_waitcnt lgkmcnt(1)
	v_lshlrev_b32_e32 v6, 16, v6
	v_mul_f32_e32 v6, 0x3e000000, v6
	v_mul_f32_e32 v5, 0xbfb8aa3b, v5
	v_mul_f32_e32 v6, v7, v6
	v_cvt_pk_bf16_f32 v6, v6, v157
	ds_write_b16 v2, v6 offset:3600
	ds_read_u16 v6, v2 offset:12816
	v_exp_f32_e32 v5, v5
	s_waitcnt lgkmcnt(0)
	v_lshlrev_b32_e32 v6, 16, v6
	v_mul_f32_e32 v5, v5, v6
	v_cvt_pk_bf16_f32 v5, v5, v157
	ds_read_u16 v6, v2 offset:3744
	ds_write_b16 v2, v5 offset:12816
	v_add_f32_e32 v5, v53, v3
	v_mul_f32_e32 v7, 0x3fb8aa3b, v5
	v_exp_f32_e32 v7, v7
	s_waitcnt lgkmcnt(1)
	v_lshlrev_b32_e32 v6, 16, v6
	v_mul_f32_e32 v6, 0x3e000000, v6
	v_mul_f32_e32 v5, 0xbfb8aa3b, v5
	v_mul_f32_e32 v6, v7, v6
	v_cvt_pk_bf16_f32 v6, v6, v157
	ds_write_b16 v2, v6 offset:3744
	ds_read_u16 v6, v2 offset:12960
	v_exp_f32_e32 v5, v5
	s_waitcnt lgkmcnt(0)
	v_lshlrev_b32_e32 v6, 16, v6
	v_mul_f32_e32 v5, v5, v6
	v_cvt_pk_bf16_f32 v5, v5, v157
	ds_read_u16 v6, v2 offset:3888
	ds_write_b16 v2, v5 offset:12960
	v_add_f32_e32 v5, v54, v3
	v_mul_f32_e32 v7, 0x3fb8aa3b, v5
	v_exp_f32_e32 v7, v7
	s_waitcnt lgkmcnt(1)
	v_lshlrev_b32_e32 v6, 16, v6
	v_mul_f32_e32 v6, 0x3e000000, v6
	v_mul_f32_e32 v5, 0xbfb8aa3b, v5
	v_mul_f32_e32 v6, v7, v6
	v_cvt_pk_bf16_f32 v6, v6, v157
	ds_write_b16 v2, v6 offset:3888
	ds_read_u16 v6, v2 offset:13104
	v_exp_f32_e32 v5, v5
	v_or_b32_e32 v54, 32, v81
	s_waitcnt lgkmcnt(0)
	v_lshlrev_b32_e32 v6, 16, v6
	v_mul_f32_e32 v5, v5, v6
	v_cvt_pk_bf16_f32 v5, v5, v157
	ds_read_u16 v6, v2 offset:4032
	ds_write_b16 v2, v5 offset:13104
	v_add_f32_e32 v5, v55, v3
	v_mul_f32_e32 v7, 0x3fb8aa3b, v5
	v_exp_f32_e32 v7, v7
	s_waitcnt lgkmcnt(1)
	v_lshlrev_b32_e32 v6, 16, v6
	v_mul_f32_e32 v6, 0x3e000000, v6
	v_mul_f32_e32 v5, 0xbfb8aa3b, v5
	v_mul_f32_e32 v6, v7, v6
	v_cvt_pk_bf16_f32 v6, v6, v157
	ds_write_b16 v2, v6 offset:4032
	ds_read_u16 v6, v2 offset:13248
	v_exp_f32_e32 v5, v5
	v_or_b32_e32 v55, 48, v81
	s_waitcnt lgkmcnt(0)
	v_lshlrev_b32_e32 v6, 16, v6
	v_mul_f32_e32 v5, v5, v6
	v_cvt_pk_bf16_f32 v5, v5, v157
	ds_read_u16 v6, v2 offset:4176
	ds_write_b16 v2, v5 offset:13248
	v_add_f32_e32 v5, v57, v3
	v_mul_f32_e32 v7, 0x3fb8aa3b, v5
	v_exp_f32_e32 v7, v7
	s_waitcnt lgkmcnt(1)
	v_lshlrev_b32_e32 v6, 16, v6
	v_mul_f32_e32 v6, 0x3e000000, v6
	v_mul_f32_e32 v5, 0xbfb8aa3b, v5
	v_mul_f32_e32 v6, v7, v6
	v_cvt_pk_bf16_f32 v6, v6, v157
	ds_write_b16 v2, v6 offset:4176
	ds_read_u16 v6, v2 offset:13392
	v_exp_f32_e32 v5, v5
	s_waitcnt lgkmcnt(0)
	v_lshlrev_b32_e32 v6, 16, v6
	v_mul_f32_e32 v5, v5, v6
	v_cvt_pk_bf16_f32 v5, v5, v157
	ds_read_u16 v6, v2 offset:4320
	ds_write_b16 v2, v5 offset:13392
	v_add_f32_e32 v5, v58, v3
	v_mul_f32_e32 v7, 0x3fb8aa3b, v5
	v_exp_f32_e32 v7, v7
	s_waitcnt lgkmcnt(1)
	v_lshlrev_b32_e32 v6, 16, v6
	v_mul_f32_e32 v6, 0x3e000000, v6
	v_mul_f32_e32 v5, 0xbfb8aa3b, v5
	v_mul_f32_e32 v6, v7, v6
	v_cvt_pk_bf16_f32 v6, v6, v157
	ds_write_b16 v2, v6 offset:4320
	ds_read_u16 v6, v2 offset:13536
	v_exp_f32_e32 v5, v5
	v_add_f32_e32 v3, v3, v4
	s_waitcnt lgkmcnt(0)
	v_lshlrev_b32_e32 v6, 16, v6
	v_mul_f32_e32 v5, v5, v6
	v_cvt_pk_bf16_f32 v5, v5, v157
	ds_read_u16 v4, v2 offset:4464
	ds_write_b16 v2, v5 offset:13536
	v_mul_f32_e32 v5, 0x3fb8aa3b, v3
	v_exp_f32_e32 v5, v5
	v_mul_f32_e32 v3, 0xbfb8aa3b, v3
	s_waitcnt lgkmcnt(1)
	v_lshlrev_b32_e32 v4, 16, v4
	v_mul_f32_e32 v4, 0x3e000000, v4
	v_mul_f32_e32 v4, v5, v4
	v_cvt_pk_bf16_f32 v4, v4, v157
	ds_write_b16 v2, v4 offset:4464
	ds_read_u16 v4, v2 offset:13680
	v_exp_f32_e32 v3, v3
	s_waitcnt lgkmcnt(0)
	v_lshlrev_b32_e32 v4, 16, v4
	v_mul_f32_e32 v3, v3, v4
	v_cvt_pk_bf16_f32 v3, v3, v157
	ds_write_b16 v2, v3 offset:13680
	v_and_b32_e32 v2, 48, v80
	v_add_u32_e32 v39, v49, v2
	v_mad_u32_u24 v31, v38, s89, v39
	v_mad_u32_u24 v40, v81, s89, v39
	v_add_u32_e32 v41, v39, v35
	v_add_u32_e32 v42, v39, v36
	v_add_u32_e32 v43, v39, v37
	s_waitcnt lgkmcnt(0)
	s_barrier
	ds_read_b128 v[2:5], v31
	ds_read_b128 v[6:9], v31 offset:2304
	ds_read_b128 v[10:13], v40 offset:9216
	ds_read_b128 v[14:17], v41 offset:9216
	ds_read_b128 v[18:21], v42 offset:9216
	ds_read_b128 v[22:25], v43 offset:9216
	s_waitcnt lgkmcnt(3)
	v_mfma_f32_16x16x32_bf16 v[44:47], v[2:5], v[10:13], 0
	s_waitcnt lgkmcnt(2)
	v_mfma_f32_16x16x32_bf16 v[50:53], v[2:5], v[14:17], 0
	s_waitcnt lgkmcnt(1)
	v_mfma_f32_16x16x32_bf16 v[2:5], v[2:5], v[18:21], 0
	v_mfma_f32_16x16x32_bf16 v[10:13], v[6:9], v[10:13], 0
	v_mfma_f32_16x16x32_bf16 v[14:17], v[6:9], v[14:17], 0
	v_mfma_f32_16x16x32_bf16 v[58:61], v[6:9], v[18:21], 0
	s_waitcnt lgkmcnt(0)
	v_mfma_f32_16x16x32_bf16 v[24:27], v[6:9], v[22:25], 0
	ds_read_b128 v[6:9], v31 offset:64
	ds_read_b128 v[62:65], v31 offset:2368
	ds_read_b128 v[18:21], v40 offset:9280
	ds_read_b128 v[66:69], v41 offset:9280
	ds_read_b128 v[70:73], v42 offset:9280
	ds_read_b128 v[74:77], v43 offset:9280
	ds_read_u16 v0, v30 offset:18432
	ds_read_u16 v1, v30 offset:18576
	s_waitcnt lgkmcnt(0)
	v_lshl_or_b32 v0, v1, 16, v0
	v_mfma_f32_16x16x32_bf16 v[82:85], v[6:9], v[70:73], v[2:5]
	ds_read_u16 v1, v30 offset:18720
	s_nop 1
	ds_read_u16 v2, v30 offset:18864
	s_waitcnt lgkmcnt(0)
	v_lshl_or_b32 v1, v2, 16, v1
	ds_read_u16 v2, v30 offset:19008
	ds_read_u16 v3, v30 offset:19152
	v_mfma_f32_16x16x32_bf16 v[44:47], v[6:9], v[18:21], v[44:47]
	s_waitcnt lgkmcnt(0)
	v_lshl_or_b32 v2, v3, 16, v2
	v_mfma_f32_16x16x32_bf16 v[20:23], v[62:65], v[18:21], v[10:13]
	v_mfma_f32_16x16x32_bf16 v[12:15], v[62:65], v[66:69], v[14:17]
	ds_read_u16 v3, v30 offset:19296
	s_nop 1
	ds_read_u16 v16, v30 offset:19440
	s_waitcnt lgkmcnt(0)
; #define LAS __attribute__((address_space(3)))
; #define LAS __attribute__((address_space(3)))
; DI bf16_t f2bf(float f) { return (bf16_t)(pk(f, 0.f) & 0xffffu); }
; template <int MODE>
; DI void gla4_unit(const bf16_t* z, float* ST, float* DEC, bf16_t* Y, const float* aw_g, const float* ab_g, const float* ng, ldsp lds, int tid, int u) {
;     ...
;         unsigned vw[16];
; #pragma unroll
;         for (int k = 0; k < 16; ++k) {
;             const unsigned lo = *(LAS bf16_t*)(hr + G4_R2 + (32 * half + 2 * k) * 144 + d * 2), hi = *(LAS bf16_t*)(hr + G4_R2 + (32 * half + 2 * k + 1) * 144 + d * 2);
;             vw[k] = lo | (hi << 16);
;         }
;         __syncthreads();
; #pragma unroll
;         for (int rt = 0; rt < 2; ++rt)
; #pragma unroll
;             for (int nt = 0; nt < 4; ++nt)
; #pragma unroll
;                 for (int r = 0; r < 4; ++r) {
;                     const int t = 32 * half + 16 * rt + 4 * fq + r, sx = 16 * nt + fr;
;                     *(LAS bf16_t*)(hr + G4_R1 + t * 144 + sx * 2) = f2bf(sx <= t ? acc[rt][nt][r] : 0.f);
;                 }
	v_lshl_or_b32 v3, v16, 16, v3
	ds_read_u16 v16, v30 offset:19584
	ds_read_u16 v17, v30 offset:19728
	v_mfma_f32_16x16x32_bf16 v[50:53], v[6:9], v[66:69], v[50:53]
	s_waitcnt lgkmcnt(0)
	v_lshl_or_b32 v16, v17, 16, v16
	ds_read_u16 v17, v30 offset:19872
	ds_read_u16 v18, v30 offset:20016
	v_mfma_f32_16x16x32_bf16 v[4:7], v[62:65], v[74:77], v[24:27]
	s_waitcnt lgkmcnt(0)
	v_lshl_or_b32 v17, v18, 16, v17
	ds_read_u16 v18, v30 offset:20160
	ds_read_u16 v19, v30 offset:20304
	v_mfma_f32_16x16x32_bf16 v[8:11], v[62:65], v[70:73], v[58:61]
	s_waitcnt lgkmcnt(0)
	v_lshl_or_b32 v18, v19, 16, v18
	ds_read_u16 v19, v30 offset:20448
	ds_read_u16 v24, v30 offset:20592
	s_waitcnt lgkmcnt(0)
	v_lshl_or_b32 v19, v24, 16, v19
	ds_read_u16 v24, v30 offset:20736
	ds_read_u16 v25, v30 offset:20880
	s_waitcnt lgkmcnt(0)
	v_lshl_or_b32 v24, v25, 16, v24
	ds_read_u16 v25, v30 offset:21024
	ds_read_u16 v26, v30 offset:21168
	s_waitcnt lgkmcnt(0)
	v_lshl_or_b32 v25, v26, 16, v25
	ds_read_u16 v26, v30 offset:21312
	ds_read_u16 v27, v30 offset:21456
	s_waitcnt lgkmcnt(0)
	v_lshl_or_b32 v26, v27, 16, v26
	ds_read_u16 v27, v30 offset:21600
	ds_read_u16 v57, v30 offset:21744
	s_waitcnt lgkmcnt(0)
	v_lshl_or_b32 v27, v57, 16, v27
	ds_read_u16 v57, v30 offset:21888
	ds_read_u16 v58, v30 offset:22032
	s_waitcnt lgkmcnt(0)
	v_lshl_or_b32 v58, v58, 16, v57
	ds_read_u16 v57, v30 offset:22176
	ds_read_u16 v59, v30 offset:22320
	s_waitcnt lgkmcnt(0)
	v_lshl_or_b32 v59, v59, 16, v57
	ds_read_u16 v57, v30 offset:22464
	ds_read_u16 v60, v30 offset:22608
	s_waitcnt lgkmcnt(0)
	v_lshl_or_b32 v60, v60, 16, v57
	ds_read_u16 v57, v30 offset:22752
	ds_read_u16 v30, v30 offset:22896
	s_waitcnt lgkmcnt(0)
	s_barrier
	v_lshl_or_b32 v61, v30, 16, v57
	v_lshl_or_b32 v30, v177, 2, v56
	v_cmp_gt_u32_e32 vcc, v81, v30
	v_lshl_add_u32 v56, v81, 1, v49
	v_mad_u32_u24 v57, v30, s89, v56
	v_cndmask_b32_e64 v44, v44, 0, vcc
	v_cvt_pk_bf16_f32 v44, v44, v157
	ds_write_b16 v57, v44 offset:9216
	v_or_b32_e32 v44, 1, v30
	v_cmp_le_u32_e64 s[0:1], v81, v44
	v_mad_u32_u24 v57, v30, s89, s89
	v_add_u32_e32 v62, v56, v57
	v_cndmask_b32_e64 v45, 0, v45, s[0:1]
	v_cvt_pk_bf16_f32 v45, v45, v157
	ds_write_b16 v62, v45 offset:9216
	v_or_b32_e32 v45, 2, v30
	v_cmp_le_u32_e64 s[0:1], v81, v45
	v_mad_u32_u24 v62, v30, s89, v206
	v_add_u32_e32 v63, v56, v62
	v_cndmask_b32_e64 v46, 0, v46, s[0:1]
	v_cvt_pk_bf16_f32 v46, v46, v157
	ds_write_b16 v63, v46 offset:9216
	v_or_b32_e32 v46, 3, v30
	v_cmp_le_u32_e64 s[0:1], v81, v46
	v_mad_u32_u24 v63, v30, s89, v207
	v_add_u32_e32 v64, v56, v63
	v_cndmask_b32_e64 v47, 0, v47, s[0:1]
	v_cvt_pk_bf16_f32 v47, v47, v157
	v_cmp_le_u32_e64 s[0:1], v48, v30
	ds_write_b16 v64, v47 offset:9216
	v_lshl_add_u32 v47, v48, 1, v49
	v_cndmask_b32_e64 v50, 0, v50, s[0:1]
	v_cvt_pk_bf16_f32 v50, v50, v157
	v_mad_u32_u24 v64, v30, s89, v47
	v_cmp_le_u32_e64 s[0:1], v48, v44
	ds_write_b16 v64, v50 offset:9216
	v_cndmask_b32_e64 v12, v12, 0, vcc
	v_cndmask_b32_e64 v50, 0, v51, s[0:1]
	v_cvt_pk_bf16_f32 v50, v50, v157
	v_add_u32_e32 v51, v47, v57
	v_cmp_le_u32_e64 s[0:1], v48, v45
	ds_write_b16 v51, v50 offset:9216
	v_add_u32_e32 v51, v47, v62
	v_cndmask_b32_e64 v50, 0, v52, s[0:1]
	v_cvt_pk_bf16_f32 v50, v50, v157
	v_cmp_le_u32_e64 s[0:1], v48, v46
	ds_write_b16 v51, v50 offset:9216
	v_add_u32_e32 v51, v47, v63
	v_cndmask_b32_e64 v50, 0, v53, s[0:1]
	v_cvt_pk_bf16_f32 v50, v50, v157
	v_cmp_le_u32_e64 s[0:1], v54, v30
	ds_write_b16 v51, v50 offset:9216
	v_lshl_add_u32 v50, v54, 1, v49
	v_cndmask_b32_e64 v51, 0, v82, s[0:1]
	v_cmp_le_u32_e64 s[0:1], v54, v44
	v_cvt_pk_bf16_f32 v51, v51, v157
	v_mad_u32_u24 v52, v30, s89, v50
	ds_write_b16 v52, v51 offset:9216
	v_cndmask_b32_e64 v44, 0, v83, s[0:1]
	v_cvt_pk_bf16_f32 v44, v44, v157
	v_add_u32_e32 v51, v50, v57
	v_cmp_le_u32_e64 s[0:1], v54, v45
	ds_write_b16 v51, v44 offset:9216
	v_add_u32_e32 v45, v50, v62
	v_cndmask_b32_e64 v44, 0, v84, s[0:1]
	v_cvt_pk_bf16_f32 v44, v44, v157
	v_cmp_le_u32_e64 s[0:1], v54, v46
	ds_write_b16 v45, v44 offset:9216
	v_add_u32_e32 v45, v50, v63
	v_cndmask_b32_e64 v44, 0, v85, s[0:1]
	v_cvt_pk_bf16_f32 v44, v44, v157
	ds_write_b16 v45, v44 offset:9216
	v_lshl_add_u32 v44, v55, 1, v49
	v_mad_u32_u24 v46, v30, s89, v44
	v_cvt_pk_bf16_f32 v45, v157, v157
	ds_write_b16 v46, v45 offset:9216
	v_add_u32_e32 v46, v44, v57
	v_cvt_pk_bf16_f32 v45, v157, v157
	ds_write_b16 v46, v45 offset:9216
	v_add_u32_e32 v46, v44, v62
	v_cvt_pk_bf16_f32 v45, v157, v157
	ds_write_b16 v46, v45 offset:9216
	v_add_u32_e32 v46, v44, v63
	v_cvt_pk_bf16_f32 v45, v157, v157
	ds_write_b16 v46, v45 offset:9216
	v_mad_u32_u24 v46, v30, s89, v202
	v_add_u32_e32 v51, v56, v46
	v_cvt_pk_bf16_f32 v20, v20, v157
	ds_write_b16 v51, v20 offset:9216
	v_mad_u32_u24 v51, v30, s89, v208
	v_add_u32_e32 v52, v56, v51
	v_cvt_pk_bf16_f32 v21, v21, v157
	ds_write_b16 v52, v21 offset:9216
	v_mad_u32_u24 v52, v30, s89, v209
	v_add_u32_e32 v53, v56, v52
	v_cvt_pk_bf16_f32 v22, v22, v157
	ds_write_b16 v53, v22 offset:9216
	v_mad_u32_u24 v53, v30, s89, v210
	v_or_b32_e32 v20, 17, v30
	v_cvt_pk_bf16_f32 v23, v23, v157
	v_add_u32_e32 v56, v56, v53
	ds_write_b16 v56, v23 offset:9216
	v_cvt_pk_bf16_f32 v12, v12, v157
	v_add_u32_e32 v23, v47, v46
	v_cmp_le_u32_e32 vcc, v48, v20
	v_or_b32_e32 v21, 18, v30
	ds_write_b16 v23, v12 offset:9216
	v_cndmask_b32_e32 v12, 0, v13, vcc
	v_cvt_pk_bf16_f32 v12, v12, v157
	v_add_u32_e32 v13, v47, v51
	v_cmp_le_u32_e32 vcc, v48, v21
	v_or_b32_e32 v22, 19, v30
	ds_write_b16 v13, v12 offset:9216
	v_cndmask_b32_e32 v12, 0, v14, vcc
	v_or_b32_e32 v45, 16, v30
	v_cvt_pk_bf16_f32 v12, v12, v157
	v_add_u32_e32 v13, v47, v52
; #define LAS __attribute__((address_space(3)))
; #define LAS __attribute__((address_space(3)))
; DI unsigned pk(float lo, float hi) { return pg8::cvt_pk_bf16(lo, hi); }
; DI bf16_t f2bf(float f) { return (bf16_t)(pk(f, 0.f) & 0xffffu); }
; #define MFMA16(a, b, c) __builtin_amdgcn_mfma_f32_16x16x32_bf16((a), (b), (c), 0, 0, 0)
; template <int MODE>
; DI void gla4_unit(const bf16_t* z, float* ST, float* DEC, bf16_t* Y, const float* aw_g, const float* ab_g, const float* ng, ldsp lds, int tid, int u) {
;     ...
;                     *(LAS bf16_t*)(hr + G4_R1 + t * 144 + sx * 2) = f2bf(sx <= t ? acc[rt][nt][r] : 0.f);
;                 }
; #pragma unroll
;         for (int j = 0; j < 4; ++j) { u32x4 o; o.x = vw[4 * j]; o.y = vw[4 * j + 1]; o.z = vw[4 * j + 2]; o.w = vw[4 * j + 3]; *(LAS u32x4*)(hr + G4_R2 + d * 144 + (32 * half + 8 * j) * 2) = o; }
;         __syncthreads();
; #pragma unroll
;         for (int rt = 0; rt < 2; ++rt)
; #pragma unroll
;             for (int nt = 0; nt < 4; ++nt) acc[rt][nt] = (f32x4){0.f, 0.f, 0.f, 0.f};
;         const float* sp = ST + (size_t)(p * 128 + c) * 4096;
; #pragma unroll
;         for (int ks = 0; ks < 4; ++ks) {
;             bf16x8 af[2], bfm[4];
;             const int kk = (ks & 1) * 32 + 8 * fq;
; #pragma unroll
;             for (int rt = 0; rt < 2; ++rt) af[rt] = *(LAS bf16x8*)(hr + (ks < 2 ? G4_R1 : 0) + (32 * half + 16 * rt + fr) * 144 + kk * 2);
; #pragma unroll
;             for (int nt = 0; nt < 4; ++nt) {
;                 if (ks < 2) bfm[nt] = *(LAS bf16x8*)(hr + G4_R2 + (16 * nt + fr) * 144 + kk * 2);
;                 else { const f32x4 s0 = *(const f32x4*)(sp + (16 * nt + fr) * 64 + kk), s1 = *(const f32x4*)(sp + (16 * nt + fr) * 64 + kk + 4);
;                        u32x4 o; o.x = pk(s0[0], s0[1]); o.y = pk(s0[2], s0[3]); o.z = pk(s1[0], s1[1]); o.w = pk(s1[2], s1[3]); bfm[nt] = __builtin_bit_cast(bf16x8, o); }
;             }
; #pragma unroll
;             for (int rt = 0; rt < 2; ++rt)
; #pragma unroll
;                 for (int nt = 0; nt < 4; ++nt) acc[rt][nt] = MFMA16(af[rt], bfm[nt], acc[rt][nt]);
;         }
	v_cmp_le_u32_e32 vcc, v48, v22
	ds_write_b16 v13, v12 offset:9216
	v_add_u32_e32 v13, v47, v53
	v_cndmask_b32_e32 v12, 0, v15, vcc
	v_cmp_le_u32_e32 vcc, v54, v45
	v_cvt_pk_bf16_f32 v12, v12, v157
	ds_write_b16 v13, v12 offset:9216
	v_add_u32_e32 v12, v50, v46
	v_cndmask_b32_e32 v8, 0, v8, vcc
	v_cvt_pk_bf16_f32 v8, v8, v157
	v_cmp_le_u32_e32 vcc, v54, v20
	ds_write_b16 v12, v8 offset:9216
	s_and_b32 s0, s30, 0x7f
	v_cndmask_b32_e32 v8, 0, v9, vcc
	v_cvt_pk_bf16_f32 v8, v8, v157
	v_add_u32_e32 v9, v50, v51
	v_cmp_le_u32_e32 vcc, v54, v21
	ds_write_b16 v9, v8 offset:9216
	v_add_u32_e32 v9, v50, v52
	v_cndmask_b32_e32 v8, 0, v10, vcc
	v_cvt_pk_bf16_f32 v8, v8, v157
	v_cmp_le_u32_e32 vcc, v54, v22
	ds_write_b16 v9, v8 offset:9216
	v_add_u32_e32 v9, v50, v53
	v_cndmask_b32_e32 v8, 0, v11, vcc
	v_cmp_le_u32_e32 vcc, v55, v45
	v_cvt_pk_bf16_f32 v8, v8, v157
	ds_write_b16 v9, v8 offset:9216
	v_add_u32_e32 v8, v44, v46
	v_cndmask_b32_e32 v4, 0, v4, vcc
	v_cvt_pk_bf16_f32 v4, v4, v157
	v_cmp_le_u32_e32 vcc, v55, v20
	ds_write_b16 v8, v4 offset:9216
	s_nop 0
	v_cndmask_b32_e32 v4, 0, v5, vcc
	v_cvt_pk_bf16_f32 v4, v4, v157
	v_add_u32_e32 v5, v44, v51
	v_cmp_le_u32_e32 vcc, v55, v21
	ds_write_b16 v5, v4 offset:9216
	v_add_u32_e32 v5, v44, v52
	v_cndmask_b32_e32 v4, 0, v6, vcc
	v_cvt_pk_bf16_f32 v4, v4, v157
	v_cmp_le_u32_e32 vcc, v55, v22
	ds_write_b16 v5, v4 offset:9216
	v_add_u32_e32 v5, v44, v53
	v_cndmask_b32_e32 v4, 0, v7, vcc
	v_cvt_pk_bf16_f32 v4, v4, v157
	ds_write_b16 v5, v4 offset:9216
	v_mul_u32_u24_e32 v4, 0x90, v178
	v_lshlrev_b32_e32 v5, 6, v29
	v_add3_u32 v4, v49, v4, v5
	ds_write_b128 v4, v[0:3] offset:18432
	ds_write_b128 v4, v[16:19] offset:18448
	ds_write_b128 v4, v[24:27] offset:18464
	ds_write_b128 v4, v[58:61] offset:18480
	v_lshl_or_b32 v0, v28, 7, s0
	v_ashrrev_i32_e32 v1, 31, v0
	v_lshlrev_b64 v[0:1], 14, v[0:1]
	v_lshl_add_u64 v[8:9], s[68:69], 0, v[0:1]
	s_waitcnt lgkmcnt(0)
	s_barrier
	ds_read_b128 v[0:3], v31 offset:9216
	ds_read_b128 v[4:7], v31 offset:11520
	v_lshl_add_u64 v[74:75], v[8:9], 0, v[156:157]
	ds_read_b128 v[8:11], v40 offset:18432
	ds_read_b128 v[12:15], v41 offset:18432
	ds_read_b128 v[16:19], v42 offset:18432
	ds_read_b128 v[20:23], v43 offset:18432
	v_add_u32_e32 v28, 64, v39
	s_waitcnt lgkmcnt(3)
	v_mfma_f32_16x16x32_bf16 v[24:27], v[0:3], v[8:11], 0
	v_mad_u32_u24 v48, v38, s89, v28
	ds_read_b128 v[54:57], v48 offset:9216
	ds_read_b128 v[58:61], v48 offset:11520
	v_lshlrev_b32_e32 v156, 8, v81
	s_waitcnt lgkmcnt(4)
	v_mfma_f32_16x16x32_bf16 v[40:43], v[0:3], v[12:15], 0
	s_mov_b64 s[0:1], 0x1000
	s_waitcnt lgkmcnt(3)
	v_mfma_f32_16x16x32_bf16 v[44:47], v[0:3], v[16:19], 0
	s_waitcnt lgkmcnt(2)
	v_mfma_f32_16x16x32_bf16 v[50:53], v[0:3], v[20:23], 0
	v_mad_u32_u24 v0, v81, s89, v28
	ds_read_b128 v[62:65], v0 offset:18432
	v_add_u32_e32 v0, v28, v35
	ds_read_b128 v[66:69], v0 offset:18432
	v_add_u32_e32 v0, v28, v36
	v_add_u32_e32 v28, v28, v37
	v_mfma_f32_16x16x32_bf16 v[8:11], v[4:7], v[8:11], 0
	v_bfe_u32 v35, v80, 1, 6
	v_mfma_f32_16x16x32_bf16 v[12:15], v[4:7], v[12:15], 0
	v_mfma_f32_16x16x32_bf16 v[16:19], v[4:7], v[16:19], 0
	v_mfma_f32_16x16x32_bf16 v[20:23], v[4:7], v[20:23], 0
	ds_read_b128 v[70:73], v0 offset:18432
	ds_read_b128 v[4:7], v31
	ds_read_b128 v[0:3], v31 offset:2304
	ds_read_b128 v[36:39], v28 offset:18432
	s_waitcnt lgkmcnt(0)
	v_mfma_f32_16x16x32_bf16 v[50:53], v[54:57], v[36:39], v[50:53]
	v_mfma_f32_16x16x32_bf16 v[36:39], v[58:61], v[36:39], v[20:23]
	s_nop 2
	v_lshl_add_u64 v[20:21], v[74:75], 0, v[156:157]
	v_mfma_f32_16x16x32_bf16 v[26:29], v[54:57], v[62:65], v[24:27]
	v_or_b32_e32 v156, s29, v35
	v_mfma_f32_16x16x32_bf16 v[40:43], v[54:57], v[66:69], v[40:43]
	v_mfma_f32_16x16x32_bf16 v[44:47], v[54:57], v[70:73], v[44:47]
	global_load_dwordx4 v[22:25], v[20:21], off offset:16
	global_load_dwordx4 v[54:57], v[20:21], off
	s_waitcnt vmcnt(0)
	v_cvt_pk_bf16_f32 v54, v54, v55
	v_cvt_pk_bf16_f32 v55, v56, v57
	v_cvt_pk_bf16_f32 v56, v22, v23
	v_cvt_pk_bf16_f32 v57, v24, v25
	v_add_co_u32_e32 v24, vcc, s33, v20
	v_mfma_f32_16x16x32_bf16 v[8:11], v[58:61], v[62:65], v[8:11]
	s_nop 0
	v_addc_co_u32_e32 v25, vcc, 0, v21, vcc
	v_add_co_u32_e32 v22, vcc, s88, v20
	v_lshl_add_u64 v[62:63], v[20:21], 0, s[0:1]
	s_nop 0
	v_addc_co_u32_e32 v23, vcc, 0, v21, vcc
	v_mfma_f32_16x16x32_bf16 v[12:15], v[58:61], v[66:69], v[12:15]
	v_lshl_add_u64 v[66:67], v[20:21], 0, s[22:23]
	s_mov_b64 s[0:1], 0x3000
	v_add_co_u32_e32 v74, vcc, s99, v20
	v_mfma_f32_16x16x32_bf16 v[16:19], v[58:61], v[70:73], v[16:19]
	global_load_dwordx4 v[58:61], v[22:23], off offset:-4096
	s_nop 0
	global_load_dwordx4 v[62:65], v[62:63], off offset:16
	s_waitcnt vmcnt(1)
	v_cvt_pk_bf16_f32 v58, v58, v59
	v_cvt_pk_bf16_f32 v59, v60, v61
	s_waitcnt vmcnt(0)
	v_cvt_pk_bf16_f32 v60, v62, v63
	v_cvt_pk_bf16_f32 v61, v64, v65
	global_load_dwordx4 v[62:65], v[22:23], off
	s_nop 0
	global_load_dwordx4 v[66:69], v[66:67], off offset:16
	v_lshl_add_u64 v[70:71], v[20:21], 0, s[0:1]
	v_addc_co_u32_e32 v75, vcc, 0, v21, vcc
	s_waitcnt vmcnt(1)
	v_cvt_pk_bf16_f32 v62, v62, v63
	v_cvt_pk_bf16_f32 v63, v64, v65
	s_waitcnt vmcnt(0)
	v_cvt_pk_bf16_f32 v64, v66, v67
	v_cvt_pk_bf16_f32 v65, v68, v69
	global_load_dwordx4 v[66:69], v[74:75], off
	s_nop 0
	global_load_dwordx4 v[70:73], v[70:71], off offset:16
	s_waitcnt vmcnt(1)
	v_cvt_pk_bf16_f32 v66, v66, v67
	v_cvt_pk_bf16_f32 v67, v68, v69
	s_waitcnt vmcnt(0)
; #define LAS __attribute__((address_space(3)))
; #define LAS __attribute__((address_space(3)))
; DI unsigned pk(float lo, float hi) { return pg8::cvt_pk_bf16(lo, hi); }
; #define MFMA16(a, b, c) __builtin_amdgcn_mfma_f32_16x16x32_bf16((a), (b), (c), 0, 0, 0)
; template <int MODE>
; DI void gla4_unit(const bf16_t* z, float* ST, float* DEC, bf16_t* Y, const float* aw_g, const float* ab_g, const float* ng, ldsp lds, int tid, int u) {
;     ...
;         for (int ks = 0; ks < 4; ++ks) {
;             bf16x8 af[2], bfm[4];
;             const int kk = (ks & 1) * 32 + 8 * fq;
; #pragma unroll
;             for (int rt = 0; rt < 2; ++rt) af[rt] = *(LAS bf16x8*)(hr + (ks < 2 ? G4_R1 : 0) + (32 * half + 16 * rt + fr) * 144 + kk * 2);
; #pragma unroll
;             for (int nt = 0; nt < 4; ++nt) {
;                 if (ks < 2) bfm[nt] = *(LAS bf16x8*)(hr + G4_R2 + (16 * nt + fr) * 144 + kk * 2);
;                 else { const f32x4 s0 = *(const f32x4*)(sp + (16 * nt + fr) * 64 + kk), s1 = *(const f32x4*)(sp + (16 * nt + fr) * 64 + kk + 4);
;                        u32x4 o; o.x = pk(s0[0], s0[1]); o.y = pk(s0[2], s0[3]); o.z = pk(s1[0], s1[1]); o.w = pk(s1[2], s1[3]); bfm[nt] = __builtin_bit_cast(bf16x8, o); }
;             }
; #pragma unroll
;             for (int rt = 0; rt < 2; ++rt)
; #pragma unroll
;                 for (int nt = 0; nt < 4; ++nt) acc[rt][nt] = MFMA16(af[rt], bfm[nt], acc[rt][nt]);
;         }
;         __syncthreads();
; #pragma unroll
;         for (int rt = 0; rt < 2; ++rt)
; #pragma unroll
;             for (int nt = 0; nt < 4; ++nt)
; #pragma unroll
;                 for (int r = 0; r < 4; ++r) *(LAS float*)(hr + (32 * half + 16 * rt + 4 * fq + r) * 272 + (16 * nt + fr) * 4) = acc[rt][nt][r];
;         __syncthreads();
;         {
;             const int t7 = tid & 127, t = t7 >> 1, e0 = (t7 & 1) * 32;
;             f32x4 o[8]; float ss = 0.f;
; #pragma unroll
;             for (int k = 0; k < 8; ++k) { o[k] = *(LAS f32x4*)(hr + t * 272 + (e0 + 4 * k) * 4); ss += (o[k][0] * o[k][0] + o[k][1] * o[k][1]) + (o[k][2] * o[k][2] + o[k][3] * o[k][3]); }
	v_cvt_pk_bf16_f32 v68, v70, v71
	v_cvt_pk_bf16_f32 v69, v72, v73
	v_mfma_f32_16x16x32_bf16 v[26:29], v[4:7], v[54:57], v[26:29]
	s_mov_b64 s[0:1], 0x1080
	v_mfma_f32_16x16x32_bf16 v[40:43], v[4:7], v[58:61], v[40:43]
	v_mfma_f32_16x16x32_bf16 v[44:47], v[4:7], v[62:65], v[44:47]
	v_mfma_f32_16x16x32_bf16 v[4:7], v[4:7], v[66:69], v[50:53]
	v_mfma_f32_16x16x32_bf16 v[8:11], v[0:3], v[54:57], v[8:11]
	v_mfma_f32_16x16x32_bf16 v[12:15], v[0:3], v[58:61], v[12:15]
	v_mfma_f32_16x16x32_bf16 v[16:19], v[0:3], v[62:65], v[16:19]
	v_lshl_add_u64 v[62:63], v[20:21], 0, s[0:1]
	s_mov_b64 s[0:1], 0x2080
	v_mfma_f32_16x16x32_bf16 v[0:3], v[0:3], v[66:69], v[36:39]
	s_nop 2
	ds_read_b128 v[36:39], v48
	ds_read_b128 v[50:53], v48 offset:2304
	global_load_dwordx4 v[54:57], v[20:21], off offset:144
	global_load_dwordx4 v[58:61], v[20:21], off offset:128
	s_waitcnt vmcnt(0)
	v_cvt_pk_bf16_f32 v58, v58, v59
	v_cvt_pk_bf16_f32 v59, v60, v61
	v_cvt_pk_bf16_f32 v60, v54, v55
	v_cvt_pk_bf16_f32 v61, v56, v57
	global_load_dwordx4 v[54:57], v[24:25], off offset:128
	s_nop 0
	global_load_dwordx4 v[62:65], v[62:63], off offset:16
	s_waitcnt vmcnt(1)
	v_cvt_pk_bf16_f32 v54, v54, v55
	v_cvt_pk_bf16_f32 v55, v56, v57
	s_waitcnt vmcnt(0)
	v_cvt_pk_bf16_f32 v56, v62, v63
	v_lshl_add_u64 v[62:63], v[20:21], 0, s[0:1]
	v_cvt_pk_bf16_f32 v57, v64, v65
	global_load_dwordx4 v[22:25], v[22:23], off offset:128
	s_nop 0
	global_load_dwordx4 v[62:65], v[62:63], off offset:16
	s_mov_b64 s[0:1], 0x3080
	s_waitcnt vmcnt(1)
	v_cvt_pk_bf16_f32 v22, v22, v23
	v_cvt_pk_bf16_f32 v23, v24, v25
	s_waitcnt vmcnt(0)
	v_cvt_pk_bf16_f32 v24, v62, v63
	v_cvt_pk_bf16_f32 v25, v64, v65
	v_lshl_add_u64 v[20:21], v[20:21], 0, s[0:1]
	global_load_dwordx4 v[62:65], v[74:75], off offset:128
	global_load_dwordx4 v[66:69], v[20:21], off offset:16
	s_waitcnt lgkmcnt(1)
	v_mfma_f32_16x16x32_bf16 v[26:29], v[36:39], v[58:61], v[26:29]
	s_waitcnt vmcnt(1)
	v_cvt_pk_bf16_f32 v62, v62, v63
	v_mfma_f32_16x16x32_bf16 v[40:43], v[36:39], v[54:57], v[40:43]
	v_cvt_pk_bf16_f32 v63, v64, v65
	s_waitcnt vmcnt(0)
	v_cvt_pk_bf16_f32 v64, v66, v67
	v_cvt_pk_bf16_f32 v65, v68, v69
	s_waitcnt lgkmcnt(0)
	v_mfma_f32_16x16x32_bf16 v[8:11], v[50:53], v[58:61], v[8:11]
	v_lshlrev_b32_e32 v20, 2, v81
	v_mul_u32_u24_e32 v21, 0x110, v30
	v_add3_u32 v20, v49, v20, v21
	v_mfma_f32_16x16x32_bf16 v[12:15], v[50:53], v[54:57], v[12:15]
	s_barrier
	v_mfma_f32_16x16x32_bf16 v[16:19], v[50:53], v[22:25], v[16:19]
	v_mad_u64_u32 v[32:33], s[0:1], v156, s97, v[32:33]
	s_mov_b64 s[0:1], 0x1800
	v_mfma_f32_16x16x32_bf16 v[0:3], v[50:53], v[62:65], v[0:3]
	v_mfma_f32_16x16x32_bf16 v[4:7], v[36:39], v[62:65], v[4:7]
	v_mfma_f32_16x16x32_bf16 v[44:47], v[36:39], v[22:25], v[44:47]
	ds_write2_b32 v20, v26, v40 offset1:16
	ds_write2_b32 v20, v27, v41 offset0:68 offset1:84
	ds_write2_b32 v20, v28, v42 offset0:136 offset1:152
	ds_write2_b32 v20, v29, v43 offset0:204 offset1:220
	s_nop 3
	ds_write2_b32 v20, v44, v4 offset0:32 offset1:48
	ds_write2_b32 v20, v45, v5 offset0:100 offset1:116
	ds_write2_b32 v20, v46, v6 offset0:168 offset1:184
	ds_write2_b32 v20, v47, v7 offset0:236 offset1:252
	ds_write_b32 v20, v11 offset:5168
	v_add_u32_e32 v4, 0x1000, v20
	v_add_u32_e32 v5, 0x1400, v20
	ds_write2_b32 v4, v8, v12 offset0:64 offset1:80
	ds_write2_b32 v4, v9, v13 offset0:132 offset1:148
	ds_write2_b32 v4, v10, v14 offset0:200 offset1:216
	ds_write2_b32 v5, v15, v19 offset0:28 offset1:44
	ds_write2_b32 v4, v16, v0 offset0:96 offset1:112
	ds_write2_b32 v4, v17, v1 offset0:164 offset1:180
	ds_write2_b32 v4, v18, v2 offset0:232 offset1:248
	ds_write_b32 v20, v3 offset:5360
	v_lshlrev_b32_e32 v0, 5, v80
	v_and_b32_e32 v42, 32, v0
	v_mul_u32_u24_e32 v0, 0x110, v35
	v_lshlrev_b32_e32 v45, 2, v42
	v_add3_u32 v40, v49, v0, v45
	s_waitcnt lgkmcnt(0)
	s_barrier
	ds_read_b128 v[28:31], v40
	ds_read_b128 v[24:27], v40 offset:16
	ds_read_b128 v[20:23], v40 offset:32
	ds_read_b128 v[16:19], v40 offset:48
	ds_read_b128 v[12:15], v40 offset:64
	ds_read_b128 v[8:11], v40 offset:80
	s_waitcnt lgkmcnt(5)
	v_mov_b32_e32 v2, v29
	s_waitcnt lgkmcnt(4)
	v_mov_b32_e32 v3, v25
	v_mov_b32_e32 v0, v28
	v_mov_b32_e32 v1, v24
	v_pk_mul_f32 v[2:3], v[2:3], v[2:3]
	v_mov_b32_e32 v4, v31
	v_mov_b32_e32 v5, v27
	v_pk_fma_f32 v[0:1], v[0:1], v[0:1], v[2:3]
	v_mov_b32_e32 v2, v30
	v_mov_b32_e32 v3, v26
	v_pk_mul_f32 v[4:5], v[4:5], v[4:5]
	v_ashrrev_i32_e32 v35, 31, v34
	v_pk_fma_f32 v[2:3], v[2:3], v[2:3], v[4:5]
	s_waitcnt lgkmcnt(3)
	v_pk_mul_f32 v[4:5], v[20:21], v[20:21]
	v_pk_add_f32 v[0:1], v[0:1], v[2:3]
	v_pk_mul_f32 v[2:3], v[22:23], v[22:23]
	v_pk_add_f32 v[0:1], v[0:1], v[0:1] op_sel:[0,1] op_sel_hi:[1,0]
	v_pk_mov_b32 v[6:7], v[4:5], v[2:3] op_sel:[1,0]
	v_mov_b32_e32 v5, v3
	v_pk_add_f32 v[2:3], v[6:7], v[4:5]
	s_waitcnt lgkmcnt(1)
	v_mul_f32_e32 v4, v12, v12
	v_mul_f32_e32 v5, v13, v13
	v_pk_add_f32 v[2:3], v[2:3], v[2:3] op_sel:[0,1] op_sel_hi:[1,0]
	v_mov_b32_e32 v1, v4
	v_mov_b32_e32 v3, v5
	v_pk_add_f32 v[0:1], v[0:1], v[2:3]
	v_mul_f32_e32 v2, v17, v17
	v_mul_f32_e32 v4, v19, v19
	v_mul_f32_e32 v6, v14, v14
	v_mul_f32_e32 v7, v15, v15
	v_pk_fma_f32 v[2:3], v[16:17], v[16:17], v[2:3] op_sel_hi:[1,1,0]
	v_pk_fma_f32 v[4:5], v[18:19], v[18:19], v[4:5] op_sel_hi:[1,1,0]
	v_mov_b32_e32 v3, v6
	v_mov_b32_e32 v5, v7
	v_pk_add_f32 v[2:3], v[2:3], v[4:5]
	v_lshlrev_b64 v[34:35], 1, v[34:35]
	v_pk_add_f32 v[36:37], v[0:1], v[2:3]
	s_waitcnt lgkmcnt(0)
; #define LAS __attribute__((address_space(3)))
; #define LAS __attribute__((address_space(3)))
; DI u32x4 pack8(const float (&f)[8]) { u32x4 o; o.x = pk(f[0], f[1]); o.y = pk(f[2], f[3]); o.z = pk(f[4], f[5]); o.w = pk(f[6], f[7]); return o; }
; template <int MODE>
; DI void gla4_unit(const bf16_t* z, float* ST, float* DEC, bf16_t* Y, const float* aw_g, const float* ab_g, const float* ng, ldsp lds, int tid, int u) {
;     ...
;             const int t7 = tid & 127, t = t7 >> 1, e0 = (t7 & 1) * 32;
;             f32x4 o[8]; float ss = 0.f;
; #pragma unroll
;             for (int k = 0; k < 8; ++k) { o[k] = *(LAS f32x4*)(hr + t * 272 + (e0 + 4 * k) * 4); ss += (o[k][0] * o[k][0] + o[k][1] * o[k][1]) + (o[k][2] * o[k][2] + o[k][3] * o[k][3]); }
;             ss += __shfl_xor(ss, 1);
;             const float rs = rsqrtf(ss * (1.0f / 64.0f) + EPS);
; #pragma unroll
;             for (int k = 0; k < 4; ++k) {
;                 float gg[8]; unpack8(*(const u32x4*)(z + (size_t)(tok0 + t) * ZLD + C_GG + hd * 64 + e0 + 8 * k), gg);
;                 float ov[8];
; #pragma unroll
;                 for (int j = 0; j < 8; ++j) {
;                     const float x = j < 4 ? o[2 * k][j & 3] : o[2 * k + 1][j & 3];
;                     ov[j] = x * rs * ng[e0 + 8 * k + j] * (gg[j] / (1.0f + __expf(-gg[j])));
;                 }
;                 *(u32x4*)(Y + (size_t)(tok0 + t) * D + 768 + hd * 64 + e0 + 8 * k) = pack8(ov);
	v_pk_mul_f32 v[0:1], v[10:11], v[10:11]
	v_pk_mul_f32 v[2:3], v[8:9], v[8:9]
	v_pk_add_f32 v[36:37], v[36:37], v[36:37] op_sel:[0,1] op_sel_hi:[1,0]
	v_pk_mov_b32 v[4:5], v[2:3], v[0:1] op_sel:[1,0]
	v_mov_b32_e32 v3, v1
	v_pk_add_f32 v[38:39], v[4:5], v[2:3]
	ds_read_b128 v[4:7], v40 offset:96
	ds_read_b128 v[0:3], v40 offset:112
	v_pk_add_f32 v[38:39], v[38:39], v[38:39] op_sel:[0,1] op_sel_hi:[1,0]
	v_lshl_add_u64 v[32:33], v[32:33], 0, v[34:35]
	s_waitcnt lgkmcnt(0)
	v_mul_f32_e32 v40, v0, v0
	v_mul_f32_e32 v41, v1, v1
	v_mov_b32_e32 v37, v40
	v_mov_b32_e32 v39, v41
	v_pk_add_f32 v[36:37], v[36:37], v[38:39]
	v_mul_f32_e32 v38, v5, v5
	v_mul_f32_e32 v40, v7, v7
	v_mul_f32_e32 v43, v2, v2
	v_mul_f32_e32 v44, v3, v3
	v_pk_fma_f32 v[38:39], v[4:5], v[4:5], v[38:39] op_sel_hi:[1,1,0]
	v_pk_fma_f32 v[40:41], v[6:7], v[6:7], v[40:41] op_sel_hi:[1,1,0]
	v_mov_b32_e32 v39, v43
	v_mov_b32_e32 v41, v44
	v_pk_add_f32 v[38:39], v[38:39], v[40:41]
	s_nop 0
	v_pk_add_f32 v[36:37], v[36:37], v[38:39]
	v_lshlrev_b64 v[38:39], 11, v[156:157]
	v_add_f32_e32 v36, v36, v37
	ds_bpermute_b32 v37, v137, v36
	v_lshl_add_u64 v[38:39], s[92:93], 0, v[38:39]
	v_lshl_add_u64 v[34:35], v[38:39], 0, v[34:35]
	s_waitcnt lgkmcnt(0)
	v_add_f32_e32 v36, v36, v37
	v_fmamk_f32 v36, v36, 0x3c800000, v162
	v_cmp_gt_f32_e32 vcc, s47, v36
	v_mul_f32_e32 v37, 0x4b800000, v36
	s_nop 0
	v_cndmask_b32_e32 v36, v36, v37, vcc
	v_rsq_f32_e32 v36, v36
	s_nop 0
	v_mul_f32_e32 v37, 0x45800000, v36
	v_cndmask_b32_e32 v44, v36, v37, vcc
	v_lshlrev_b32_e32 v36, 1, v42
	v_mov_b32_e32 v37, v157
	v_lshl_add_u64 v[32:33], v[32:33], 0, v[36:37]
	v_lshl_add_u64 v[42:43], v[32:33], 0, s[0:1]
	v_add_co_u32_e32 v32, vcc, s33, v32
	v_lshl_add_u64 v[40:41], v[34:35], 0, v[36:37]
	s_nop 0
	v_addc_co_u32_e32 v33, vcc, 0, v33, vcc
	global_load_dwordx4 v[32:35], v[32:33], off offset:2048
	global_load_dwordx4 v[86:89], v[42:43], off offset:16
	global_load_dwordx4 v[90:93], v[42:43], off offset:32
	global_load_dwordx4 v[94:97], v[42:43], off offset:48
	global_load_dwordx4 v[98:101], v45, s[20:21]
	global_load_dwordx4 v[102:105], v45, s[20:21] offset:16
	global_load_dwordx4 v[106:109], v45, s[20:21] offset:32
	global_load_dwordx4 v[110:113], v45, s[20:21] offset:48
	global_load_dwordx4 v[120:123], v45, s[20:21] offset:64
	global_load_dwordx4 v[124:127], v45, s[20:21] offset:80
	global_load_dwordx4 v[128:131], v45, s[20:21] offset:96
	global_load_dwordx4 v[132:135], v45, s[20:21] offset:112
	v_mul_f32_e32 v28, v28, v44
	v_mul_f32_e32 v29, v29, v44
	v_mul_f32_e32 v30, v30, v44
	v_mul_f32_e32 v31, v31, v44
	v_mul_f32_e32 v24, v24, v44
	v_mul_f32_e32 v20, v20, v44
	v_mul_f32_e32 v21, v21, v44
	v_mul_f32_e32 v22, v22, v44
	v_mul_f32_e32 v23, v23, v44
	v_mul_f32_e32 v16, v16, v44
	v_mul_f32_e32 v12, v12, v44
	v_mul_f32_e32 v13, v13, v44
	v_mul_f32_e32 v14, v14, v44
	v_mul_f32_e32 v15, v15, v44
	v_mul_f32_e32 v8, v8, v44
	v_mul_f32_e32 v1, v1, v44
	v_mul_f32_e32 v2, v2, v44
	v_mul_f32_e32 v0, v0, v44
	v_mul_f32_e32 v6, v6, v44
	v_mul_f32_e32 v5, v5, v44
	v_mul_f32_e32 v4, v4, v44
	v_mul_f32_e32 v3, v3, v44
	s_waitcnt vmcnt(0)
	v_lshlrev_b32_e32 v52, 16, v32
	v_and_b32_e32 v53, 0xffff0000, v32
	v_lshlrev_b32_e32 v51, 16, v33
	v_and_b32_e32 v50, 0xffff0000, v33
	v_lshlrev_b32_e32 v49, 16, v34
	v_and_b32_e32 v48, 0xffff0000, v34
	v_lshlrev_b32_e32 v47, 16, v35
	v_and_b32_e32 v46, 0xffff0000, v35
	s_nop 1
	v_mov_b32_e32 v32, v102
	v_mov_b32_e32 v33, v103
	v_mov_b32_e32 v34, v104
	v_mov_b32_e32 v35, v105
	s_nop 1
	v_mov_b32_e32 v36, v98
	v_mov_b32_e32 v37, v99
	v_mov_b32_e32 v38, v100
	v_mov_b32_e32 v39, v101
	v_mul_f32_e32 v24, v32, v24
	v_mul_f32_e32 v28, v36, v28
	v_mul_f32_e32 v36, 0xbfb8aa3b, v52
	v_exp_f32_e32 v36, v36
	v_mul_f32_e32 v29, v37, v29
	v_mul_f32_e32 v30, v38, v30
	v_mul_f32_e32 v31, v39, v31
	v_add_f32_e32 v36, 1.0, v36
	v_div_scale_f32 v54, s[0:1], v36, v36, v52
	v_rcp_f32_e32 v55, v54
	v_mul_f32_e32 v32, 0xbfb8aa3b, v49
	v_exp_f32_e32 v32, v32
	v_fma_f32 v56, -v54, v55, 1.0
	v_fmac_f32_e32 v55, v56, v55
	v_div_scale_f32 v56, vcc, v52, v36, v52
	v_mul_f32_e32 v57, v56, v55
	v_fma_f32 v58, -v54, v57, v56
	v_fmac_f32_e32 v57, v58, v55
	v_fma_f32 v54, -v54, v57, v56
	v_div_fmas_f32 v54, v54, v55, v57
	v_div_fixup_f32 v36, v54, v36, v52
	v_mul_f32_e32 v28, v36, v28
	v_mul_f32_e32 v36, 0xbfb8aa3b, v53
	v_exp_f32_e32 v36, v36
	v_add_f32_e32 v32, 1.0, v32
	v_add_f32_e32 v36, 1.0, v36
	v_div_scale_f32 v37, s[0:1], v36, v36, v53
	v_rcp_f32_e32 v52, v37
	s_nop 0
	v_fma_f32 v54, -v37, v52, 1.0
	v_fmac_f32_e32 v52, v54, v52
	v_div_scale_f32 v54, vcc, v53, v36, v53
	v_mul_f32_e32 v55, v54, v52
	v_fma_f32 v56, -v37, v55, v54
	v_fmac_f32_e32 v55, v56, v52
	v_fma_f32 v37, -v37, v55, v54
	v_div_fmas_f32 v37, v37, v52, v55
	v_div_fixup_f32 v36, v37, v36, v53
	v_mul_f32_e32 v29, v36, v29
	v_mul_f32_e32 v36, 0xbfb8aa3b, v51
	v_exp_f32_e32 v36, v36
	s_nop 0
	v_add_f32_e32 v36, 1.0, v36
	v_div_scale_f32 v37, s[0:1], v36, v36, v51
	v_rcp_f32_e32 v38, v37
	s_nop 0
	v_fma_f32 v52, -v37, v38, 1.0
	v_fmac_f32_e32 v38, v52, v38
	v_div_scale_f32 v52, vcc, v51, v36, v51
	v_mul_f32_e32 v53, v52, v38
	v_fma_f32 v54, -v37, v53, v52
	v_fmac_f32_e32 v53, v54, v38
	v_fma_f32 v37, -v37, v53, v52
	v_div_fmas_f32 v37, v37, v38, v53
	v_div_fixup_f32 v36, v37, v36, v51
	v_mul_f32_e32 v30, v36, v30
	v_mul_f32_e32 v36, 0xbfb8aa3b, v50
	v_exp_f32_e32 v36, v36
	s_nop 0
	v_add_f32_e32 v36, 1.0, v36
	v_div_scale_f32 v37, s[0:1], v36, v36, v50
	v_rcp_f32_e32 v38, v37
	s_nop 0
	v_fma_f32 v39, -v37, v38, 1.0
	v_fmac_f32_e32 v38, v39, v38
	v_div_scale_f32 v39, vcc, v50, v36, v50
	v_mul_f32_e32 v51, v39, v38
	v_fma_f32 v52, -v37, v51, v39
; DI u32x4 pack8(const float (&f)[8]) { u32x4 o; o.x = pk(f[0], f[1]); o.y = pk(f[2], f[3]); o.z = pk(f[4], f[5]); o.w = pk(f[6], f[7]); return o; }
; template <int MODE>
; DI void gla4_unit(const bf16_t* z, float* ST, float* DEC, bf16_t* Y, const float* aw_g, const float* ab_g, const float* ng, ldsp lds, int tid, int u) {
;     ...
; #pragma unroll
;             for (int k = 0; k < 4; ++k) {
;                 float gg[8]; unpack8(*(const u32x4*)(z + (size_t)(tok0 + t) * ZLD + C_GG + hd * 64 + e0 + 8 * k), gg);
;                 float ov[8];
; #pragma unroll
;                 for (int j = 0; j < 8; ++j) {
;                     const float x = j < 4 ? o[2 * k][j & 3] : o[2 * k + 1][j & 3];
;                     ov[j] = x * rs * ng[e0 + 8 * k + j] * (gg[j] / (1.0f + __expf(-gg[j])));
;                 }
;                 *(u32x4*)(Y + (size_t)(tok0 + t) * D + 768 + hd * 64 + e0 + 8 * k) = pack8(ov);
	v_fmac_f32_e32 v51, v52, v38
	v_fma_f32 v37, -v37, v51, v39
	v_div_fmas_f32 v37, v37, v38, v51
	v_div_fixup_f32 v36, v37, v36, v50
	v_mul_f32_e32 v31, v36, v31
	v_div_scale_f32 v36, s[0:1], v32, v32, v49
	v_rcp_f32_e32 v37, v36
	s_nop 0
	v_fma_f32 v38, -v36, v37, 1.0
	v_fmac_f32_e32 v37, v38, v37
	v_div_scale_f32 v38, vcc, v49, v32, v49
	v_mul_f32_e32 v39, v38, v37
	v_fma_f32 v50, -v36, v39, v38
	v_fmac_f32_e32 v39, v50, v37
	v_fma_f32 v36, -v36, v39, v38
	v_div_fmas_f32 v36, v36, v37, v39
	v_div_fixup_f32 v32, v36, v32, v49
	v_mul_f32_e32 v32, v32, v24
	v_mul_f32_e32 v24, v25, v44
	v_mul_f32_e32 v25, 0xbfb8aa3b, v48
	v_exp_f32_e32 v25, v25
	v_mul_f32_e32 v24, v33, v24
	v_add_f32_e32 v25, 1.0, v25
	v_div_scale_f32 v33, s[0:1], v25, v25, v48
	v_rcp_f32_e32 v36, v33
	s_nop 0
	v_fma_f32 v37, -v33, v36, 1.0
	v_fmac_f32_e32 v36, v37, v36
	v_div_scale_f32 v37, vcc, v48, v25, v48
	v_mul_f32_e32 v38, v37, v36
	v_fma_f32 v39, -v33, v38, v37
	v_fmac_f32_e32 v38, v39, v36
	v_fma_f32 v33, -v33, v38, v37
	v_div_fmas_f32 v33, v33, v36, v38
	v_div_fixup_f32 v25, v33, v25, v48
	v_mul_f32_e32 v33, v25, v24
	v_mul_f32_e32 v25, 0xbfb8aa3b, v47
	v_exp_f32_e32 v25, v25
	v_mul_f32_e32 v24, v26, v44
	v_mul_f32_e32 v24, v34, v24
	v_add_f32_e32 v25, 1.0, v25
	v_div_scale_f32 v26, s[0:1], v25, v25, v47
	v_rcp_f32_e32 v34, v26
	s_nop 0
	v_fma_f32 v36, -v26, v34, 1.0
	v_fmac_f32_e32 v34, v36, v34
	v_div_scale_f32 v36, vcc, v47, v25, v47
	v_mul_f32_e32 v37, v36, v34
	v_fma_f32 v38, -v26, v37, v36
	v_fmac_f32_e32 v37, v38, v34
	v_fma_f32 v26, -v26, v37, v36
	v_div_fmas_f32 v26, v26, v34, v37
	v_div_fixup_f32 v25, v26, v25, v47
	v_mul_f32_e32 v34, v25, v24
	v_mul_f32_e32 v25, 0xbfb8aa3b, v46
	v_exp_f32_e32 v25, v25
	v_mul_f32_e32 v24, v27, v44
	v_mul_f32_e32 v24, v35, v24
	v_add_f32_e32 v25, 1.0, v25
	v_div_scale_f32 v26, s[0:1], v25, v25, v46
	v_rcp_f32_e32 v27, v26
	s_nop 0
	v_fma_f32 v35, -v26, v27, 1.0
	v_fmac_f32_e32 v27, v35, v27
	v_div_scale_f32 v35, vcc, v46, v25, v46
	v_mul_f32_e32 v36, v35, v27
	v_fma_f32 v37, -v26, v36, v35
	v_fmac_f32_e32 v36, v37, v27
	v_fma_f32 v26, -v26, v36, v35
	v_div_fmas_f32 v26, v26, v27, v36
	v_div_fixup_f32 v25, v26, v25, v46
	v_mul_f32_e32 v27, v25, v24
	v_cvt_pk_bf16_f32 v24, v28, v29
	v_cvt_pk_bf16_f32 v25, v30, v31
	v_cvt_pk_bf16_f32 v26, v32, v33
	v_cvt_pk_bf16_f32 v27, v34, v27
	global_store_dwordx4 v[40:41], v[24:27], off offset:1536
	s_nop 1
	v_mov_b32_e32 v24, v86
	v_mov_b32_e32 v25, v87
	v_mov_b32_e32 v26, v88
	v_mov_b32_e32 v27, v89
	v_lshlrev_b32_e32 v34, 16, v24
	v_and_b32_e32 v35, 0xffff0000, v24
	v_lshlrev_b32_e32 v36, 16, v25
	v_and_b32_e32 v37, 0xffff0000, v25
	v_lshlrev_b32_e32 v38, 16, v26
	v_and_b32_e32 v39, 0xffff0000, v26
	v_lshlrev_b32_e32 v29, 16, v27
	v_and_b32_e32 v28, 0xffff0000, v27
	s_nop 1
	v_mov_b32_e32 v24, v110
	v_mov_b32_e32 v25, v111
	v_mov_b32_e32 v26, v112
	v_mov_b32_e32 v27, v113
	s_nop 1
	v_mov_b32_e32 v30, v106
	v_mov_b32_e32 v31, v107
	v_mov_b32_e32 v32, v108
	v_mov_b32_e32 v33, v109
	v_mul_f32_e32 v16, v16, v24
	v_mul_f32_e32 v20, v20, v30
	v_mul_f32_e32 v30, 0xbfb8aa3b, v34
	v_exp_f32_e32 v30, v30
	v_mul_f32_e32 v21, v21, v31
	v_mul_f32_e32 v22, v22, v32
	v_mul_f32_e32 v23, v23, v33
	v_add_f32_e32 v30, 1.0, v30
	v_div_scale_f32 v46, s[0:1], v30, v30, v34
	v_rcp_f32_e32 v47, v46
	v_mul_f32_e32 v24, 0xbfb8aa3b, v38
	v_exp_f32_e32 v24, v24
	v_fma_f32 v48, -v46, v47, 1.0
	v_fmac_f32_e32 v47, v48, v47
	v_div_scale_f32 v48, vcc, v34, v30, v34
	v_mul_f32_e32 v49, v48, v47
	v_fma_f32 v50, -v46, v49, v48
	v_fmac_f32_e32 v49, v50, v47
	v_fma_f32 v46, -v46, v49, v48
	v_div_fmas_f32 v46, v46, v47, v49
	v_div_fixup_f32 v30, v46, v30, v34
	v_mul_f32_e32 v20, v20, v30
	v_mul_f32_e32 v30, 0xbfb8aa3b, v35
	v_exp_f32_e32 v30, v30
	v_add_f32_e32 v24, 1.0, v24
	v_add_f32_e32 v30, 1.0, v30
	v_div_scale_f32 v31, s[0:1], v30, v30, v35
	v_rcp_f32_e32 v34, v31
	s_nop 0
	v_fma_f32 v46, -v31, v34, 1.0
	v_fmac_f32_e32 v34, v46, v34
	v_div_scale_f32 v46, vcc, v35, v30, v35
	v_mul_f32_e32 v47, v46, v34
	v_fma_f32 v48, -v31, v47, v46
	v_fmac_f32_e32 v47, v48, v34
	v_fma_f32 v31, -v31, v47, v46
	v_div_fmas_f32 v31, v31, v34, v47
	v_div_fixup_f32 v30, v31, v30, v35
	v_mul_f32_e32 v21, v21, v30
	v_mul_f32_e32 v30, 0xbfb8aa3b, v36
	v_exp_f32_e32 v30, v30
	s_nop 0
	v_add_f32_e32 v30, 1.0, v30
	v_div_scale_f32 v31, s[0:1], v30, v30, v36
	v_rcp_f32_e32 v32, v31
	s_nop 0
	v_fma_f32 v34, -v31, v32, 1.0
	v_fmac_f32_e32 v32, v34, v32
	v_div_scale_f32 v34, vcc, v36, v30, v36
	v_mul_f32_e32 v35, v34, v32
	v_fma_f32 v46, -v31, v35, v34
	v_fmac_f32_e32 v35, v46, v32
	v_fma_f32 v31, -v31, v35, v34
	v_div_fmas_f32 v31, v31, v32, v35
	v_div_fixup_f32 v30, v31, v30, v36
	v_mul_f32_e32 v22, v22, v30
	v_mul_f32_e32 v30, 0xbfb8aa3b, v37
	v_exp_f32_e32 v30, v30
	s_nop 0
	v_add_f32_e32 v30, 1.0, v30
	v_div_scale_f32 v31, s[0:1], v30, v30, v37
	v_rcp_f32_e32 v32, v31
	s_nop 0
	v_fma_f32 v33, -v31, v32, 1.0
	v_fmac_f32_e32 v32, v33, v32
	v_div_scale_f32 v33, vcc, v37, v30, v37
	v_mul_f32_e32 v34, v33, v32
	v_fma_f32 v35, -v31, v34, v33
	v_fmac_f32_e32 v34, v35, v32
	v_fma_f32 v31, -v31, v34, v33
	v_div_fmas_f32 v31, v31, v32, v34
	v_div_fixup_f32 v30, v31, v30, v37
	v_mul_f32_e32 v23, v23, v30
	v_div_scale_f32 v30, s[0:1], v24, v24, v38
	v_rcp_f32_e32 v31, v30
	s_nop 0
	v_fma_f32 v32, -v30, v31, 1.0
	v_fmac_f32_e32 v31, v32, v31
	v_div_scale_f32 v32, vcc, v38, v24, v38
	v_mul_f32_e32 v33, v32, v31
	v_fma_f32 v34, -v30, v33, v32
	v_fmac_f32_e32 v33, v34, v31
	v_fma_f32 v30, -v30, v33, v32
	v_div_fmas_f32 v30, v30, v31, v33
	v_div_fixup_f32 v24, v30, v24, v38
	v_mul_f32_e32 v24, v16, v24
	v_mul_f32_e32 v16, v17, v44
	v_mul_f32_e32 v17, 0xbfb8aa3b, v39
; DI u32x4 pack8(const float (&f)[8]) { u32x4 o; o.x = pk(f[0], f[1]); o.y = pk(f[2], f[3]); o.z = pk(f[4], f[5]); o.w = pk(f[6], f[7]); return o; }
; template <int MODE>
; DI void gla4_unit(const bf16_t* z, float* ST, float* DEC, bf16_t* Y, const float* aw_g, const float* ab_g, const float* ng, ldsp lds, int tid, int u) {
;     ...
; #pragma unroll
;             for (int k = 0; k < 4; ++k) {
;                 float gg[8]; unpack8(*(const u32x4*)(z + (size_t)(tok0 + t) * ZLD + C_GG + hd * 64 + e0 + 8 * k), gg);
;                 float ov[8];
; #pragma unroll
;                 for (int j = 0; j < 8; ++j) {
;                     const float x = j < 4 ? o[2 * k][j & 3] : o[2 * k + 1][j & 3];
;                     ov[j] = x * rs * ng[e0 + 8 * k + j] * (gg[j] / (1.0f + __expf(-gg[j])));
;                 }
;                 *(u32x4*)(Y + (size_t)(tok0 + t) * D + 768 + hd * 64 + e0 + 8 * k) = pack8(ov);
	v_exp_f32_e32 v17, v17
	v_mul_f32_e32 v16, v16, v25
	v_add_f32_e32 v17, 1.0, v17
	v_div_scale_f32 v25, s[0:1], v17, v17, v39
	v_rcp_f32_e32 v30, v25
	s_nop 0
	v_fma_f32 v31, -v25, v30, 1.0
	v_fmac_f32_e32 v30, v31, v30
	v_div_scale_f32 v31, vcc, v39, v17, v39
	v_mul_f32_e32 v32, v31, v30
	v_fma_f32 v33, -v25, v32, v31
	v_fmac_f32_e32 v32, v33, v30
	v_fma_f32 v25, -v25, v32, v31
	v_div_fmas_f32 v25, v25, v30, v32
	v_div_fixup_f32 v17, v25, v17, v39
	v_mul_f32_e32 v25, v17, v16
	v_mul_f32_e32 v17, 0xbfb8aa3b, v29
	v_exp_f32_e32 v17, v17
	v_mul_f32_e32 v16, v18, v44
	v_mul_f32_e32 v16, v16, v26
	v_add_f32_e32 v17, 1.0, v17
	v_div_scale_f32 v18, s[0:1], v17, v17, v29
	v_rcp_f32_e32 v26, v18
	s_nop 0
	v_fma_f32 v30, -v18, v26, 1.0
	v_fmac_f32_e32 v26, v30, v26
	v_div_scale_f32 v30, vcc, v29, v17, v29
	v_mul_f32_e32 v31, v30, v26
	v_fma_f32 v32, -v18, v31, v30
	v_fmac_f32_e32 v31, v32, v26
	v_fma_f32 v18, -v18, v31, v30
	v_div_fmas_f32 v18, v18, v26, v31
	v_div_fixup_f32 v17, v18, v17, v29
	v_mul_f32_e32 v26, v17, v16
	v_mul_f32_e32 v17, 0xbfb8aa3b, v28
	v_exp_f32_e32 v17, v17
	v_mul_f32_e32 v16, v19, v44
	v_mul_f32_e32 v16, v16, v27
	v_add_f32_e32 v17, 1.0, v17
	v_div_scale_f32 v18, s[0:1], v17, v17, v28
	v_rcp_f32_e32 v19, v18
	s_nop 0
	v_fma_f32 v27, -v18, v19, 1.0
	v_fmac_f32_e32 v19, v27, v19
	v_div_scale_f32 v27, vcc, v28, v17, v28
	v_mul_f32_e32 v29, v27, v19
	v_fma_f32 v30, -v18, v29, v27
	v_fmac_f32_e32 v29, v30, v19
	v_fma_f32 v18, -v18, v29, v27
	v_div_fmas_f32 v18, v18, v19, v29
	v_div_fixup_f32 v17, v18, v17, v28
	v_mul_f32_e32 v19, v17, v16
	v_cvt_pk_bf16_f32 v16, v20, v21
	v_cvt_pk_bf16_f32 v17, v22, v23
	v_cvt_pk_bf16_f32 v18, v24, v25
	v_cvt_pk_bf16_f32 v19, v26, v19
	global_store_dwordx4 v[40:41], v[16:19], off offset:1552
	s_nop 1
	v_mov_b32_e32 v16, v90
	v_mov_b32_e32 v17, v91
	v_mov_b32_e32 v18, v92
	v_mov_b32_e32 v19, v93
	v_lshlrev_b32_e32 v26, 16, v16
	v_and_b32_e32 v27, 0xffff0000, v16
	v_lshlrev_b32_e32 v28, 16, v17
	v_and_b32_e32 v29, 0xffff0000, v17
	v_lshlrev_b32_e32 v30, 16, v18
	v_and_b32_e32 v31, 0xffff0000, v18
	v_lshlrev_b32_e32 v21, 16, v19
	v_and_b32_e32 v20, 0xffff0000, v19
	s_nop 1
	v_mov_b32_e32 v16, v124
	v_mov_b32_e32 v17, v125
	v_mov_b32_e32 v18, v126
	v_mov_b32_e32 v19, v127
	s_nop 1
	v_mov_b32_e32 v22, v120
	v_mov_b32_e32 v23, v121
	v_mov_b32_e32 v24, v122
	v_mov_b32_e32 v25, v123
	v_mul_f32_e32 v8, v8, v16
	v_mul_f32_e32 v12, v12, v22
	v_mul_f32_e32 v22, 0xbfb8aa3b, v26
	v_exp_f32_e32 v22, v22
	v_mul_f32_e32 v13, v13, v23
	v_mul_f32_e32 v14, v14, v24
	v_mul_f32_e32 v15, v15, v25
	v_add_f32_e32 v22, 1.0, v22
	v_div_scale_f32 v32, s[0:1], v22, v22, v26
	v_rcp_f32_e32 v33, v32
	v_mul_f32_e32 v16, 0xbfb8aa3b, v30
	v_exp_f32_e32 v16, v16
	v_fma_f32 v34, -v32, v33, 1.0
	v_fmac_f32_e32 v33, v34, v33
	v_div_scale_f32 v34, vcc, v26, v22, v26
	v_mul_f32_e32 v35, v34, v33
	v_fma_f32 v36, -v32, v35, v34
	v_fmac_f32_e32 v35, v36, v33
	v_fma_f32 v32, -v32, v35, v34
	v_div_fmas_f32 v32, v32, v33, v35
	v_div_fixup_f32 v22, v32, v22, v26
	v_mul_f32_e32 v12, v12, v22
	v_mul_f32_e32 v22, 0xbfb8aa3b, v27
	v_exp_f32_e32 v22, v22
	v_add_f32_e32 v16, 1.0, v16
	v_add_f32_e32 v22, 1.0, v22
	v_div_scale_f32 v23, s[0:1], v22, v22, v27
	v_rcp_f32_e32 v26, v23
	s_nop 0
	v_fma_f32 v32, -v23, v26, 1.0
	v_fmac_f32_e32 v26, v32, v26
	v_div_scale_f32 v32, vcc, v27, v22, v27
	v_mul_f32_e32 v33, v32, v26
	v_fma_f32 v34, -v23, v33, v32
	v_fmac_f32_e32 v33, v34, v26
	v_fma_f32 v23, -v23, v33, v32
	v_div_fmas_f32 v23, v23, v26, v33
	v_div_fixup_f32 v22, v23, v22, v27
	v_mul_f32_e32 v13, v13, v22
	v_mul_f32_e32 v22, 0xbfb8aa3b, v28
	v_exp_f32_e32 v22, v22
	s_nop 0
	v_add_f32_e32 v22, 1.0, v22
	v_div_scale_f32 v23, s[0:1], v22, v22, v28
	v_rcp_f32_e32 v24, v23
	s_nop 0
	v_fma_f32 v26, -v23, v24, 1.0
	v_fmac_f32_e32 v24, v26, v24
	v_div_scale_f32 v26, vcc, v28, v22, v28
	v_mul_f32_e32 v27, v26, v24
	v_fma_f32 v32, -v23, v27, v26
	v_fmac_f32_e32 v27, v32, v24
	v_fma_f32 v23, -v23, v27, v26
	v_div_fmas_f32 v23, v23, v24, v27
	v_div_fixup_f32 v22, v23, v22, v28
	v_mul_f32_e32 v14, v14, v22
	v_mul_f32_e32 v22, 0xbfb8aa3b, v29
	v_exp_f32_e32 v22, v22
	s_nop 0
	v_add_f32_e32 v22, 1.0, v22
	v_div_scale_f32 v23, s[0:1], v22, v22, v29
	v_rcp_f32_e32 v24, v23
	s_nop 0
	v_fma_f32 v25, -v23, v24, 1.0
	v_fmac_f32_e32 v24, v25, v24
	v_div_scale_f32 v25, vcc, v29, v22, v29
	v_mul_f32_e32 v26, v25, v24
	v_fma_f32 v27, -v23, v26, v25
	v_fmac_f32_e32 v26, v27, v24
	v_fma_f32 v23, -v23, v26, v25
	v_div_fmas_f32 v23, v23, v24, v26
	v_div_fixup_f32 v22, v23, v22, v29
	v_mul_f32_e32 v15, v15, v22
	v_div_scale_f32 v22, s[0:1], v16, v16, v30
	v_rcp_f32_e32 v23, v22
	s_nop 0
	v_fma_f32 v24, -v22, v23, 1.0
	v_fmac_f32_e32 v23, v24, v23
	v_div_scale_f32 v24, vcc, v30, v16, v30
	v_mul_f32_e32 v25, v24, v23
	v_fma_f32 v26, -v22, v25, v24
	v_fmac_f32_e32 v25, v26, v23
	v_fma_f32 v22, -v22, v25, v24
	v_div_fmas_f32 v22, v22, v23, v25
	v_div_fixup_f32 v16, v22, v16, v30
	v_mul_f32_e32 v16, v8, v16
	v_mul_f32_e32 v8, v9, v44
	v_mul_f32_e32 v9, 0xbfb8aa3b, v31
	v_exp_f32_e32 v9, v9
	v_mul_f32_e32 v8, v8, v17
	v_add_f32_e32 v9, 1.0, v9
	v_div_scale_f32 v17, s[0:1], v9, v9, v31
	v_rcp_f32_e32 v22, v17
	s_nop 0
	v_fma_f32 v23, -v17, v22, 1.0
	v_fmac_f32_e32 v22, v23, v22
	v_div_scale_f32 v23, vcc, v31, v9, v31
	v_mul_f32_e32 v24, v23, v22
	v_fma_f32 v25, -v17, v24, v23
	v_fmac_f32_e32 v24, v25, v22
	v_fma_f32 v17, -v17, v24, v23
	v_div_fmas_f32 v17, v17, v22, v24
	v_div_fixup_f32 v9, v17, v9, v31
	v_mul_f32_e32 v17, v9, v8
	v_mul_f32_e32 v9, 0xbfb8aa3b, v21
	v_exp_f32_e32 v9, v9
	v_mul_f32_e32 v8, v10, v44
	v_mul_f32_e32 v8, v8, v18
	v_add_f32_e32 v9, 1.0, v9
; DI u32x4 pack8(const float (&f)[8]) { u32x4 o; o.x = pk(f[0], f[1]); o.y = pk(f[2], f[3]); o.z = pk(f[4], f[5]); o.w = pk(f[6], f[7]); return o; }
; template <int MODE>
; DI void gla4_unit(const bf16_t* z, float* ST, float* DEC, bf16_t* Y, const float* aw_g, const float* ab_g, const float* ng, ldsp lds, int tid, int u) {
;     ...
; #pragma unroll
;             for (int k = 0; k < 4; ++k) {
;                 float gg[8]; unpack8(*(const u32x4*)(z + (size_t)(tok0 + t) * ZLD + C_GG + hd * 64 + e0 + 8 * k), gg);
;                 float ov[8];
; #pragma unroll
;                 for (int j = 0; j < 8; ++j) {
;                     const float x = j < 4 ? o[2 * k][j & 3] : o[2 * k + 1][j & 3];
;                     ov[j] = x * rs * ng[e0 + 8 * k + j] * (gg[j] / (1.0f + __expf(-gg[j])));
;                 }
;                 *(u32x4*)(Y + (size_t)(tok0 + t) * D + 768 + hd * 64 + e0 + 8 * k) = pack8(ov);
	v_div_scale_f32 v10, s[0:1], v9, v9, v21
	v_rcp_f32_e32 v18, v10
	s_nop 0
	v_fma_f32 v22, -v10, v18, 1.0
	v_fmac_f32_e32 v18, v22, v18
	v_div_scale_f32 v22, vcc, v21, v9, v21
	v_mul_f32_e32 v23, v22, v18
	v_fma_f32 v24, -v10, v23, v22
	v_fmac_f32_e32 v23, v24, v18
	v_fma_f32 v10, -v10, v23, v22
	v_div_fmas_f32 v10, v10, v18, v23
	v_div_fixup_f32 v9, v10, v9, v21
	v_mul_f32_e32 v18, v9, v8
	v_mul_f32_e32 v9, 0xbfb8aa3b, v20
	v_exp_f32_e32 v9, v9
	v_mul_f32_e32 v8, v11, v44
	v_mul_f32_e32 v8, v8, v19
	v_add_f32_e32 v9, 1.0, v9
	v_div_scale_f32 v10, s[0:1], v9, v9, v20
	v_rcp_f32_e32 v11, v10
	s_nop 0
	v_fma_f32 v19, -v10, v11, 1.0
	v_fmac_f32_e32 v11, v19, v11
	v_div_scale_f32 v19, vcc, v20, v9, v20
	v_mul_f32_e32 v21, v19, v11
	v_fma_f32 v22, -v10, v21, v19
	v_fmac_f32_e32 v21, v22, v11
	v_fma_f32 v10, -v10, v21, v19
	v_div_fmas_f32 v10, v10, v11, v21
	v_div_fixup_f32 v9, v10, v9, v20
	v_mul_f32_e32 v11, v9, v8
	v_cvt_pk_bf16_f32 v8, v12, v13
	v_cvt_pk_bf16_f32 v9, v14, v15
	v_cvt_pk_bf16_f32 v10, v16, v17
	v_cvt_pk_bf16_f32 v11, v18, v11
	global_store_dwordx4 v[40:41], v[8:11], off offset:1568
	s_nop 1
	v_mov_b32_e32 v16, v94
	v_mov_b32_e32 v17, v95
	v_mov_b32_e32 v18, v96
	v_mov_b32_e32 v19, v97
	s_nop 0
	s_nop 1
	v_mov_b32_e32 v8, v132
	v_mov_b32_e32 v9, v133
	v_mov_b32_e32 v10, v134
	v_mov_b32_e32 v11, v135
	s_nop 1
	v_mov_b32_e32 v12, v128
	v_mov_b32_e32 v13, v129
	v_mov_b32_e32 v14, v130
	v_mov_b32_e32 v15, v131
	v_lshlrev_b32_e32 v20, 16, v19
	v_mul_f32_e32 v21, 0xbfb8aa3b, v20
	v_exp_f32_e32 v21, v21
	v_mul_f32_e32 v1, v1, v9
	v_mul_f32_e32 v2, v2, v10
	v_mul_f32_e32 v0, v0, v8
	v_add_f32_e32 v21, 1.0, v21
	v_div_scale_f32 v22, s[0:1], v21, v21, v20
	v_rcp_f32_e32 v23, v22
	v_mul_f32_e32 v6, v6, v14
	v_mul_f32_e32 v5, v5, v13
	v_and_b32_e32 v19, 0xffff0000, v19
	v_fma_f32 v24, -v22, v23, 1.0
	v_fmac_f32_e32 v23, v24, v23
	v_div_scale_f32 v24, vcc, v20, v21, v20
	v_mul_f32_e32 v25, v24, v23
	v_fma_f32 v26, -v22, v25, v24
	v_fmac_f32_e32 v25, v26, v23
	v_fma_f32 v22, -v22, v25, v24
	v_div_fmas_f32 v22, v22, v23, v25
	v_div_fixup_f32 v20, v22, v21, v20
	v_lshlrev_b32_e32 v21, 16, v18
	v_and_b32_e32 v18, 0xffff0000, v18
	v_mul_f32_e32 v22, 0xbfb8aa3b, v18
	v_exp_f32_e32 v22, v22
	v_mul_f32_e32 v10, v20, v2
	v_lshlrev_b32_e32 v20, 16, v17
	v_and_b32_e32 v17, 0xffff0000, v17
	v_add_f32_e32 v22, 1.0, v22
	v_div_scale_f32 v23, s[0:1], v22, v22, v18
	v_rcp_f32_e32 v24, v23
	v_lshlrev_b32_e32 v2, 16, v16
	v_and_b32_e32 v16, 0xffff0000, v16
	v_mul_f32_e32 v4, v4, v12
	v_fma_f32 v25, -v23, v24, 1.0
	v_fmac_f32_e32 v24, v25, v24
	v_div_scale_f32 v25, vcc, v18, v22, v18
	v_mul_f32_e32 v26, v25, v24
	v_fma_f32 v27, -v23, v26, v25
	v_fmac_f32_e32 v26, v27, v24
	v_fma_f32 v23, -v23, v26, v25
	v_div_fmas_f32 v23, v23, v24, v26
	v_div_fixup_f32 v18, v23, v22, v18
	v_mul_f32_e32 v9, v18, v1
	v_mul_f32_e32 v1, 0xbfb8aa3b, v21
	v_exp_f32_e32 v1, v1
	v_mul_f32_e32 v3, v3, v11
	v_add_f32_e32 v1, 1.0, v1
	v_div_scale_f32 v18, s[0:1], v1, v1, v21
	v_rcp_f32_e32 v22, v18
	s_nop 0
	v_fma_f32 v23, -v18, v22, 1.0
	v_fmac_f32_e32 v22, v23, v22
	v_div_scale_f32 v23, vcc, v21, v1, v21
	v_mul_f32_e32 v24, v23, v22
	v_fma_f32 v25, -v18, v24, v23
	v_fmac_f32_e32 v24, v25, v22
	v_fma_f32 v18, -v18, v24, v23
	v_div_fmas_f32 v18, v18, v22, v24
	v_div_fixup_f32 v1, v18, v1, v21
	v_mul_f32_e32 v8, v0, v1
	v_mul_f32_e32 v0, 0xbfb8aa3b, v17
	v_exp_f32_e32 v0, v0
	s_nop 0
	v_add_f32_e32 v0, 1.0, v0
	v_div_scale_f32 v1, s[0:1], v0, v0, v17
	v_rcp_f32_e32 v18, v1
	s_nop 0
	v_fma_f32 v21, -v1, v18, 1.0
	v_fmac_f32_e32 v18, v21, v18
	v_div_scale_f32 v21, vcc, v17, v0, v17
	v_mul_f32_e32 v22, v21, v18
	v_fma_f32 v23, -v1, v22, v21
	v_fmac_f32_e32 v22, v23, v18
	v_fma_f32 v1, -v1, v22, v21
	v_div_fmas_f32 v1, v1, v18, v22
	v_div_fixup_f32 v0, v1, v0, v17
	v_mul_f32_e32 v1, v7, v44
	v_mul_f32_e32 v1, v1, v15
	v_mul_f32_e32 v1, v1, v0
	v_mul_f32_e32 v0, 0xbfb8aa3b, v20
	v_exp_f32_e32 v0, v0
	s_nop 0
	v_add_f32_e32 v0, 1.0, v0
	v_div_scale_f32 v7, s[0:1], v0, v0, v20
	v_rcp_f32_e32 v15, v7
	s_nop 0
	v_fma_f32 v17, -v7, v15, 1.0
	v_fmac_f32_e32 v15, v17, v15
	v_div_scale_f32 v17, vcc, v20, v0, v20
	v_mul_f32_e32 v18, v17, v15
	v_fma_f32 v21, -v7, v18, v17
	v_fmac_f32_e32 v18, v21, v15
	v_fma_f32 v7, -v7, v18, v17
	v_div_fmas_f32 v7, v7, v15, v18
	v_div_fixup_f32 v0, v7, v0, v20
	v_mul_f32_e32 v6, v6, v0
	v_mul_f32_e32 v0, 0xbfb8aa3b, v16
	v_exp_f32_e32 v0, v0
	s_nop 0
	v_add_f32_e32 v0, 1.0, v0
	v_div_scale_f32 v7, s[0:1], v0, v0, v16
	v_rcp_f32_e32 v14, v7
	s_nop 0
	v_fma_f32 v15, -v7, v14, 1.0
	v_fmac_f32_e32 v14, v15, v14
	v_div_scale_f32 v15, vcc, v16, v0, v16
	v_mul_f32_e32 v17, v15, v14
	v_fma_f32 v18, -v7, v17, v15
	v_fmac_f32_e32 v17, v18, v14
	v_fma_f32 v7, -v7, v17, v15
	v_div_fmas_f32 v7, v7, v14, v17
	v_div_fixup_f32 v0, v7, v0, v16
	v_mul_f32_e32 v0, v5, v0
	v_mul_f32_e32 v5, 0xbfb8aa3b, v2
	v_exp_f32_e32 v5, v5
	s_nop 0
	v_add_f32_e32 v5, 1.0, v5
	v_div_scale_f32 v7, s[0:1], v5, v5, v2
	v_rcp_f32_e32 v13, v7
	s_nop 0
	v_fma_f32 v14, -v7, v13, 1.0
	v_fmac_f32_e32 v13, v14, v13
	v_div_scale_f32 v14, vcc, v2, v5, v2
	v_mul_f32_e32 v15, v14, v13
	v_fma_f32 v16, -v7, v15, v14
	v_fmac_f32_e32 v15, v16, v13
	v_fma_f32 v7, -v7, v15, v14
	v_div_fmas_f32 v7, v7, v13, v15
	v_div_fixup_f32 v2, v7, v5, v2
	v_mul_f32_e32 v2, v4, v2
	v_mul_f32_e32 v4, 0xbfb8aa3b, v19
	v_exp_f32_e32 v4, v4
	v_cvt_pk_bf16_f32 v0, v2, v0
	v_cvt_pk_bf16_f32 v1, v6, v1
	v_cvt_pk_bf16_f32 v2, v8, v9
	s_nop 0
	v_add_f32_e32 v4, 1.0, v4
	v_div_scale_f32 v5, s[0:1], v4, v4, v19
	v_rcp_f32_e32 v7, v5
	s_mov_b64 s[0:1], 0
	v_fma_f32 v11, -v5, v7, 1.0
	v_fmac_f32_e32 v7, v11, v7
	v_div_scale_f32 v11, vcc, v19, v4, v19
	v_mul_f32_e32 v12, v11, v7
	v_fma_f32 v13, -v5, v12, v11
	v_fmac_f32_e32 v12, v13, v7
	v_fma_f32 v5, -v5, v12, v11
	v_div_fmas_f32 v5, v5, v7, v12
	v_div_fixup_f32 v4, v5, v4, v19
	v_mul_f32_e32 v3, v4, v3
	v_cvt_pk_bf16_f32 v3, v10, v3
	global_store_dwordx4 v[40:41], v[0:3], off offset:1584

; #define LAS __attribute__((address_space(3)))
; #define LAS __attribute__((address_space(3)))
; DI void attn_unit(const bf16_t* z, const bf16_t* VT, bf16_t* Y, const float* subg, ldsp lds, int tid, int b, int h, int qb, float lam, float ns, float oscale, int win) {
;     ...
;     if (!comp) {
;         float ss0 = 0.f, ss1 = 0.f;
; #pragma unroll
;         for (int e = 0; e < 8; ++e)
; #pragma unroll
;             for (int qt = 0; qt < 2; ++qt)
; #pragma unroll
;                 for (int r = 0; r < 4; ++r) {
;                     const float o = O[e][qt][r] * (qt ? sc1 : sc0) - *(LAS float*)(xp + ((2 * e + qt) * 4 + r) * 256);
;                     O[e][qt][r] = o; if (qt) ss1 += o * o; else ss0 += o * o;
;                 }
.LBB0_421:
	s_andn2_b64 vcc, exec, s[0:1]
	s_waitcnt lgkmcnt(0)
	s_barrier
	s_cbranch_vccnz .LBB0_401
	ds_read2st64_b32 v[60:61], v70 offset1:1
	ds_read2st64_b32 v[62:63], v70 offset0:4 offset1:5
	ds_read2st64_b32 v[64:65], v70 offset0:6 offset1:7
	ds_read2st64_b32 v[66:67], v70 offset0:2 offset1:3
	v_mov_b32_e32 v59, v72
	s_waitcnt lgkmcnt(3)
	v_mov_b32_e32 v69, v60
	v_mov_b32_e32 v72, v77
	s_waitcnt lgkmcnt(2)
	v_mov_b32_e32 v60, v63
	v_mov_b32_e32 v58, v76
	v_mov_b32_e32 v68, v62
	v_pk_fma_f32 v[60:61], v[72:73], v[56:57], v[60:61] neg_lo:[0,0,1] neg_hi:[0,0,1]
	v_pk_fma_f32 v[58:59], v[58:59], v[56:57], v[68:69] neg_lo:[0,0,1] neg_hi:[0,0,1]
	v_pk_mul_f32 v[62:63], v[60:61], v[60:61]
	s_waitcnt lgkmcnt(1)
	v_mov_b32_e32 v72, v64
	v_pk_fma_f32 v[68:69], v[58:59], v[58:59], v[62:63]
	v_mov_b32_e32 v62, v78
	v_mov_b32_e32 v63, v74
	s_waitcnt lgkmcnt(0)
	v_mov_b32_e32 v73, v66
	v_mov_b32_e32 v74, v79
	v_mov_b32_e32 v66, v65
	v_pk_fma_f32 v[62:63], v[62:63], v[56:57], v[72:73] neg_lo:[0,0,1] neg_hi:[0,0,1]
	v_pk_fma_f32 v[64:65], v[74:75], v[56:57], v[66:67] neg_lo:[0,0,1] neg_hi:[0,0,1]
	ds_read2st64_b32 v[72:73], v70 offset0:8 offset1:9
	ds_read2st64_b32 v[74:75], v70 offset0:12 offset1:13
	ds_read2st64_b32 v[76:77], v70 offset0:14 offset1:15
	ds_read2st64_b32 v[78:79], v70 offset0:10 offset1:11
	v_pk_fma_f32 v[68:69], v[62:63], v[62:63], v[68:69]
	v_mov_b32_e32 v66, v48
	v_mov_b32_e32 v67, v52
	s_waitcnt lgkmcnt(2)
	v_mov_b32_e32 v80, v74
	v_mov_b32_e32 v81, v72
	v_pk_fma_f32 v[66:67], v[66:67], v[56:57], v[80:81] neg_lo:[0,0,1] neg_hi:[0,0,1]
	v_mov_b32_e32 v52, v49
	v_pk_fma_f32 v[48:49], v[64:65], v[64:65], v[68:69]
	v_mov_b32_e32 v72, v75
	ds_read2st64_b32 v[80:81], v70 offset0:16 offset1:17
	ds_read2st64_b32 v[82:83], v70 offset0:18 offset1:19
	ds_read2st64_b32 v[84:85], v70 offset0:20 offset1:21
	ds_read2st64_b32 v[86:87], v70 offset0:22 offset1:23
	ds_read2st64_b32 v[88:89], v70 offset0:24 offset1:25
	ds_read2st64_b32 v[90:91], v70 offset0:28 offset1:29
	v_pk_fma_f32 v[68:69], v[66:67], v[66:67], v[48:49]
	v_pk_fma_f32 v[48:49], v[52:53], v[56:57], v[72:73] neg_lo:[0,0,1] neg_hi:[0,0,1]
	v_mov_b32_e32 v52, v50
	v_mov_b32_e32 v53, v54
	s_waitcnt lgkmcnt(7)
	v_mov_b32_e32 v72, v76
	s_waitcnt lgkmcnt(6)
	v_mov_b32_e32 v73, v78
	v_pk_fma_f32 v[68:69], v[48:49], v[48:49], v[68:69]
	v_pk_fma_f32 v[52:53], v[52:53], v[56:57], v[72:73] neg_lo:[0,0,1] neg_hi:[0,0,1]
	v_mov_b32_e32 v54, v51
	v_mov_b32_e32 v78, v77
	v_pk_fma_f32 v[68:69], v[52:53], v[52:53], v[68:69]
	v_pk_fma_f32 v[54:55], v[54:55], v[56:57], v[78:79] neg_lo:[0,0,1] neg_hi:[0,0,1]
	v_mov_b32_e32 v50, v40
	v_mov_b32_e32 v51, v44
	s_waitcnt lgkmcnt(3)
	v_mov_b32_e32 v72, v84
	v_mov_b32_e32 v73, v80
	v_mov_b32_e32 v44, v41
	v_mov_b32_e32 v80, v85
	v_pk_fma_f32 v[68:69], v[54:55], v[54:55], v[68:69]
	v_pk_fma_f32 v[50:51], v[50:51], v[56:57], v[72:73] neg_lo:[0,0,1] neg_hi:[0,0,1]
	v_pk_fma_f32 v[40:41], v[44:45], v[56:57], v[80:81] neg_lo:[0,0,1] neg_hi:[0,0,1]
	v_mov_b32_e32 v44, v42
	v_mov_b32_e32 v45, v46
	s_waitcnt lgkmcnt(2)
	v_mov_b32_e32 v72, v86
	v_mov_b32_e32 v73, v82
	v_pk_fma_f32 v[68:69], v[50:51], v[50:51], v[68:69]
	v_pk_fma_f32 v[44:45], v[44:45], v[56:57], v[72:73] neg_lo:[0,0,1] neg_hi:[0,0,1]
	ds_read2st64_b32 v[72:73], v70 offset0:30 offset1:31
	ds_read2st64_b32 v[74:75], v70 offset0:26 offset1:27
	v_pk_fma_f32 v[68:69], v[40:41], v[40:41], v[68:69]
	v_mov_b32_e32 v46, v43
	v_mov_b32_e32 v82, v87
	v_pk_fma_f32 v[68:69], v[44:45], v[44:45], v[68:69]
	v_pk_fma_f32 v[42:43], v[46:47], v[56:57], v[82:83] neg_lo:[0,0,1] neg_hi:[0,0,1]
	v_mov_b32_e32 v46, v32
	v_mov_b32_e32 v47, v36
	s_waitcnt lgkmcnt(2)
	v_mov_b32_e32 v76, v90
	v_mov_b32_e32 v77, v88
	v_pk_fma_f32 v[68:69], v[42:43], v[42:43], v[68:69]
	v_pk_fma_f32 v[46:47], v[46:47], v[56:57], v[76:77] neg_lo:[0,0,1] neg_hi:[0,0,1]
	v_mov_b32_e32 v36, v33
	v_mov_b32_e32 v88, v91
	v_pk_fma_f32 v[68:69], v[46:47], v[46:47], v[68:69]
	v_pk_fma_f32 v[32:33], v[36:37], v[56:57], v[88:89] neg_lo:[0,0,1] neg_hi:[0,0,1]
	v_mov_b32_e32 v37, v38
	v_pk_fma_f32 v[76:77], v[32:33], v[32:33], v[68:69]
	s_waitcnt lgkmcnt(0)
	v_mov_b32_e32 v69, v74
	v_mov_b32_e32 v38, v35
	v_mov_b32_e32 v74, v73
	v_mov_b32_e32 v36, v34
	v_mov_b32_e32 v68, v72
	v_pk_fma_f32 v[34:35], v[38:39], v[56:57], v[74:75] neg_lo:[0,0,1] neg_hi:[0,0,1]
	ds_read2st64_b32 v[74:75], v70 offset0:32 offset1:33
	ds_read2st64_b32 v[78:79], v70 offset0:34 offset1:35
	ds_read2st64_b32 v[80:81], v70 offset0:36 offset1:37
	ds_read2st64_b32 v[82:83], v70 offset0:38 offset1:39
	ds_read2st64_b32 v[38:39], v70 offset0:48 offset1:49
	ds_read2st64_b32 v[84:85], v70 offset0:40 offset1:41
	ds_read2st64_b32 v[86:87], v70 offset0:42 offset1:43
	ds_read2st64_b32 v[88:89], v70 offset0:44 offset1:45
	ds_read2st64_b32 v[90:91], v70 offset0:46 offset1:47
	ds_read2st64_b32 v[92:93], v70 offset0:50 offset1:51
	ds_read2st64_b32 v[94:95], v70 offset0:52 offset1:53
	ds_read2st64_b32 v[96:97], v70 offset0:54 offset1:55
	v_pk_fma_f32 v[36:37], v[36:37], v[56:57], v[68:69] neg_lo:[0,0,1] neg_hi:[0,0,1]
	s_waitcnt lgkmcnt(7)
	v_pk_fma_f32 v[68:69], v[24:25], v[56:57], v[38:39] op_sel:[0,1,0] neg_lo:[0,0,1] neg_hi:[0,0,1]
	v_pk_fma_f32 v[24:25], v[36:37], v[36:37], v[76:77]
	v_mov_b32_e32 v72, v20
	v_mov_b32_e32 v73, v28
	s_waitcnt lgkmcnt(2)
; #define LAS __attribute__((address_space(3)))
; #define LAS __attribute__((address_space(3)))
; DI unsigned pk(float lo, float hi) { return pg8::cvt_pk_bf16(lo, hi); }
; DI void attn_unit(const bf16_t* z, const bf16_t* VT, bf16_t* Y, const float* subg, ldsp lds, int tid, int b, int h, int qb, float lam, float ns, float oscale, int win) {
;     ...
;     if (!comp) {
;         float ss0 = 0.f, ss1 = 0.f;
; #pragma unroll
;         for (int e = 0; e < 8; ++e)
; #pragma unroll
;             for (int qt = 0; qt < 2; ++qt)
; #pragma unroll
;                 for (int r = 0; r < 4; ++r) {
;                     const float o = O[e][qt][r] * (qt ? sc1 : sc0) - *(LAS float*)(xp + ((2 * e + qt) * 4 + r) * 256);
;                     O[e][qt][r] = o; if (qt) ss1 += o * o; else ss0 += o * o;
;                 }
;         ss0 += __shfl_xor(ss0, 16); ss0 += __shfl_xor(ss0, 32);
;         ss1 += __shfl_xor(ss1, 16); ss1 += __shfl_xor(ss1, 32);
;         const float r0 = rsqrtf(ss0 * (1.0f / 128.0f) + EPS) * oscale, r1 = rsqrtf(ss1 * (1.0f / 128.0f) + EPS) * oscale;
; #pragma unroll
;         for (int qt = 0; qt < 2; ++qt) {
;             bf16_t* yrow = Y + (size_t)(b * SEQ + q0 + 16 * qt + fr) * D + 256 + h * 128;
;             const float rr = qt ? r1 : r0;
; #pragma unroll
;             for (int e = 0; e < 8; ++e) {
;                 const int e0 = 16 * e + 4 * fq;
;                 const f32x4 gn = *(const f32x4*)(subg + e0);
;                 u32x2 o; o.x = pk(O[e][qt][0] * rr * gn[0], O[e][qt][1] * rr * gn[1]); o.y = pk(O[e][qt][2] * rr * gn[2], O[e][qt][3] * rr * gn[3]);
;                 *(u32x2*)(yrow + e0) = o;
	v_pk_fma_f32 v[38:39], v[26:27], v[56:57], v[92:93] op_sel:[0,1,0] neg_lo:[0,0,1] neg_hi:[0,0,1]
	v_pk_fma_f32 v[26:27], v[34:35], v[34:35], v[24:25]
	v_mov_b32_e32 v24, v80
	v_mov_b32_e32 v25, v74
	v_pk_fma_f32 v[24:25], v[72:73], v[56:57], v[24:25] neg_lo:[0,0,1] neg_hi:[0,0,1]
	v_mov_b32_e32 v28, v21
	v_mov_b32_e32 v74, v81
	v_pk_fma_f32 v[26:27], v[24:25], v[24:25], v[26:27]
	v_pk_fma_f32 v[20:21], v[28:29], v[56:57], v[74:75] neg_lo:[0,0,1] neg_hi:[0,0,1]
	v_mov_b32_e32 v72, v82
	v_pk_fma_f32 v[28:29], v[20:21], v[20:21], v[26:27]
	v_mov_b32_e32 v26, v22
	v_mov_b32_e32 v27, v30
	v_mov_b32_e32 v73, v78
	v_pk_fma_f32 v[26:27], v[26:27], v[56:57], v[72:73] neg_lo:[0,0,1] neg_hi:[0,0,1]
	v_mov_b32_e32 v30, v23
	v_mov_b32_e32 v78, v83
	v_pk_fma_f32 v[72:73], v[26:27], v[26:27], v[28:29]
	v_pk_fma_f32 v[28:29], v[30:31], v[56:57], v[78:79] neg_lo:[0,0,1] neg_hi:[0,0,1]
	v_mov_b32_e32 v22, v12
	v_pk_fma_f32 v[30:31], v[28:29], v[28:29], v[72:73]
	v_mov_b32_e32 v23, v16
	v_mov_b32_e32 v72, v88
	v_mov_b32_e32 v73, v84
	v_lshlrev_b32_e32 v88, 4, v177
	v_pk_fma_f32 v[22:23], v[22:23], v[56:57], v[72:73] neg_lo:[0,0,1] neg_hi:[0,0,1]
	global_load_dwordx4 v[72:75], v88, s[26:27]
	global_load_dwordx4 v[142:145], v88, s[26:27]
	global_load_dwordx4 v[100:103], v88, s[26:27] offset:64
	global_load_dwordx4 v[104:107], v88, s[26:27] offset:128
	global_load_dwordx4 v[108:111], v88, s[26:27] offset:192
	global_load_dwordx4 v[112:115], v88, s[26:27] offset:256
	global_load_dwordx4 v[130:133], v88, s[26:27] offset:320
	global_load_dwordx4 v[146:149], v88, s[26:27] offset:384
	global_load_dwordx4 v[150:153], v88, s[26:27] offset:448
	v_mov_b32_e32 v16, v13
	v_mov_b32_e32 v84, v89
	v_pk_fma_f32 v[30:31], v[22:23], v[22:23], v[30:31]
	v_pk_fma_f32 v[12:13], v[16:17], v[56:57], v[84:85] neg_lo:[0,0,1] neg_hi:[0,0,1]
	v_mov_b32_e32 v16, v14
	v_mov_b32_e32 v17, v18
	v_mov_b32_e32 v76, v90
	v_mov_b32_e32 v77, v86
	s_waitcnt lgkmcnt(1)
	v_pk_fma_f32 v[8:9], v[8:9], v[56:57], v[94:95] op_sel_hi:[1,0,1] neg_lo:[0,0,1] neg_hi:[0,0,1]
	v_pk_fma_f32 v[30:31], v[12:13], v[12:13], v[30:31]
	v_pk_fma_f32 v[16:17], v[16:17], v[56:57], v[76:77] neg_lo:[0,0,1] neg_hi:[0,0,1]
	v_mov_b32_e32 v18, v15
	v_mov_b32_e32 v86, v91
	v_pk_mul_f32 v[98:99], v[68:69], v[68:69]
	v_pk_mul_f32 v[94:95], v[8:9], v[8:9]
	v_pk_fma_f32 v[30:31], v[16:17], v[16:17], v[30:31]
	v_pk_fma_f32 v[14:15], v[18:19], v[56:57], v[86:87] neg_lo:[0,0,1] neg_hi:[0,0,1]
	s_waitcnt lgkmcnt(0)
	v_pk_fma_f32 v[10:11], v[10:11], v[56:57], v[96:97] op_sel_hi:[1,0,1] neg_lo:[0,0,1] neg_hi:[0,0,1]
	v_pk_fma_f32 v[18:19], v[14:15], v[14:15], v[30:31]
	v_mov_b32_e32 v30, v94
	v_mov_b32_e32 v31, v98
	v_pk_add_f32 v[18:19], v[18:19], v[30:31]
	ds_read2st64_b32 v[30:31], v70 offset0:56 offset1:57
	ds_read2st64_b32 v[78:79], v70 offset0:58 offset1:59
	ds_read2st64_b32 v[80:81], v70 offset0:60 offset1:61
	ds_read2st64_b32 v[70:71], v70 offset0:62 offset1:63
	v_pk_mul_f32 v[92:93], v[38:39], v[38:39]
	v_pk_mul_f32 v[76:77], v[10:11], v[10:11]
	v_mov_b32_e32 v98, v95
	s_waitcnt lgkmcnt(3)
	v_pk_fma_f32 v[30:31], v[4:5], v[56:57], v[30:31] op_sel:[0,1,0] neg_lo:[0,0,1] neg_hi:[0,0,1]
	s_waitcnt lgkmcnt(2)
	v_pk_fma_f32 v[6:7], v[6:7], v[56:57], v[78:79] op_sel:[0,1,0] neg_lo:[0,0,1] neg_hi:[0,0,1]
	s_waitcnt lgkmcnt(1)
	v_pk_fma_f32 v[4:5], v[0:1], v[56:57], v[80:81] op_sel_hi:[1,0,1] neg_lo:[0,0,1] neg_hi:[0,0,1]
	s_waitcnt lgkmcnt(0)
	v_pk_fma_f32 v[0:1], v[2:3], v[56:57], v[70:71] op_sel_hi:[1,0,1] neg_lo:[0,0,1] neg_hi:[0,0,1]
	v_pk_add_f32 v[18:19], v[18:19], v[98:99]
	v_mov_b32_e32 v56, v76
	v_mov_b32_e32 v57, v92
	v_pk_mul_f32 v[82:83], v[30:31], v[30:31]
	v_pk_mul_f32 v[80:81], v[4:5], v[4:5]
	v_pk_add_f32 v[18:19], v[18:19], v[56:57]
	v_mov_b32_e32 v92, v77
	v_pk_add_f32 v[18:19], v[18:19], v[92:93]
	v_mov_b32_e32 v56, v80
	v_mov_b32_e32 v57, v82
	v_pk_mul_f32 v[78:79], v[6:7], v[6:7]
	v_pk_mul_f32 v[2:3], v[0:1], v[0:1]
	v_pk_add_f32 v[18:19], v[18:19], v[56:57]
	v_mov_b32_e32 v82, v81
	v_pk_add_f32 v[18:19], v[18:19], v[82:83]
	v_mov_b32_e32 v56, v2
	v_mov_b32_e32 v57, v78
	v_pk_add_f32 v[18:19], v[18:19], v[56:57]
	v_mov_b32_e32 v78, v3
	v_pk_add_f32 v[2:3], v[18:19], v[78:79]
	ds_bpermute_b32 v19, v172, v3
	ds_bpermute_b32 v18, v172, v2
	s_brev_b32 s0, 60
	s_lshl_b32 s30, s6, 1
	v_lshlrev_b32_e32 v156, 3, v177
	s_waitcnt lgkmcnt(0)
	v_pk_add_f32 v[2:3], v[2:3], v[18:19]
	ds_bpermute_b32 v19, v173, v3
	ds_bpermute_b32 v18, v173, v2
	s_waitcnt lgkmcnt(0)
	v_pk_add_f32 v[2:3], v[2:3], v[18:19]
	s_nop 0
	v_pk_fma_f32 v[2:3], v[2:3], s[0:1], v[162:163] op_sel_hi:[1,0,0]
	s_nop 0
	v_mul_f32_e32 v18, 0x4b800000, v3
	v_cmp_gt_f32_e32 vcc, s47, v3
	s_nop 1
	v_cndmask_b32_e32 v3, v3, v18, vcc
	v_rsq_f32_e32 v3, v3
	s_nop 0
	v_mul_f32_e32 v18, 0x45800000, v3
	v_cndmask_b32_e32 v3, v3, v18, vcc
	v_mul_f32_e32 v3, v176, v3
	v_lshlrev_b64 v[18:19], 11, v[120:121]
	v_mul_f32_e32 v56, v59, v3
	v_mul_f32_e32 v57, v61, v3
	v_lshl_add_u64 v[18:19], s[92:93], 0, v[18:19]
	s_waitcnt vmcnt(0)
; DI unsigned pk(float lo, float hi) { return pg8::cvt_pk_bf16(lo, hi); }
; DI void attn_unit(const bf16_t* z, const bf16_t* VT, bf16_t* Y, const float* subg, ldsp lds, int tid, int b, int h, int qb, float lam, float ns, float oscale, int win) {
;     ...
; #pragma unroll
;         for (int qt = 0; qt < 2; ++qt) {
;             bf16_t* yrow = Y + (size_t)(b * SEQ + q0 + 16 * qt + fr) * D + 256 + h * 128;
;             const float rr = qt ? r1 : r0;
; #pragma unroll
;             for (int e = 0; e < 8; ++e) {
;                 const int e0 = 16 * e + 4 * fq;
;                 const f32x4 gn = *(const f32x4*)(subg + e0);
;                 u32x2 o; o.x = pk(O[e][qt][0] * rr * gn[0], O[e][qt][1] * rr * gn[1]); o.y = pk(O[e][qt][2] * rr * gn[2], O[e][qt][3] * rr * gn[3]);
;                 *(u32x2*)(yrow + e0) = o;
;             }
	v_mul_f32_e32 v56, v72, v56
	v_mul_f32_e32 v57, v73, v57
	v_lshl_add_u64 v[18:19], v[18:19], 0, s[30:31]
	v_cvt_pk_bf16_f32 v56, v56, v57
	v_mul_f32_e32 v57, v63, v3
	v_mul_f32_e32 v57, v74, v57
	v_mul_f32_e32 v59, v65, v3
	v_lshl_add_u64 v[18:19], v[18:19], 0, v[156:157]
	v_mul_f32_e32 v59, v75, v59
	v_cvt_pk_bf16_f32 v57, v57, v59
	global_store_dwordx2 v[18:19], v[56:57], off offset:512
	v_mov_b32_e32 v70, v100
	v_mov_b32_e32 v71, v101
	v_mov_b32_e32 v72, v102
	v_mov_b32_e32 v73, v103
	v_mul_f32_e32 v56, v67, v3
	v_mul_f32_e32 v49, v49, v3
	v_mul_f32_e32 v41, v41, v3
	v_mul_f32_e32 v45, v45, v3
	v_mul_f32_e32 v43, v43, v3
	v_mul_f32_e32 v33, v33, v3
	v_mul_f32_e32 v37, v37, v3
	v_mul_f32_e32 v35, v35, v3
	v_mul_f32_e32 v25, v25, v3
	v_mul_f32_e32 v21, v21, v3
	v_mul_f32_e32 v27, v27, v3
	v_mul_f32_e32 v29, v29, v3
	v_mul_f32_e32 v13, v13, v3
	v_mul_f32_e32 v17, v17, v3
	v_mul_f32_e32 v15, v15, v3
	v_mul_f32_e32 v6, v6, v3
	v_cmp_gt_f32_e32 vcc, s47, v2
	v_mul_f32_e32 v56, v70, v56
	v_mul_f32_e32 v49, v71, v49
	v_cvt_pk_bf16_f32 v56, v56, v49
	v_mul_f32_e32 v49, v53, v3
	v_mul_f32_e32 v53, v55, v3
	v_mul_f32_e32 v49, v72, v49
	v_mul_f32_e32 v53, v73, v53
	v_cvt_pk_bf16_f32 v57, v49, v53
	global_store_dwordx2 v[18:19], v[56:57], off offset:544
	v_mov_b32_e32 v70, v104
	v_mov_b32_e32 v71, v105
	v_mov_b32_e32 v72, v106
	v_mov_b32_e32 v73, v107
	v_mul_f32_e32 v49, v51, v3
	v_mul_f32_e32 v49, v49, v70
	v_mul_f32_e32 v41, v41, v71
	v_mul_f32_e32 v45, v45, v72
	v_mul_f32_e32 v43, v43, v73
	v_cvt_pk_bf16_f32 v56, v49, v41
	v_cvt_pk_bf16_f32 v57, v45, v43
	global_store_dwordx2 v[18:19], v[56:57], off offset:576
	v_mov_b32_e32 v70, v108
	v_mov_b32_e32 v71, v109
	v_mov_b32_e32 v72, v110
	v_mov_b32_e32 v73, v111
	v_mul_f32_e32 v41, v47, v3
	v_mul_f32_e32 v41, v41, v70
	v_mul_f32_e32 v33, v33, v71
	v_mul_f32_e32 v37, v37, v72
	v_mul_f32_e32 v35, v35, v73
	v_cvt_pk_bf16_f32 v56, v41, v33
	v_cvt_pk_bf16_f32 v57, v37, v35
	global_store_dwordx2 v[18:19], v[56:57], off offset:608
	v_mov_b32_e32 v70, v112
	v_mov_b32_e32 v71, v113
	v_mov_b32_e32 v72, v114
	v_mov_b32_e32 v73, v115
	v_mul_f32_e32 v25, v25, v70
	v_mul_f32_e32 v21, v21, v71
	v_mul_f32_e32 v27, v27, v72
	v_mul_f32_e32 v29, v29, v73
	v_cvt_pk_bf16_f32 v56, v25, v21
	v_cvt_pk_bf16_f32 v57, v27, v29
	global_store_dwordx2 v[18:19], v[56:57], off offset:640
	v_mov_b32_e32 v70, v130
	v_mov_b32_e32 v71, v131
	v_mov_b32_e32 v72, v132
	v_mov_b32_e32 v73, v133
	v_mul_f32_e32 v21, v23, v3
	v_mul_f32_e32 v21, v21, v70
	v_mul_f32_e32 v13, v13, v71
	v_mul_f32_e32 v17, v17, v72
	v_mul_f32_e32 v15, v15, v73
	v_cvt_pk_bf16_f32 v56, v21, v13
	v_cvt_pk_bf16_f32 v57, v17, v15
	global_store_dwordx2 v[18:19], v[56:57], off offset:672
	v_mov_b32_e32 v70, v146
	v_mov_b32_e32 v71, v147
	v_mov_b32_e32 v72, v148
	v_mov_b32_e32 v73, v149
	v_mul_f32_e32 v13, v68, v3
	v_mul_f32_e32 v15, v69, v3
	v_mul_f32_e32 v17, v38, v3
	v_mul_f32_e32 v21, v39, v3
	v_mul_f32_e32 v13, v13, v70
	v_mul_f32_e32 v15, v15, v71
	v_mul_f32_e32 v17, v17, v72
	v_mul_f32_e32 v21, v21, v73
	v_cvt_pk_bf16_f32 v38, v13, v15
	v_cvt_pk_bf16_f32 v39, v17, v21
	global_store_dwordx2 v[18:19], v[38:39], off offset:704
	v_mov_b32_e32 v68, v150
	v_mov_b32_e32 v69, v151
	v_mov_b32_e32 v70, v152
	v_mov_b32_e32 v71, v153
	v_mul_f32_e32 v13, v30, v3
	v_mul_f32_e32 v15, v31, v3
	v_mul_f32_e32 v3, v7, v3
	v_mul_f32_e32 v7, v13, v68
	v_mul_f32_e32 v13, v15, v69
	v_mul_f32_e32 v15, v6, v70
	v_mul_f32_e32 v3, v3, v71
	v_cvt_pk_bf16_f32 v6, v7, v13
	v_cvt_pk_bf16_f32 v7, v15, v3
	global_store_dwordx2 v[18:19], v[6:7], off offset:736
	v_mov_b32_e32 v68, v142
	v_mov_b32_e32 v69, v143
	v_mov_b32_e32 v70, v144
	v_mov_b32_e32 v71, v145
	v_mul_f32_e32 v3, 0x4b800000, v2
	v_cndmask_b32_e32 v2, v2, v3, vcc
; DI unsigned pk(float lo, float hi) { return pg8::cvt_pk_bf16(lo, hi); }
; DI void attn_unit(const bf16_t* z, const bf16_t* VT, bf16_t* Y, const float* subg, ldsp lds, int tid, int b, int h, int qb, float lam, float ns, float oscale, int win) {
;     ...
;         const float r0 = rsqrtf(ss0 * (1.0f / 128.0f) + EPS) * oscale, r1 = rsqrtf(ss1 * (1.0f / 128.0f) + EPS) * oscale;
; #pragma unroll
;         for (int qt = 0; qt < 2; ++qt) {
;             bf16_t* yrow = Y + (size_t)(b * SEQ + q0 + 16 * qt + fr) * D + 256 + h * 128;
;             const float rr = qt ? r1 : r0;
; #pragma unroll
;             for (int e = 0; e < 8; ++e) {
;                 const int e0 = 16 * e + 4 * fq;
;                 const f32x4 gn = *(const f32x4*)(subg + e0);
;                 u32x2 o; o.x = pk(O[e][qt][0] * rr * gn[0], O[e][qt][1] * rr * gn[1]); o.y = pk(O[e][qt][2] * rr * gn[2], O[e][qt][3] * rr * gn[3]);
;                 *(u32x2*)(yrow + e0) = o;
;             }
	v_rsq_f32_e32 v13, v2
	v_lshlrev_b64 v[6:7], 11, v[118:119]
	v_lshl_add_u64 v[2:3], s[92:93], 0, v[6:7]
	v_lshl_add_u64 v[2:3], v[2:3], 0, s[30:31]
	v_mul_f32_e32 v6, 0x45800000, v13
	v_cndmask_b32_e32 v6, v13, v6, vcc
	v_mul_f32_e32 v17, v176, v6
	v_mul_f32_e32 v6, v58, v17
	v_mul_f32_e32 v7, v60, v17
	v_lshl_add_u64 v[2:3], v[2:3], 0, v[156:157]
	v_mul_f32_e32 v13, v62, v17
	v_mul_f32_e32 v15, v64, v17
	v_mul_f32_e32 v1, v1, v17
	v_mul_f32_e32 v4, v4, v17
	v_mul_f32_e32 v5, v5, v17
	v_mul_f32_e32 v0, v0, v17
	v_mul_f32_e32 v6, v6, v68
	v_mul_f32_e32 v7, v7, v69
	v_mul_f32_e32 v13, v13, v70
	v_mul_f32_e32 v15, v15, v71
	v_cvt_pk_bf16_f32 v6, v6, v7
	v_cvt_pk_bf16_f32 v7, v13, v15
	global_store_dwordx2 v[2:3], v[6:7], off offset:512
	v_mov_b32_e32 v56, v100
	v_mov_b32_e32 v57, v101
	v_mov_b32_e32 v58, v102
	v_mov_b32_e32 v59, v103
	v_mul_f32_e32 v6, v66, v17
	v_mul_f32_e32 v7, v48, v17
	v_mul_f32_e32 v13, v52, v17
	v_mul_f32_e32 v15, v54, v17
	v_mul_f32_e32 v6, v6, v56
	v_mul_f32_e32 v7, v7, v57
	v_mul_f32_e32 v13, v13, v58
	v_mul_f32_e32 v15, v15, v59
	v_cvt_pk_bf16_f32 v6, v6, v7
	v_cvt_pk_bf16_f32 v7, v13, v15
	global_store_dwordx2 v[2:3], v[6:7], off offset:544
	v_mov_b32_e32 v52, v104
	v_mov_b32_e32 v53, v105
	v_mov_b32_e32 v54, v106
	v_mov_b32_e32 v55, v107
	v_mul_f32_e32 v6, v50, v17
	v_mul_f32_e32 v7, v40, v17
	v_mul_f32_e32 v13, v44, v17
	v_mul_f32_e32 v15, v42, v17
	v_mul_f32_e32 v6, v6, v52
	v_mul_f32_e32 v7, v7, v53
	v_mul_f32_e32 v13, v13, v54
	v_mul_f32_e32 v15, v15, v55
	v_cvt_pk_bf16_f32 v6, v6, v7
	v_cvt_pk_bf16_f32 v7, v13, v15
	global_store_dwordx2 v[2:3], v[6:7], off offset:576
	v_mov_b32_e32 v38, v108
	v_mov_b32_e32 v39, v109
	v_mov_b32_e32 v40, v110
	v_mov_b32_e32 v41, v111
	v_mul_f32_e32 v6, v46, v17
	v_mul_f32_e32 v7, v32, v17
	v_mul_f32_e32 v13, v36, v17
	v_mul_f32_e32 v15, v34, v17
	v_mul_f32_e32 v6, v6, v38
	v_mul_f32_e32 v7, v7, v39
	v_mul_f32_e32 v13, v13, v40
	v_mul_f32_e32 v15, v15, v41
	v_cvt_pk_bf16_f32 v6, v6, v7
	v_cvt_pk_bf16_f32 v7, v13, v15
	global_store_dwordx2 v[2:3], v[6:7], off offset:608
	v_mov_b32_e32 v30, v112
	v_mov_b32_e32 v31, v113
	v_mov_b32_e32 v32, v114
	v_mov_b32_e32 v33, v115
	v_mul_f32_e32 v6, v24, v17
	v_mul_f32_e32 v7, v20, v17
	v_mul_f32_e32 v13, v26, v17
	v_mul_f32_e32 v15, v28, v17
	v_mul_f32_e32 v6, v6, v30
	v_mul_f32_e32 v7, v7, v31
	v_mul_f32_e32 v13, v13, v32
	v_mul_f32_e32 v15, v15, v33
	v_cvt_pk_bf16_f32 v6, v6, v7
	v_cvt_pk_bf16_f32 v7, v13, v15
	global_store_dwordx2 v[2:3], v[6:7], off offset:640
	v_mov_b32_e32 v18, v130
	v_mov_b32_e32 v19, v131
	v_mov_b32_e32 v20, v132
	v_mov_b32_e32 v21, v133
	v_mul_f32_e32 v6, v22, v17
	v_mul_f32_e32 v7, v12, v17
	v_mul_f32_e32 v12, v16, v17
	v_mul_f32_e32 v13, v14, v17
	v_mul_f32_e32 v6, v6, v18
	v_mul_f32_e32 v7, v7, v19
	v_mul_f32_e32 v12, v12, v20
	v_mul_f32_e32 v13, v13, v21
	v_cvt_pk_bf16_f32 v6, v6, v7
	v_cvt_pk_bf16_f32 v7, v12, v13
	global_store_dwordx2 v[2:3], v[6:7], off offset:672
	v_mov_b32_e32 v12, v146
	v_mov_b32_e32 v13, v147
	v_mov_b32_e32 v14, v148
	v_mov_b32_e32 v15, v149
	v_mul_f32_e32 v6, v8, v17
	v_mul_f32_e32 v7, v9, v17
	v_mul_f32_e32 v8, v10, v17
	v_mul_f32_e32 v9, v11, v17
	v_mul_f32_e32 v6, v6, v12
	v_mul_f32_e32 v7, v7, v13
	v_mul_f32_e32 v8, v8, v14
	v_mul_f32_e32 v9, v9, v15
	v_cvt_pk_bf16_f32 v6, v6, v7
	v_cvt_pk_bf16_f32 v7, v8, v9
	global_store_dwordx2 v[2:3], v[6:7], off offset:704
	v_mov_b32_e32 v6, v150
	v_mov_b32_e32 v7, v151
	v_mov_b32_e32 v8, v152
	v_mov_b32_e32 v9, v153
	v_mul_f32_e32 v1, v1, v9
	v_mul_f32_e32 v4, v4, v6
	v_mul_f32_e32 v5, v5, v7
	v_mul_f32_e32 v6, v0, v8
	v_cvt_pk_bf16_f32 v0, v4, v5
	v_cvt_pk_bf16_f32 v1, v6, v1
	global_store_dwordx2 v[2:3], v[0:1], off offset:736
	s_branch .LBB0_401
